# gather: candidate ranking chains re-pipelined (3 instr per candidate, no hazard nops); peerq epilogue: query-bias loads hoisted to tile head (no serial vmcnt(0) round trips)
# speedup vs baseline: 1.1516x; 1.0005x over previous
.LBB0_20:
	s_and_b32 s0, s19, 7
	s_mulk_i32 s0, 0x108
	s_ashr_i32 s26, s19, 3
	s_add_i32 s0, s0, s26
	v_mov_b32_e32 v26, v220
	s_ashr_i32 s16, s0, 4
	s_ashr_i32 s17, s16, 31
	v_lshlrev_b32_e32 v105, 4, v26
	v_and_b32_e32 v0, 32, v26
	v_bitop3_b32 v0, v105, v0, 48 bitop3:0x6c
	s_lshl_b32 s21, s2, 3
	s_and_b32 s20, s0, 15
	v_lshl_or_b32 v254, s20, 9, v98
	global_load_dword v250, v254, s[10:11]
	global_load_dword v251, v254, s[10:11] offset:64
	global_load_dword v252, v254, s[10:11] offset:128
	global_load_dword v253, v254, s[10:11] offset:192
	s_lshl_b64 s[0:1], s[16:17], 18
	v_lshrrev_b32_e32 v16, 2, v26
	v_lshrrev_b32_e32 v1, 1, v26
	v_lshrrev_b32_e32 v0, 1, v0
	v_ashrrev_i32_e32 v4, 3, v26
	s_add_u32 s22, s8, s0
	v_and_or_b32 v0, v1, 32, v0
	v_bfi_b32 v4, 15, v16, v4
	s_addc_u32 s23, s9, s1
	s_lshl_b32 s17, s20, 18
	v_lshlrev_b32_e32 v0, 1, v0
	v_mov_b32_e32 v1, v80
	v_ashrrev_i32_e32 v5, 31, v4
	v_add_u32_e32 v12, 0x1000, v105
	s_add_u32 s24, s3, s17
	v_lshl_add_u64 v[2:3], s[22:23], 0, v[0:1]
	v_lshlrev_b64 v[4:5], 11, v[4:5]
	v_readfirstlane_b32 s17, v105
	v_ashrrev_i32_e32 v8, 7, v12
	v_add_u32_e32 v17, 0x2000, v105
	v_lshl_add_u64 v[6:7], v[2:3], 0, v[4:5]
	s_mov_b32 m0, s17
	v_bfi_b32 v8, -16, v8, v16
	v_readfirstlane_b32 s17, v12
	v_ashrrev_i32_e32 v12, 7, v17
	v_add_u32_e32 v18, 0x3000, v105
	global_load_lds_dwordx4 v[6:7], off
	v_ashrrev_i32_e32 v9, 31, v8
	s_mov_b32 m0, s17
	v_bfi_b32 v12, -16, v12, v16
	v_readfirstlane_b32 s17, v17
	v_ashrrev_i32_e32 v17, 7, v18
	v_lshlrev_b64 v[8:9], 11, v[8:9]
	v_ashrrev_i32_e32 v13, 31, v12
	v_bfi_b32 v16, -16, v17, v16
	s_addc_u32 s25, s18, 0
	v_lshl_add_u64 v[10:11], v[2:3], 0, v[8:9]
	v_lshlrev_b64 v[12:13], 11, v[12:13]
	v_ashrrev_i32_e32 v17, 31, v16
	global_load_lds_dwordx4 v[10:11], off
	v_lshl_add_u64 v[14:15], v[2:3], 0, v[12:13]
	s_mov_b32 m0, s17
	v_lshlrev_b64 v[16:17], 11, v[16:17]
	v_readfirstlane_b32 s17, v18
	v_lshl_add_u64 v[18:19], s[24:25], 0, v[0:1]
	v_add_u32_e32 v1, 0x4000, v105
	global_load_lds_dwordx4 v[14:15], off
	v_lshl_add_u64 v[2:3], v[2:3], 0, v[16:17]
	s_mov_b32 m0, s17
	v_readfirstlane_b32 s17, v1
	v_add_u32_e32 v1, 0x5000, v105
	global_load_lds_dwordx4 v[2:3], off
	v_lshl_add_u64 v[20:21], v[18:19], 0, v[4:5]
	s_mov_b32 m0, s17
	v_readfirstlane_b32 s17, v1
	v_add_u32_e32 v1, 0x6000, v105
	global_load_lds_dwordx4 v[20:21], off
	v_lshl_add_u64 v[22:23], v[18:19], 0, v[8:9]
	s_mov_b32 m0, s17
	v_readfirstlane_b32 s17, v1
	v_add_u32_e32 v1, 0x7000, v105
	global_load_lds_dwordx4 v[22:23], off
	v_lshl_add_u64 v[24:25], v[18:19], 0, v[12:13]
	s_mov_b32 m0, s17
	v_readfirstlane_b32 s17, v1
	v_add_u32_e32 v1, 0x8000, v105
	global_load_lds_dwordx4 v[24:25], off
	v_lshl_add_u64 v[18:19], v[18:19], 0, v[16:17]
	s_mov_b32 m0, s17
	s_mov_b64 s[22:23], 0x80
	v_readfirstlane_b32 s17, v1
	v_add_u32_e32 v1, 0x9000, v105
	global_load_lds_dwordx4 v[18:19], off
	v_lshl_add_u64 v[6:7], v[6:7], 0, s[22:23]
	s_mov_b32 m0, s17
	v_readfirstlane_b32 s17, v1
	v_add_u32_e32 v1, 0xa000, v105
	global_load_lds_dwordx4 v[6:7], off
	v_lshl_add_u64 v[6:7], v[10:11], 0, s[22:23]
	s_mov_b32 m0, s17
	v_readfirstlane_b32 s17, v1
	v_add_u32_e32 v1, 0xb000, v105
	global_load_lds_dwordx4 v[6:7], off
	v_lshl_add_u64 v[6:7], v[14:15], 0, s[22:23]
	s_mov_b32 m0, s17
	v_readfirstlane_b32 s17, v1
	v_add_u32_e32 v1, 0xc000, v105
	global_load_lds_dwordx4 v[6:7], off
	v_lshl_add_u64 v[2:3], v[2:3], 0, s[22:23]
	s_mov_b32 m0, s17
	v_readfirstlane_b32 s17, v1
	v_add_u32_e32 v1, 0xd000, v105
	global_load_lds_dwordx4 v[2:3], off
	v_lshl_add_u64 v[2:3], v[20:21], 0, s[22:23]
	s_mov_b32 m0, s17
	v_readfirstlane_b32 s17, v1
	v_add_u32_e32 v1, 0xe000, v105
	global_load_lds_dwordx4 v[2:3], off
	v_lshl_add_u64 v[2:3], v[22:23], 0, s[22:23]
	s_mov_b32 m0, s17
	v_readfirstlane_b32 s17, v1
	v_add_u32_e32 v1, 0xf000, v105
	global_load_lds_dwordx4 v[2:3], off
	v_lshl_add_u64 v[2:3], v[24:25], 0, s[22:23]
	s_mov_b32 m0, s17
	v_readfirstlane_b32 s17, v1
	global_load_lds_dwordx4 v[2:3], off
	v_lshl_add_u64 v[2:3], v[18:19], 0, s[22:23]
	s_mov_b32 m0, s17
	v_lshlrev_b32_e32 v1, 6, v26
	global_load_lds_dwordx4 v[2:3], off
	v_lshlrev_b32_e32 v2, 2, v26
	v_and_b32_e32 v3, 48, v26
	v_bitop3_b32 v2, v2, v3, 32 bitop3:0x6c
	s_movk_i32 s17, 0x3c0
	v_and_or_b32 v2, v1, s17, v2
	s_movk_i32 s17, 0xe000
	v_and_or_b32 v104, v1, s17, v2
	v_lshlrev_b32_e32 v1, 7, v26
	s_movk_i32 s17, 0x2000
	s_add_i32 s21, s21, s26
	v_and_or_b32 v73, v1, s17, v2
	s_and_b32 s17, s21, 15
	v_readlane_b32 s22, v249, 19
	v_readlane_b32 s23, v249, 20
	s_lshl_b32 s22, s17, 18
	s_mov_b32 s17, s23
	v_lshl_add_u64 v[2:3], s[22:23], 0, v[16:17]
	v_or_b32_e32 v2, v2, v0
	v_lshl_add_u64 v[74:75], s[12:13], 0, v[2:3]
	v_lshl_add_u64 v[2:3], s[22:23], 0, v[12:13]
	v_or_b32_e32 v2, v2, v0
	v_lshl_add_u64 v[76:77], s[12:13], 0, v[2:3]
	v_lshl_add_u64 v[2:3], s[22:23], 0, v[8:9]
	v_or_b32_e32 v2, v2, v0
	v_lshl_add_u64 v[78:79], s[12:13], 0, v[2:3]
	v_lshl_add_u64 v[2:3], s[22:23], 0, v[4:5]
	v_or_b32_e32 v2, v2, v0
	v_lshl_add_u64 v[82:83], s[12:13], 0, v[2:3]
	v_lshl_add_u64 v[2:3], s[0:1], 0, v[16:17]
	v_or_b32_e32 v2, v2, v0
	v_lshl_add_u64 v[84:85], s[14:15], 0, v[2:3]
	v_lshl_add_u64 v[2:3], s[0:1], 0, v[12:13]
	v_or_b32_e32 v2, v2, v0
	v_lshl_add_u64 v[86:87], s[14:15], 0, v[2:3]
	v_lshl_add_u64 v[2:3], s[0:1], 0, v[8:9]
	v_or_b32_e32 v2, v2, v0
	v_lshl_add_u64 v[88:89], s[14:15], 0, v[2:3]
	v_lshl_add_u64 v[2:3], s[0:1], 0, v[4:5]
	v_writelane_b32 v249, s16, 19
	v_or_b32_e32 v2, v2, v0
	v_mov_b32_e32 v0, 0
	v_writelane_b32 v249, s17, 20
	v_lshl_add_u64 v[90:91], s[14:15], 0, v[2:3]
	s_mov_b64 s[0:1], 0
	s_mov_b32 s17, 0
	v_mov_b32_e32 v1, v0
	v_mov_b32_e32 v2, v0
	v_mov_b32_e32 v3, v0
	v_mov_b32_e32 v4, v0
	v_mov_b32_e32 v5, v0
	v_mov_b32_e32 v6, v0
	v_mov_b32_e32 v7, v0
	v_mov_b32_e32 v8, v0
	v_mov_b32_e32 v9, v0
	v_mov_b32_e32 v10, v0
	v_mov_b32_e32 v11, v0
	v_mov_b32_e32 v12, v0
	v_mov_b32_e32 v13, v0
	v_mov_b32_e32 v14, v0
	v_mov_b32_e32 v15, v0
	v_mov_b32_e32 v16, v0
	v_mov_b32_e32 v17, v0
	v_mov_b32_e32 v18, v0
	v_mov_b32_e32 v19, v0
	v_mov_b32_e32 v20, v0
	v_mov_b32_e32 v21, v0
	v_mov_b32_e32 v22, v0
	v_mov_b32_e32 v23, v0
	v_mov_b32_e32 v24, v0
	v_mov_b32_e32 v25, v0
	v_mov_b32_e32 v26, v0
	v_mov_b32_e32 v27, v0
	v_mov_b32_e32 v28, v0
	v_mov_b32_e32 v29, v0
	v_mov_b32_e32 v30, v0
	v_mov_b32_e32 v31, v0
	v_mov_b32_e32 v32, v0
	v_mov_b32_e32 v33, v0
	v_mov_b32_e32 v34, v0
	v_mov_b32_e32 v35, v0
	v_mov_b32_e32 v36, v0
	v_mov_b32_e32 v37, v0
	v_mov_b32_e32 v38, v0
	v_mov_b32_e32 v39, v0
	v_mov_b32_e32 v40, v0
	v_mov_b32_e32 v41, v0
	v_mov_b32_e32 v42, v0
	v_mov_b32_e32 v43, v0
	v_mov_b32_e32 v44, v0
	v_mov_b32_e32 v45, v0
	v_mov_b32_e32 v46, v0
	v_mov_b32_e32 v47, v0
	v_mov_b32_e32 v48, v0
	v_mov_b32_e32 v49, v0
	v_mov_b32_e32 v50, v0
	v_mov_b32_e32 v51, v0
	v_mov_b32_e32 v52, v0
	v_mov_b32_e32 v53, v0
	v_mov_b32_e32 v54, v0
	v_mov_b32_e32 v55, v0
	v_mov_b32_e32 v56, v0
	v_mov_b32_e32 v57, v0
	v_mov_b32_e32 v58, v0
	v_mov_b32_e32 v59, v0
	v_mov_b32_e32 v60, v0
	v_mov_b32_e32 v61, v0
	v_mov_b32_e32 v62, v0
	v_mov_b32_e32 v63, v0
	v_readfirstlane_b32 s60, v105
.LBB0_21:
	s_and_b32 s21, s17, 0x8000
	s_waitcnt vmcnt(8)
	s_barrier
	v_add_u32_e32 v140, s21, v104
	v_or_b32_e32 v141, s21, v73
	s_add_u32 s61, s60, s21
	ds_read_b128 v[106:109], v140
	ds_read_b128 v[124:127], v141 offset:16384
	ds_read_b128 v[128:131], v141 offset:18432
	ds_read_b128 v[132:135], v141 offset:20480
	ds_read_b128 v[136:139], v141 offset:22528
	ds_read_b128 v[110:113], v140 offset:2048
	ds_read_b128 v[116:119], v140 offset:4096
	ds_read_b128 v[120:123], v140 offset:6144
	s_waitcnt lgkmcnt(6)
	v_mfma_f32_16x16x32_bf16 v[60:63], v[106:109], v[124:127], v[60:63]
	ds_read_b128 v[196:199], v140 offset:1024
	s_waitcnt lgkmcnt(6)
	v_mfma_f32_16x16x32_bf16 v[56:59], v[106:109], v[128:131], v[56:59]
	ds_read_b128 v[212:215], v141 offset:17408
	s_waitcnt lgkmcnt(6)
	v_mfma_f32_16x16x32_bf16 v[52:55], v[106:109], v[132:135], v[52:55]
	ds_read_b128 v[216:219], v141 offset:19456
	s_waitcnt lgkmcnt(6)
	v_mfma_f32_16x16x32_bf16 v[48:51], v[106:109], v[136:139], v[48:51]
	ds_read_b128 v[240:243], v141 offset:21504
	ds_read_b128 v[244:247], v141 offset:23552
	s_waitcnt lgkmcnt(7)
	v_mfma_f32_16x16x32_bf16 v[44:47], v[110:113], v[124:127], v[44:47]
	v_mfma_f32_16x16x32_bf16 v[40:43], v[110:113], v[128:131], v[40:43]
	v_mfma_f32_16x16x32_bf16 v[36:39], v[110:113], v[132:135], v[36:39]
	v_mfma_f32_16x16x32_bf16 v[32:35], v[110:113], v[136:139], v[32:35]
	ds_read_b128 v[200:203], v140 offset:3072
	ds_read_b128 v[204:207], v140 offset:5120
	s_waitcnt lgkmcnt(8)
	v_mfma_f32_16x16x32_bf16 v[28:31], v[116:119], v[124:127], v[28:31]
	v_mfma_f32_16x16x32_bf16 v[24:27], v[116:119], v[128:131], v[24:27]
	v_mfma_f32_16x16x32_bf16 v[20:23], v[116:119], v[132:135], v[20:23]
	v_mfma_f32_16x16x32_bf16 v[16:19], v[116:119], v[136:139], v[16:19]
	ds_read_b128 v[208:211], v140 offset:7168
	s_waitcnt lgkmcnt(8)
	v_mfma_f32_16x16x32_bf16 v[12:15], v[120:123], v[124:127], v[12:15]
	v_mfma_f32_16x16x32_bf16 v[8:11], v[120:123], v[128:131], v[8:11]
	v_mfma_f32_16x16x32_bf16 v[4:7], v[120:123], v[132:135], v[4:7]
	v_mfma_f32_16x16x32_bf16 v[0:3], v[120:123], v[136:139], v[0:3]
	s_waitcnt lgkmcnt(0)
	s_barrier
	s_mov_b32 m0, s61
	v_lshl_add_u64 v[106:107], v[90:91], 0, s[0:1]
	v_mfma_f32_16x16x32_bf16 v[60:63], v[196:199], v[212:215], v[60:63]
	global_load_lds_dwordx4 v[106:107], off
	v_mfma_f32_16x16x32_bf16 v[56:59], v[196:199], v[216:219], v[56:59]
	s_add_u32 m0, s61, 0x1000
	v_lshl_add_u64 v[108:109], v[88:89], 0, s[0:1]
	v_mfma_f32_16x16x32_bf16 v[52:55], v[196:199], v[240:243], v[52:55]
	global_load_lds_dwordx4 v[108:109], off
	v_mfma_f32_16x16x32_bf16 v[48:51], v[196:199], v[244:247], v[48:51]
	s_add_u32 m0, s61, 0x2000
	v_lshl_add_u64 v[110:111], v[86:87], 0, s[0:1]
	v_mfma_f32_16x16x32_bf16 v[44:47], v[200:203], v[212:215], v[44:47]
	global_load_lds_dwordx4 v[110:111], off
	v_mfma_f32_16x16x32_bf16 v[40:43], v[200:203], v[216:219], v[40:43]
	s_add_u32 m0, s61, 0x3000
	v_lshl_add_u64 v[112:113], v[84:85], 0, s[0:1]
	v_mfma_f32_16x16x32_bf16 v[36:39], v[200:203], v[240:243], v[36:39]
	global_load_lds_dwordx4 v[112:113], off
	v_mfma_f32_16x16x32_bf16 v[32:35], v[200:203], v[244:247], v[32:35]
	s_add_u32 m0, s61, 0x4000
	v_lshl_add_u64 v[116:117], v[82:83], 0, s[0:1]
	v_mfma_f32_16x16x32_bf16 v[28:31], v[204:207], v[212:215], v[28:31]
	global_load_lds_dwordx4 v[116:117], off
	v_mfma_f32_16x16x32_bf16 v[24:27], v[204:207], v[216:219], v[24:27]
	s_add_u32 m0, s61, 0x5000
	v_lshl_add_u64 v[118:119], v[78:79], 0, s[0:1]
	v_mfma_f32_16x16x32_bf16 v[20:23], v[204:207], v[240:243], v[20:23]
	global_load_lds_dwordx4 v[118:119], off
	v_mfma_f32_16x16x32_bf16 v[16:19], v[204:207], v[244:247], v[16:19]
	s_add_u32 m0, s61, 0x6000
	v_lshl_add_u64 v[120:121], v[76:77], 0, s[0:1]
	v_mfma_f32_16x16x32_bf16 v[12:15], v[208:211], v[212:215], v[12:15]
	global_load_lds_dwordx4 v[120:121], off
	v_mfma_f32_16x16x32_bf16 v[8:11], v[208:211], v[216:219], v[8:11]
	s_add_u32 m0, s61, 0x7000
	v_lshl_add_u64 v[122:123], v[74:75], 0, s[0:1]
	v_mfma_f32_16x16x32_bf16 v[4:7], v[208:211], v[240:243], v[4:7]
	global_load_lds_dwordx4 v[122:123], off
	v_mfma_f32_16x16x32_bf16 v[0:3], v[208:211], v[244:247], v[0:3]
	s_add_u32 s0, s0, 0x80
	s_addc_u32 s1, s1, 0
	s_add_i32 s17, s17, 0x8000
	s_cmpk_lg_i32 s0, 0x700
	s_cbranch_scc1 .LBB0_21
	s_waitcnt vmcnt(8)
	s_barrier
	ds_read_b128 v[74:77], v104
	ds_read_b128 v[82:85], v104 offset:2048
	ds_read_b128 v[86:89], v104 offset:4096
	ds_read_b128 v[106:109], v104 offset:6144
	ds_read_b128 v[110:113], v73 offset:16384
	ds_read_b128 v[116:119], v73 offset:18432
	ds_read_b128 v[120:123], v73 offset:20480
	ds_read_b128 v[124:127], v73 offset:22528
	s_waitcnt lgkmcnt(0)
	v_mfma_f32_16x16x32_bf16 v[60:63], v[74:77], v[110:113], v[60:63]
	v_readlane_b32 s0, v249, 30
	v_readlane_b32 s1, v249, 31
	v_readlane_b32 s22, v249, 41
	v_mfma_f32_16x16x32_bf16 v[56:59], v[74:77], v[116:119], v[56:59]
	v_readlane_b32 s23, v249, 42
	s_movk_i32 s21, 0x6f
	v_mfma_f32_16x16x32_bf16 v[52:55], v[74:77], v[120:123], v[52:55]
	v_mfma_f32_16x16x32_bf16 v[48:51], v[74:77], v[124:127], v[48:51]
	v_mfma_f32_16x16x32_bf16 v[44:47], v[82:85], v[110:113], v[44:47]
	v_mfma_f32_16x16x32_bf16 v[40:43], v[82:85], v[116:119], v[40:43]
	v_mfma_f32_16x16x32_bf16 v[36:39], v[82:85], v[120:123], v[36:39]
	v_mfma_f32_16x16x32_bf16 v[32:35], v[82:85], v[124:127], v[32:35]
	v_mfma_f32_16x16x32_bf16 v[28:31], v[86:89], v[110:113], v[28:31]
	v_mfma_f32_16x16x32_bf16 v[24:27], v[86:89], v[116:119], v[24:27]
	v_mfma_f32_16x16x32_bf16 v[20:23], v[86:89], v[120:123], v[20:23]
	v_mfma_f32_16x16x32_bf16 v[16:19], v[86:89], v[124:127], v[16:19]
	v_mfma_f32_16x16x32_bf16 v[12:15], v[106:109], v[110:113], v[12:15]
	v_mfma_f32_16x16x32_bf16 v[8:11], v[106:109], v[116:119], v[8:11]
	v_mfma_f32_16x16x32_bf16 v[4:7], v[106:109], v[120:123], v[4:7]
	v_mfma_f32_16x16x32_bf16 v[0:3], v[106:109], v[124:127], v[0:3]
	ds_read_b128 v[74:77], v104 offset:1024
	ds_read_b128 v[82:85], v104 offset:3072
	ds_read_b128 v[86:89], v104 offset:5120
	ds_read_b128 v[106:109], v104 offset:7168
	ds_read_b128 v[110:113], v73 offset:17408
	ds_read_b128 v[116:119], v73 offset:19456
	ds_read_b128 v[120:123], v73 offset:21504
	ds_read_b128 v[124:127], v73 offset:23552
	s_waitcnt lgkmcnt(0)
	s_barrier
	s_waitcnt vmcnt(0)
	s_barrier
	s_waitcnt lgkmcnt(3)
	v_mfma_f32_16x16x32_bf16 v[60:63], v[74:77], v[110:113], v[60:63]
	s_waitcnt lgkmcnt(2)
	v_mfma_f32_16x16x32_bf16 v[56:59], v[74:77], v[116:119], v[56:59]
	s_waitcnt lgkmcnt(1)
	v_mfma_f32_16x16x32_bf16 v[52:55], v[74:77], v[120:123], v[52:55]
	s_waitcnt lgkmcnt(0)
	v_mfma_f32_16x16x32_bf16 v[48:51], v[74:77], v[124:127], v[48:51]
	v_mfma_f32_16x16x32_bf16 v[44:47], v[82:85], v[110:113], v[44:47]
	v_mfma_f32_16x16x32_bf16 v[40:43], v[82:85], v[116:119], v[40:43]
	v_mfma_f32_16x16x32_bf16 v[36:39], v[82:85], v[120:123], v[36:39]
	v_mfma_f32_16x16x32_bf16 v[32:35], v[82:85], v[124:127], v[32:35]
	v_mfma_f32_16x16x32_bf16 v[28:31], v[86:89], v[110:113], v[28:31]
	v_mfma_f32_16x16x32_bf16 v[24:27], v[86:89], v[116:119], v[24:27]
	v_mfma_f32_16x16x32_bf16 v[20:23], v[86:89], v[120:123], v[20:23]
	v_mfma_f32_16x16x32_bf16 v[16:19], v[86:89], v[124:127], v[16:19]
	v_mfma_f32_16x16x32_bf16 v[12:15], v[106:109], v[110:113], v[12:15]
	v_mfma_f32_16x16x32_bf16 v[8:11], v[106:109], v[116:119], v[8:11]
	v_mfma_f32_16x16x32_bf16 v[4:7], v[106:109], v[120:123], v[4:7]
	v_mfma_f32_16x16x32_bf16 v[0:3], v[106:109], v[124:127], v[0:3]
	ds_read_b128 v[74:77], v104 offset:32768
	ds_read_b128 v[82:85], v104 offset:34816
	ds_read_b128 v[86:89], v104 offset:36864
	ds_read_b128 v[106:109], v104 offset:38912
	ds_read_b128 v[110:113], v73 offset:49152
	ds_read_b128 v[116:119], v73 offset:51200
	ds_read_b128 v[120:123], v73 offset:53248
	ds_read_b128 v[124:127], v73 offset:55296
	s_waitcnt lgkmcnt(3)
	v_mfma_f32_16x16x32_bf16 v[60:63], v[74:77], v[110:113], v[60:63]
	s_waitcnt lgkmcnt(2)
	v_mfma_f32_16x16x32_bf16 v[56:59], v[74:77], v[116:119], v[56:59]
	s_waitcnt lgkmcnt(1)
	v_mfma_f32_16x16x32_bf16 v[52:55], v[74:77], v[120:123], v[52:55]
	s_waitcnt lgkmcnt(0)
	v_mfma_f32_16x16x32_bf16 v[48:51], v[74:77], v[124:127], v[48:51]
	v_mfma_f32_16x16x32_bf16 v[44:47], v[82:85], v[110:113], v[44:47]
	v_mfma_f32_16x16x32_bf16 v[40:43], v[82:85], v[116:119], v[40:43]
	v_mfma_f32_16x16x32_bf16 v[36:39], v[82:85], v[120:123], v[36:39]
	v_mfma_f32_16x16x32_bf16 v[32:35], v[82:85], v[124:127], v[32:35]
	v_mfma_f32_16x16x32_bf16 v[28:31], v[86:89], v[110:113], v[28:31]
	v_mfma_f32_16x16x32_bf16 v[24:27], v[86:89], v[116:119], v[24:27]
	v_mfma_f32_16x16x32_bf16 v[20:23], v[86:89], v[120:123], v[20:23]
	v_mfma_f32_16x16x32_bf16 v[16:19], v[86:89], v[124:127], v[16:19]
	v_mfma_f32_16x16x32_bf16 v[12:15], v[106:109], v[110:113], v[12:15]
	v_mfma_f32_16x16x32_bf16 v[8:11], v[106:109], v[116:119], v[8:11]
	v_mfma_f32_16x16x32_bf16 v[4:7], v[106:109], v[120:123], v[4:7]
	v_mfma_f32_16x16x32_bf16 v[0:3], v[106:109], v[124:127], v[0:3]
	ds_read_b128 v[74:77], v104 offset:33792
	ds_read_b128 v[82:85], v104 offset:35840
	ds_read_b128 v[86:89], v104 offset:37888
	ds_read_b128 v[104:107], v104 offset:39936
	ds_read_b128 v[108:111], v73 offset:50176
	ds_read_b128 v[116:119], v73 offset:52224
	ds_read_b128 v[120:123], v73 offset:54272
	ds_read_b128 v[124:127], v73 offset:56320
	s_waitcnt lgkmcnt(0)
	s_barrier
	s_waitcnt lgkmcnt(0)
	s_barrier
	s_load_dwordx2 s[0:1], s[0:1], 0x130
	v_mov_b32_e32 v73, v80
	v_mfma_f32_16x16x32_bf16 v[60:63], v[74:77], v[108:111], v[60:63]
	s_waitcnt lgkmcnt(0)
	s_add_u32 s0, s0, s22
	s_addc_u32 s1, s1, s23
	s_lshl_b32 s17, s20, 15
	s_add_u32 s0, s0, s17
	s_addc_u32 s1, s1, 0
	v_mfma_f32_16x16x32_bf16 v[56:59], v[74:77], v[116:119], v[56:59]
	s_mov_b64 s[22:23], 0x80
	s_movk_i32 s17, 0x7f
	v_mfma_f32_16x16x32_bf16 v[52:55], v[74:77], v[120:123], v[52:55]
	v_mfma_f32_16x16x32_bf16 v[48:51], v[74:77], v[124:127], v[48:51]
	v_lshl_add_u64 v[74:75], s[0:1], 0, v[72:73]
	v_add_u32_e32 v73, 0x9000, v92
	v_lshl_add_u64 v[76:77], v[64:65], 1, v[74:75]
	v_readfirstlane_b32 s0, v73
	v_add_u32_e32 v73, 0xa000, v92
	s_mov_b32 m0, s0
	v_readfirstlane_b32 s0, v73
	v_add_u32_e32 v73, 0xb000, v92
	global_load_lds_dwordx4 v[76:77], off
	v_lshl_add_u64 v[78:79], v[66:67], 1, v[74:75]
	s_mov_b32 m0, s0
	v_readfirstlane_b32 s0, v73
	v_add_u32_e32 v73, 0xc000, v92
	v_mfma_f32_16x16x32_bf16 v[44:47], v[82:85], v[108:111], v[44:47]
	global_load_lds_dwordx4 v[78:79], off
	s_mov_b32 m0, s0
	v_mfma_f32_16x16x32_bf16 v[40:43], v[82:85], v[116:119], v[40:43]
	v_readfirstlane_b32 s0, v73
	v_add_u32_e32 v73, 0xd000, v92
	v_lshl_add_u64 v[76:77], v[76:77], 0, s[22:23]
	v_mfma_f32_16x16x32_bf16 v[36:39], v[82:85], v[120:123], v[36:39]
	v_mfma_f32_16x16x32_bf16 v[32:35], v[82:85], v[124:127], v[32:35]
	v_lshl_add_u64 v[82:83], v[68:69], 1, v[74:75]
	global_load_lds_dwordx4 v[82:83], off
	v_lshl_add_u64 v[74:75], v[70:71], 1, v[74:75]
	s_mov_b32 m0, s0
	v_readfirstlane_b32 s0, v73
	v_add_u32_e32 v73, 0xe000, v92
	global_load_lds_dwordx4 v[74:75], off
	s_mov_b32 m0, s0
	v_readfirstlane_b32 s0, v73
	v_add_u32_e32 v73, 0xf000, v92
	global_load_lds_dwordx4 v[76:77], off
	v_lshl_add_u64 v[76:77], v[78:79], 0, s[22:23]
	s_mov_b32 m0, s0
	v_readfirstlane_b32 s0, v73
	v_add_u32_e32 v73, 0xd000, v93
	global_load_lds_dwordx4 v[76:77], off
	v_lshl_add_u64 v[76:77], v[82:83], 0, s[22:23]
	s_mov_b32 m0, s0
	v_readfirstlane_b32 s0, v73
	global_load_lds_dwordx4 v[76:77], off
	v_lshl_add_u64 v[74:75], v[74:75], 0, s[22:23]
	s_mov_b32 m0, s0
	v_mfma_f32_16x16x32_bf16 v[28:31], v[86:89], v[108:111], v[28:31]
	global_load_lds_dwordx4 v[74:75], off
	v_lshl_or_b32 v74, s20, 9, v98
	v_mov_b32_e32 v73, v250
	v_mfma_f32_16x16x32_bf16 v[24:27], v[86:89], v[116:119], v[24:27]
	s_movk_i32 s22, 0x5f
	s_movk_i32 s23, 0x4f
	s_nop 0
	v_add_f32_e32 v60, v60, v73
	v_bfe_u32 v75, v60, 16, 1
	v_add3_u32 v75, v60, v75, s33
	v_add_u32_e32 v60, v96, v97
	v_add_f32_e32 v61, v61, v73
	ds_write_b16_d16_hi v60, v75
	v_bfe_u32 v75, v61, 16, 1
	v_add3_u32 v61, v61, v75, s33
	ds_write_b16_d16_hi v60, v61 offset:272
	v_add_f32_e32 v61, v62, v73
	v_bfe_u32 v62, v61, 16, 1
	v_add3_u32 v61, v61, v62, s33
	ds_write_b16_d16_hi v60, v61 offset:544
	v_add_f32_e32 v61, v63, v73
	v_bfe_u32 v62, v61, 16, 1
	v_add3_u32 v61, v61, v62, s33
	ds_write_b16_d16_hi v60, v61 offset:816
	v_mov_b32_e32 v61, v251
	v_add_f32_e32 v44, v44, v73
	v_add_f32_e32 v28, v28, v73
	v_mfma_f32_16x16x32_bf16 v[20:23], v[86:89], v[120:123], v[20:23]
	s_nop 0
	v_add_f32_e32 v56, v56, v61
	v_bfe_u32 v62, v56, 16, 1
	v_add3_u32 v56, v56, v62, s33
	ds_write_b16_d16_hi v60, v56 offset:32
	v_add_f32_e32 v56, v57, v61
	v_bfe_u32 v57, v56, 16, 1
	v_add3_u32 v56, v56, v57, s33
	ds_write_b16_d16_hi v60, v56 offset:304
	v_add_f32_e32 v56, v58, v61
	v_bfe_u32 v57, v56, 16, 1
	v_add3_u32 v56, v56, v57, s33
	ds_write_b16_d16_hi v60, v56 offset:576
	v_add_f32_e32 v56, v59, v61
	v_bfe_u32 v57, v56, 16, 1
	v_add3_u32 v56, v56, v57, s33
	ds_write_b16_d16_hi v60, v56 offset:848
	v_mov_b32_e32 v56, v252
	v_add_f32_e32 v40, v40, v61
	v_add_f32_e32 v24, v24, v61
	v_mfma_f32_16x16x32_bf16 v[16:19], v[86:89], v[124:127], v[16:19]
	s_nop 0
	v_add_f32_e32 v52, v52, v56
	v_bfe_u32 v57, v52, 16, 1
	v_add3_u32 v52, v52, v57, s33
	ds_write_b16_d16_hi v60, v52 offset:64
	v_add_f32_e32 v52, v53, v56
	v_bfe_u32 v53, v52, 16, 1
	v_add3_u32 v52, v52, v53, s33
	ds_write_b16_d16_hi v60, v52 offset:336
	v_add_f32_e32 v52, v54, v56
	v_bfe_u32 v53, v52, 16, 1
	v_add3_u32 v52, v52, v53, s33
	ds_write_b16_d16_hi v60, v52 offset:608
	v_add_f32_e32 v52, v55, v56
	v_bfe_u32 v53, v52, 16, 1
	v_add3_u32 v52, v52, v53, s33
	ds_write_b16_d16_hi v60, v52 offset:880
	v_mov_b32_e32 v52, v253
	v_add_f32_e32 v36, v36, v56
	v_add_f32_e32 v20, v20, v56
	v_mfma_f32_16x16x32_bf16 v[12:15], v[104:107], v[108:111], v[12:15]
	s_nop 0
	v_add_f32_e32 v48, v48, v52
	v_bfe_u32 v53, v48, 16, 1
	v_add3_u32 v48, v48, v53, s33
	ds_write_b16_d16_hi v60, v48 offset:96
	v_add_f32_e32 v48, v49, v52
	v_bfe_u32 v49, v48, 16, 1
	v_add3_u32 v48, v48, v49, s33
	ds_write_b16_d16_hi v60, v48 offset:368
	v_add_f32_e32 v48, v50, v52
	v_bfe_u32 v49, v48, 16, 1
	v_add3_u32 v48, v48, v49, s33
	ds_write_b16_d16_hi v60, v48 offset:640
	v_add_f32_e32 v48, v51, v52
	v_bfe_u32 v49, v48, 16, 1
	v_add3_u32 v48, v48, v49, s33
	ds_write_b16_d16_hi v60, v48 offset:912
	v_bfe_u32 v48, v44, 16, 1
	v_add3_u32 v44, v44, v48, s33
	ds_write_b16_d16_hi v60, v44 offset:4352
	v_add_f32_e32 v44, v45, v73
	v_bfe_u32 v45, v44, 16, 1
	v_add3_u32 v44, v44, v45, s33
	ds_write_b16_d16_hi v60, v44 offset:4624
	v_add_f32_e32 v44, v46, v73
	v_bfe_u32 v45, v44, 16, 1
	v_add3_u32 v44, v44, v45, s33
	ds_write_b16_d16_hi v100, v44 offset:272
	v_add_f32_e32 v44, v47, v73
	v_bfe_u32 v45, v44, 16, 1
	v_add3_u32 v44, v44, v45, s33
	ds_write_b16_d16_hi v100, v44 offset:544
	v_bfe_u32 v44, v40, 16, 1
	v_add3_u32 v40, v40, v44, s33
	ds_write_b16_d16_hi v60, v40 offset:4384
	v_add_f32_e32 v40, v41, v61
	v_bfe_u32 v41, v40, 16, 1
	v_add3_u32 v40, v40, v41, s33
	ds_write_b16_d16_hi v100, v40 offset:32
	v_add_f32_e32 v40, v42, v61
	v_bfe_u32 v41, v40, 16, 1
	v_add3_u32 v40, v40, v41, s33
	ds_write_b16_d16_hi v100, v40 offset:304
	v_add_f32_e32 v40, v43, v61
	v_bfe_u32 v41, v40, 16, 1
	v_add3_u32 v40, v40, v41, s33
	ds_write_b16_d16_hi v100, v40 offset:576
	v_bfe_u32 v40, v36, 16, 1
	v_add3_u32 v36, v36, v40, s33
	ds_write_b16_d16_hi v60, v36 offset:4416
	v_add_f32_e32 v36, v37, v56
	v_bfe_u32 v37, v36, 16, 1
	v_add3_u32 v36, v36, v37, s33
	ds_write_b16_d16_hi v100, v36 offset:64
	v_add_f32_e32 v36, v38, v56
	v_bfe_u32 v37, v36, 16, 1
	v_add3_u32 v36, v36, v37, s33
	ds_write_b16_d16_hi v100, v36 offset:336
	v_add_f32_e32 v36, v39, v56
	v_bfe_u32 v37, v36, 16, 1
	v_add3_u32 v36, v36, v37, s33
	v_add_f32_e32 v32, v32, v52
	ds_write_b16_d16_hi v100, v36 offset:608
	v_bfe_u32 v36, v32, 16, 1
	v_add3_u32 v32, v32, v36, s33
	ds_write_b16_d16_hi v60, v32 offset:4448
	v_add_f32_e32 v32, v33, v52
	v_bfe_u32 v33, v32, 16, 1
	v_add3_u32 v32, v32, v33, s33
	ds_write_b16_d16_hi v100, v32 offset:96
	v_add_f32_e32 v32, v34, v52
	v_bfe_u32 v33, v32, 16, 1
	v_add3_u32 v32, v32, v33, s33
	ds_write_b16_d16_hi v100, v32 offset:368
	v_add_f32_e32 v32, v35, v52
	v_bfe_u32 v33, v32, 16, 1
	v_add3_u32 v32, v32, v33, s33
	ds_write_b16_d16_hi v100, v32 offset:640
	v_bfe_u32 v32, v28, 16, 1
	v_add3_u32 v28, v28, v32, s33
	ds_write_b16_d16_hi v100, v28 offset:4080
	v_add_f32_e32 v28, v29, v73
	v_bfe_u32 v29, v28, 16, 1
	v_add3_u32 v28, v28, v29, s33
	ds_write_b16_d16_hi v100, v28 offset:4352
	v_add_f32_e32 v28, v30, v73
	v_bfe_u32 v29, v28, 16, 1
	v_add3_u32 v28, v28, v29, s33
	ds_write_b16_d16_hi v100, v28 offset:4624
	v_add_f32_e32 v28, v31, v73
	v_bfe_u32 v29, v28, 16, 1
	v_add3_u32 v28, v28, v29, s33
	ds_write_b16_d16_hi v100, v28 offset:4896
	v_bfe_u32 v28, v24, 16, 1
	v_add3_u32 v24, v24, v28, s33
	ds_write_b16_d16_hi v100, v24 offset:4112
	v_add_f32_e32 v24, v25, v61
	v_bfe_u32 v25, v24, 16, 1
	v_add3_u32 v24, v24, v25, s33
	ds_write_b16_d16_hi v100, v24 offset:4384
	v_add_f32_e32 v24, v26, v61
	v_bfe_u32 v25, v24, 16, 1
	v_add3_u32 v24, v24, v25, s33
	ds_write_b16_d16_hi v100, v24 offset:4656
	v_add_f32_e32 v24, v27, v61
	v_bfe_u32 v25, v24, 16, 1
	v_add3_u32 v24, v24, v25, s33
	ds_write_b16_d16_hi v100, v24 offset:4928
	v_bfe_u32 v24, v20, 16, 1
	v_add3_u32 v20, v20, v24, s33
	ds_write_b16_d16_hi v100, v20 offset:4144
	v_add_f32_e32 v20, v21, v56
	v_bfe_u32 v21, v20, 16, 1
	v_add3_u32 v20, v20, v21, s33
	ds_write_b16_d16_hi v100, v20 offset:4416
	v_add_f32_e32 v20, v22, v56
	v_bfe_u32 v21, v20, 16, 1
	v_add3_u32 v20, v20, v21, s33
	ds_write_b16_d16_hi v100, v20 offset:4688
	v_add_f32_e32 v20, v23, v56
	v_bfe_u32 v21, v20, 16, 1
	v_add3_u32 v20, v20, v21, s33
	v_add_f32_e32 v16, v16, v52
	ds_write_b16_d16_hi v100, v20 offset:4960
	v_bfe_u32 v20, v16, 16, 1
	v_add3_u32 v16, v16, v20, s33
	ds_write_b16_d16_hi v100, v16 offset:4176
	v_add_f32_e32 v16, v17, v52
	v_bfe_u32 v17, v16, 16, 1
	v_add3_u32 v16, v16, v17, s33
	ds_write_b16_d16_hi v100, v16 offset:4448
	v_add_f32_e32 v16, v18, v52
	v_bfe_u32 v17, v16, 16, 1
	v_add3_u32 v16, v16, v17, s33
	ds_write_b16_d16_hi v100, v16 offset:4720
	v_add_f32_e32 v16, v19, v52
	v_bfe_u32 v17, v16, 16, 1
	v_add3_u32 v16, v16, v17, s33
	v_add_f32_e32 v12, v12, v73
	ds_write_b16_d16_hi v100, v16 offset:4992
	v_bfe_u32 v16, v12, 16, 1
	v_add3_u32 v12, v12, v16, s33
	ds_write_b16_d16_hi v100, v12 offset:8432
	v_add_f32_e32 v12, v13, v73
	v_bfe_u32 v13, v12, 16, 1
	v_add3_u32 v12, v12, v13, s33
	ds_write_b16_d16_hi v100, v12 offset:8704
	v_add_f32_e32 v12, v14, v73
	v_mfma_f32_16x16x32_bf16 v[8:11], v[104:107], v[116:119], v[8:11]
	v_bfe_u32 v13, v12, 16, 1
	v_add3_u32 v12, v12, v13, s33
	ds_write_b16_d16_hi v100, v12 offset:8976
	v_add_f32_e32 v12, v15, v73
	v_bfe_u32 v13, v12, 16, 1
	v_add3_u32 v12, v12, v13, s33
	s_nop 1
	v_add_f32_e32 v8, v8, v61
	ds_write_b16_d16_hi v100, v12 offset:9248
	v_bfe_u32 v12, v8, 16, 1
	v_add3_u32 v8, v8, v12, s33
	ds_write_b16_d16_hi v100, v8 offset:8464
	v_add_f32_e32 v8, v9, v61
	v_bfe_u32 v9, v8, 16, 1
	v_add3_u32 v8, v8, v9, s33
	ds_write_b16_d16_hi v100, v8 offset:8736
	v_add_f32_e32 v8, v10, v61
	v_mfma_f32_16x16x32_bf16 v[4:7], v[104:107], v[120:123], v[4:7]
	v_bfe_u32 v9, v8, 16, 1
	v_add3_u32 v8, v8, v9, s33
	ds_write_b16_d16_hi v100, v8 offset:9008
	v_add_f32_e32 v8, v11, v61
	v_bfe_u32 v9, v8, 16, 1
	v_add3_u32 v8, v8, v9, s33
	s_nop 1
	v_add_f32_e32 v4, v4, v56
	ds_write_b16_d16_hi v100, v8 offset:9280
	v_bfe_u32 v8, v4, 16, 1
	v_add3_u32 v4, v4, v8, s33
	ds_write_b16_d16_hi v100, v4 offset:8496
	v_add_f32_e32 v4, v5, v56
	v_bfe_u32 v5, v4, 16, 1
	v_add3_u32 v4, v4, v5, s33
	ds_write_b16_d16_hi v100, v4 offset:8768
	v_add_f32_e32 v4, v6, v56
	v_mfma_f32_16x16x32_bf16 v[0:3], v[104:107], v[124:127], v[0:3]
	v_bfe_u32 v5, v4, 16, 1
	v_add3_u32 v4, v4, v5, s33
	ds_write_b16_d16_hi v100, v4 offset:9040
	v_add_f32_e32 v4, v7, v56
	v_bfe_u32 v5, v4, 16, 1
	v_add3_u32 v4, v4, v5, s33
	s_nop 1
	v_add_f32_e32 v0, v0, v52
	ds_write_b16_d16_hi v100, v4 offset:9312
	v_bfe_u32 v4, v0, 16, 1
	v_add3_u32 v0, v0, v4, s33
	ds_write_b16_d16_hi v100, v0 offset:8528
	v_add_f32_e32 v0, v1, v52
	v_bfe_u32 v1, v0, 16, 1
	v_add3_u32 v0, v0, v1, s33
	ds_write_b16_d16_hi v100, v0 offset:8800
	v_add_f32_e32 v0, v2, v52
	v_bfe_u32 v1, v0, 16, 1
	v_add3_u32 v0, v0, v1, s33
	ds_write_b16_d16_hi v100, v0 offset:9072
	v_add_f32_e32 v0, v3, v52
	v_bfe_u32 v1, v0, 16, 1
	v_add3_u32 v0, v0, v1, s33
	ds_write_b16_d16_hi v100, v0 offset:9344
	s_waitcnt vmcnt(0)
	s_waitcnt lgkmcnt(0)
	s_barrier
	ds_read_b128 v[0:3], v101
	ds_read_b128 v[4:7], v101 offset:4352
	ds_read_b128 v[8:11], v101 offset:8704
	ds_read_b128 v[12:15], v101 offset:13056
	ds_read_b128 v[16:19], v102 offset:36864
	ds_read_b128 v[20:23], v102 offset:38912
	ds_read_b128 v[24:27], v102 offset:40960
	ds_read_b128 v[28:31], v102 offset:43008
	s_waitcnt lgkmcnt(3)
	v_mfma_f32_16x16x32_bf16 v[32:35], v[0:3], v[16:19], 0
	s_waitcnt lgkmcnt(2)
	v_mfma_f32_16x16x32_bf16 v[36:39], v[0:3], v[20:23], 0
	s_waitcnt lgkmcnt(1)
	v_mfma_f32_16x16x32_bf16 v[40:43], v[0:3], v[24:27], 0
	s_waitcnt lgkmcnt(0)
	v_mfma_f32_16x16x32_bf16 v[0:3], v[0:3], v[28:31], 0
	v_mfma_f32_16x16x32_bf16 v[44:47], v[4:7], v[16:19], 0
	v_mfma_f32_16x16x32_bf16 v[48:51], v[4:7], v[20:23], 0
	v_mfma_f32_16x16x32_bf16 v[52:55], v[4:7], v[24:27], 0
	v_mfma_f32_16x16x32_bf16 v[4:7], v[4:7], v[28:31], 0
	v_mfma_f32_16x16x32_bf16 v[56:59], v[8:11], v[16:19], 0
	v_mfma_f32_16x16x32_bf16 v[60:63], v[8:11], v[20:23], 0
	v_mfma_f32_16x16x32_bf16 v[74:77], v[8:11], v[24:27], 0
	v_mfma_f32_16x16x32_bf16 v[8:11], v[8:11], v[28:31], 0
	v_mfma_f32_16x16x32_bf16 v[16:19], v[12:15], v[16:19], 0
	v_mfma_f32_16x16x32_bf16 v[20:23], v[12:15], v[20:23], 0
	v_mfma_f32_16x16x32_bf16 v[24:27], v[12:15], v[24:27], 0
	v_mfma_f32_16x16x32_bf16 v[12:15], v[12:15], v[28:31], 0
	ds_read_b128 v[28:31], v101 offset:64
	ds_read_b128 v[82:85], v101 offset:4416
	ds_read_b128 v[86:89], v101 offset:8768
	ds_read_b128 v[104:107], v101 offset:13120
	ds_read_b128 v[108:111], v102 offset:37888
	ds_read_b128 v[116:119], v102 offset:39936
	ds_read_b128 v[120:123], v102 offset:41984
	ds_read_b128 v[124:127], v102 offset:44032
	s_waitcnt lgkmcnt(3)
	v_mfma_f32_16x16x32_bf16 v[32:35], v[28:31], v[108:111], v[32:35]
	s_waitcnt lgkmcnt(2)
	v_mfma_f32_16x16x32_bf16 v[36:39], v[28:31], v[116:119], v[36:39]
	s_waitcnt lgkmcnt(1)
	v_mfma_f32_16x16x32_bf16 v[40:43], v[28:31], v[120:123], v[40:43]
	s_waitcnt lgkmcnt(0)
	v_mfma_f32_16x16x32_bf16 v[0:3], v[28:31], v[124:127], v[0:3]
	v_mfma_f32_16x16x32_bf16 v[28:31], v[82:85], v[108:111], v[44:47]
	v_mfma_f32_16x16x32_bf16 v[44:47], v[82:85], v[116:119], v[48:51]
	v_mfma_f32_16x16x32_bf16 v[48:51], v[82:85], v[120:123], v[52:55]
	v_mfma_f32_16x16x32_bf16 v[4:7], v[82:85], v[124:127], v[4:7]
	v_mfma_f32_16x16x32_bf16 v[52:55], v[86:89], v[108:111], v[56:59]
	v_mfma_f32_16x16x32_bf16 v[56:59], v[86:89], v[116:119], v[60:63]
	v_mfma_f32_16x16x32_bf16 v[60:63], v[86:89], v[120:123], v[74:77]
	v_mfma_f32_16x16x32_bf16 v[8:11], v[86:89], v[124:127], v[8:11]
	v_mfma_f32_16x16x32_bf16 v[16:19], v[104:107], v[108:111], v[16:19]
	v_mfma_f32_16x16x32_bf16 v[20:23], v[104:107], v[116:119], v[20:23]
	v_mfma_f32_16x16x32_bf16 v[24:27], v[104:107], v[120:123], v[24:27]
	v_mfma_f32_16x16x32_bf16 v[12:15], v[104:107], v[124:127], v[12:15]
	ds_read_b128 v[74:77], v101 offset:128
	ds_read_b128 v[82:85], v101 offset:4480
	ds_read_b128 v[86:89], v101 offset:8832
	ds_read_b128 v[104:107], v101 offset:13184
	ds_read_b128 v[108:111], v102 offset:53248
	ds_read_b128 v[116:119], v102 offset:55296
	ds_read_b128 v[120:123], v102 offset:57344
	ds_read_b128 v[124:127], v102 offset:59392
	s_waitcnt lgkmcnt(3)
	v_mfma_f32_16x16x32_bf16 v[32:35], v[74:77], v[108:111], v[32:35]
	s_waitcnt lgkmcnt(2)
	v_mfma_f32_16x16x32_bf16 v[36:39], v[74:77], v[116:119], v[36:39]
	s_waitcnt lgkmcnt(1)
	v_mfma_f32_16x16x32_bf16 v[40:43], v[74:77], v[120:123], v[40:43]
	s_waitcnt lgkmcnt(0)
	v_mfma_f32_16x16x32_bf16 v[0:3], v[74:77], v[124:127], v[0:3]
	v_mfma_f32_16x16x32_bf16 v[28:31], v[82:85], v[108:111], v[28:31]
	v_mfma_f32_16x16x32_bf16 v[44:47], v[82:85], v[116:119], v[44:47]
	v_mfma_f32_16x16x32_bf16 v[48:51], v[82:85], v[120:123], v[48:51]
	v_mfma_f32_16x16x32_bf16 v[4:7], v[82:85], v[124:127], v[4:7]
	v_mfma_f32_16x16x32_bf16 v[52:55], v[86:89], v[108:111], v[52:55]
	v_mfma_f32_16x16x32_bf16 v[56:59], v[86:89], v[116:119], v[56:59]
	v_mfma_f32_16x16x32_bf16 v[60:63], v[86:89], v[120:123], v[60:63]
	v_mfma_f32_16x16x32_bf16 v[8:11], v[86:89], v[124:127], v[8:11]
	v_mfma_f32_16x16x32_bf16 v[74:77], v[104:107], v[108:111], v[16:19]
	v_mfma_f32_16x16x32_bf16 v[82:85], v[104:107], v[116:119], v[20:23]
	v_mfma_f32_16x16x32_bf16 v[24:27], v[104:107], v[120:123], v[24:27]
	v_mfma_f32_16x16x32_bf16 v[86:89], v[104:107], v[124:127], v[12:15]
	s_nop 2
	ds_read_b128 v[12:15], v101 offset:192
	ds_read_b128 v[16:19], v101 offset:4544
	ds_read_b128 v[104:107], v101 offset:8896
	ds_read_b128 v[108:111], v101 offset:13248
	ds_read_b128 v[116:119], v102 offset:54272
	ds_read_b128 v[120:123], v102 offset:56320
	ds_read_b128 v[124:127], v102 offset:58368
	ds_read_b128 v[128:131], v102 offset:60416
	s_waitcnt lgkmcnt(0)
	s_barrier
	v_mfma_f32_16x16x32_bf16 v[32:35], v[12:15], v[116:119], v[32:35]
	v_mfma_f32_16x16x32_bf16 v[36:39], v[12:15], v[120:123], v[36:39]
	v_mfma_f32_16x16x32_bf16 v[136:139], v[16:19], v[128:131], v[4:7]
	s_nop 5
	v_cmp_gt_i32_e64 s[0:1], 0, v32
	v_mfma_f32_16x16x32_bf16 v[4:7], v[108:111], v[124:127], v[24:27]
	s_nop 2
	v_not_b32_e32 v24, v32
	v_cndmask_b32_e64 v24, -|v32|, v24, s[0:1]
	v_not_b32_e32 v26, v33
	v_cmp_gt_i32_e64 s[0:1], 0, v33
	v_not_b32_e32 v27, v34
	v_not_b32_e32 v32, v35
	v_cndmask_b32_e64 v26, -|v33|, v26, s[0:1]
	v_cmp_gt_i32_e64 s[0:1], 0, v34
	v_not_b32_e32 v33, v36
	v_and_b32_e32 v24, 0xffffff80, v24
	v_cndmask_b32_e64 v27, -|v34|, v27, s[0:1]
	v_cmp_gt_i32_e64 s[0:1], 0, v35
	v_bitop3_b32 v24, v94, s17, v24 bitop3:0x36
	v_add_u32_e32 v25, v98, v99
	v_cndmask_b32_e64 v32, -|v35|, v32, s[0:1]
	v_cmp_gt_i32_e64 s[0:1], 0, v36
	v_and_b32_e32 v26, 0xffffff80, v26
	v_bitop3_b32 v26, v94, s17, v26 bitop3:0x36
	v_cndmask_b32_e64 v33, -|v36|, v33, s[0:1]
	v_and_b32_e32 v33, 0xffffff80, v33
	v_bitop3_b32 v33, v94, s21, v33 bitop3:0x36
	ds_write2_b32 v25, v24, v33 offset1:16
	v_not_b32_e32 v24, v37
	v_cmp_gt_i32_e64 s[0:1], 0, v37
	v_and_b32_e32 v27, 0xffffff80, v27
	v_bitop3_b32 v27, v94, s17, v27 bitop3:0x36
	v_cndmask_b32_e64 v24, -|v37|, v24, s[0:1]
	v_and_b32_e32 v24, 0xffffff80, v24
	v_bitop3_b32 v24, v94, s21, v24 bitop3:0x36
	ds_write2_b32 v25, v26, v24 offset0:129 offset1:145
	v_not_b32_e32 v24, v38
	v_cmp_gt_i32_e64 s[0:1], 0, v38
	v_add_u32_e32 v26, 0x400, v25
	v_mfma_f32_16x16x32_bf16 v[40:43], v[12:15], v[124:127], v[40:43]
	v_cndmask_b32_e64 v24, -|v38|, v24, s[0:1]
	v_and_b32_e32 v24, 0xffffff80, v24
	v_bitop3_b32 v24, v94, s21, v24 bitop3:0x36
	ds_write2_b32 v26, v27, v24 offset0:2 offset1:18
	v_not_b32_e32 v24, v39
	v_cmp_gt_i32_e64 s[0:1], 0, v39
	v_and_b32_e32 v32, 0xffffff80, v32
	v_bitop3_b32 v32, v94, s17, v32 bitop3:0x36
	v_cndmask_b32_e64 v24, -|v39|, v24, s[0:1]
	v_and_b32_e32 v24, 0xffffff80, v24
	v_bitop3_b32 v24, v94, s21, v24 bitop3:0x36
	v_mfma_f32_16x16x32_bf16 v[132:135], v[12:15], v[128:131], v[0:3]
	ds_write2_b32 v26, v32, v24 offset0:131 offset1:147
	v_not_b32_e32 v24, v40
	v_cmp_gt_i32_e64 s[0:1], 0, v40
	v_not_b32_e32 v27, v41
	v_not_b32_e32 v32, v42
	v_cndmask_b32_e64 v24, -|v40|, v24, s[0:1]
	v_cmp_gt_i32_e64 s[0:1], 0, v41
	v_not_b32_e32 v33, v43
	v_not_b32_e32 v34, v132
	v_cndmask_b32_e64 v27, -|v41|, v27, s[0:1]
	v_cmp_gt_i32_e64 s[0:1], 0, v42
	v_and_b32_e32 v24, 0xffffff80, v24
	v_bitop3_b32 v24, v94, s22, v24 bitop3:0x36
	v_cndmask_b32_e64 v32, -|v42|, v32, s[0:1]
	v_cmp_gt_i32_e64 s[0:1], 0, v43
	v_and_b32_e32 v27, 0xffffff80, v27
	v_bitop3_b32 v27, v94, s22, v27 bitop3:0x36
	v_cndmask_b32_e64 v33, -|v43|, v33, s[0:1]
	v_cmp_gt_i32_e64 s[0:1], 0, v132
	v_and_b32_e32 v32, 0xffffff80, v32
	v_bitop3_b32 v32, v94, s22, v32 bitop3:0x36
	v_cndmask_b32_e64 v34, -|v132|, v34, s[0:1]
	v_and_b32_e32 v34, 0xffffff80, v34
	v_bitop3_b32 v34, v94, s23, v34 bitop3:0x36
	ds_write2_b32 v25, v24, v34 offset0:32 offset1:48
	v_not_b32_e32 v24, v133
	v_cmp_gt_i32_e64 s[0:1], 0, v133
	v_mfma_f32_16x16x32_bf16 v[28:31], v[16:19], v[116:119], v[28:31]
	v_and_b32_e32 v33, 0xffffff80, v33
	v_cndmask_b32_e64 v24, -|v133|, v24, s[0:1]
	v_and_b32_e32 v24, 0xffffff80, v24
	v_bitop3_b32 v24, v94, s23, v24 bitop3:0x36
	ds_write2_b32 v25, v27, v24 offset0:161 offset1:177
	v_not_b32_e32 v24, v134
	v_cmp_gt_i32_e64 s[0:1], 0, v134
	v_bitop3_b32 v33, v94, s22, v33 bitop3:0x36
	v_mfma_f32_16x16x32_bf16 v[44:47], v[16:19], v[120:123], v[44:47]
	v_cndmask_b32_e64 v24, -|v134|, v24, s[0:1]
	v_and_b32_e32 v24, 0xffffff80, v24
	v_bitop3_b32 v24, v94, s23, v24 bitop3:0x36
	ds_write2_b32 v26, v32, v24 offset0:34 offset1:50
	v_not_b32_e32 v24, v135
	v_cmp_gt_i32_e64 s[0:1], 0, v135
	v_not_b32_e32 v27, v31
	v_mfma_f32_16x16x32_bf16 v[48:51], v[16:19], v[124:127], v[48:51]
	v_cndmask_b32_e64 v24, -|v135|, v24, s[0:1]
	v_and_b32_e32 v24, 0xffffff80, v24
	v_bitop3_b32 v24, v94, s23, v24 bitop3:0x36
	ds_write2_b32 v26, v33, v24 offset0:163 offset1:179
	v_not_b32_e32 v24, v28
	v_cmp_gt_i32_e64 s[0:1], 0, v28
	v_not_b32_e32 v26, v29
	v_mfma_f32_16x16x32_bf16 v[52:55], v[104:107], v[116:119], v[52:55]
	v_cndmask_b32_e64 v24, -|v28|, v24, s[0:1]
	v_cmp_gt_i32_e64 s[0:1], 0, v29
	v_not_b32_e32 v28, v44
	v_and_b32_e32 v24, 0xffffff80, v24
	v_cndmask_b32_e64 v26, -|v29|, v26, s[0:1]
	v_and_b32_e32 v26, 0xffffff80, v26
	v_bitop3_b32 v26, v94, s17, v26 bitop3:0x36
	ds_write_b32 v25, v26 offset:8772
	v_not_b32_e32 v26, v30
	v_cmp_gt_i32_e64 s[0:1], 0, v30
	v_bitop3_b32 v24, v94, s17, v24 bitop3:0x36
	v_add_u32_e32 v25, 0x2000, v25
	v_cndmask_b32_e64 v26, -|v30|, v26, s[0:1]
	v_cmp_gt_i32_e64 s[0:1], 0, v31
	v_not_b32_e32 v29, v47
	v_not_b32_e32 v30, v48
	v_cndmask_b32_e64 v27, -|v31|, v27, s[0:1]
	v_cmp_gt_i32_e64 s[0:1], 0, v44
	v_not_b32_e32 v31, v49
	v_and_b32_e32 v26, 0xffffff80, v26
	v_cndmask_b32_e64 v28, -|v44|, v28, s[0:1]
	v_and_b32_e32 v28, 0xffffff80, v28
	v_bitop3_b32 v28, v94, s21, v28 bitop3:0x36
	ds_write2_b32 v25, v24, v28 offset0:16 offset1:32
	v_not_b32_e32 v24, v45
	v_cmp_gt_i32_e64 s[0:1], 0, v45
	v_not_b32_e32 v28, v46
	v_bitop3_b32 v26, v94, s17, v26 bitop3:0x36
	v_cndmask_b32_e64 v24, -|v45|, v24, s[0:1]
	v_cmp_gt_i32_e64 s[0:1], 0, v46
	v_and_b32_e32 v24, 0xffffff80, v24
	v_bitop3_b32 v24, v94, s21, v24 bitop3:0x36
	v_cndmask_b32_e64 v28, -|v46|, v28, s[0:1]
	v_cmp_gt_i32_e64 s[0:1], 0, v47
	v_and_b32_e32 v28, 0xffffff80, v28
	v_bitop3_b32 v28, v94, s21, v28 bitop3:0x36
	v_cndmask_b32_e64 v29, -|v47|, v29, s[0:1]
	v_cmp_gt_i32_e64 s[0:1], 0, v48
	v_and_b32_e32 v29, 0xffffff80, v29
	v_bitop3_b32 v29, v94, s21, v29 bitop3:0x36
	v_cndmask_b32_e64 v30, -|v48|, v30, s[0:1]
	v_cmp_gt_i32_e64 s[0:1], 0, v49
	v_and_b32_e32 v30, 0xffffff80, v30
	v_bitop3_b32 v30, v94, s22, v30 bitop3:0x36
	v_cndmask_b32_e64 v31, -|v49|, v31, s[0:1]
	v_and_b32_e32 v31, 0xffffff80, v31
	v_bitop3_b32 v31, v94, s22, v31 bitop3:0x36
	ds_write2_b32 v103, v24, v31 offset0:16 offset1:32
	v_not_b32_e32 v24, v50
	v_cmp_gt_i32_e64 s[0:1], 0, v50
	v_and_b32_e32 v27, 0xffffff80, v27
	v_bitop3_b32 v27, v94, s17, v27 bitop3:0x36
	v_cndmask_b32_e64 v24, -|v50|, v24, s[0:1]
	v_and_b32_e32 v24, 0xffffff80, v24
	v_bitop3_b32 v24, v94, s22, v24 bitop3:0x36
	ds_write2_b32 v103, v28, v24 offset0:145 offset1:161
	v_not_b32_e32 v24, v51
	v_cmp_gt_i32_e64 s[0:1], 0, v51
	v_add_u32_e32 v28, 0x400, v103
	v_mfma_f32_16x16x32_bf16 v[56:59], v[104:107], v[120:123], v[56:59]
	v_cndmask_b32_e64 v24, -|v51|, v24, s[0:1]
	v_and_b32_e32 v24, 0xffffff80, v24
	v_bitop3_b32 v24, v94, s22, v24 bitop3:0x36
	ds_write2_b32 v28, v29, v24 offset0:18 offset1:34
	v_not_b32_e32 v24, v136
	v_cmp_gt_i32_e64 s[0:1], 0, v136
	s_nop 1
	v_not_b32_e32 v28, v56
	v_add_u32_e32 v29, 0x1c00, v103
	v_cndmask_b32_e64 v24, -|v136|, v24, s[0:1]
	v_and_b32_e32 v24, 0xffffff80, v24
	v_bitop3_b32 v24, v94, s23, v24 bitop3:0x36
	ds_write2_b32 v25, v30, v24 offset0:48 offset1:64
	v_not_b32_e32 v24, v137
	v_cmp_gt_i32_e64 s[0:1], 0, v137
	v_add_u32_e32 v25, 0x200, v103
	v_mfma_f32_16x16x32_bf16 v[20:23], v[104:107], v[124:127], v[60:63]
	v_cndmask_b32_e64 v24, -|v137|, v24, s[0:1]
	v_and_b32_e32 v24, 0xffffff80, v24
	v_bitop3_b32 v24, v94, s23, v24 bitop3:0x36
	ds_write2_b32 v103, v24, v26 offset0:48 offset1:129
	v_not_b32_e32 v24, v138
	v_cmp_gt_i32_e64 s[0:1], 0, v138
	v_not_b32_e32 v26, v54
	v_mfma_f32_16x16x32_bf16 v[16:19], v[104:107], v[128:131], v[8:11]
	v_cndmask_b32_e64 v24, -|v138|, v24, s[0:1]
	v_and_b32_e32 v24, 0xffffff80, v24
	v_bitop3_b32 v24, v94, s23, v24 bitop3:0x36
	ds_write2_b32 v25, v24, v27 offset0:49 offset1:130
	v_not_b32_e32 v24, v139
	v_cmp_gt_i32_e64 s[0:1], 0, v139
	v_not_b32_e32 v25, v53
	v_not_b32_e32 v27, v55
	v_cndmask_b32_e64 v24, -|v139|, v24, s[0:1]
	v_and_b32_e32 v24, 0xffffff80, v24
	v_bitop3_b32 v24, v94, s23, v24 bitop3:0x36
	ds_write_b32 v103, v24 offset:1224
	v_not_b32_e32 v24, v52
	v_cmp_gt_i32_e64 s[0:1], 0, v52
	v_mfma_f32_16x16x32_bf16 v[12:15], v[108:111], v[116:119], v[74:77]
	s_nop 0
	v_cndmask_b32_e64 v24, -|v52|, v24, s[0:1]
	v_cmp_gt_i32_e64 s[0:1], 0, v53
	v_and_b32_e32 v24, 0xffffff80, v24
	v_bitop3_b32 v24, v94, s17, v24 bitop3:0x36
	v_cndmask_b32_e64 v25, -|v53|, v25, s[0:1]
	v_cmp_gt_i32_e64 s[0:1], 0, v54
	v_and_b32_e32 v25, 0xffffff80, v25
	v_bitop3_b32 v25, v94, s17, v25 bitop3:0x36
	v_cndmask_b32_e64 v26, -|v54|, v26, s[0:1]
	v_cmp_gt_i32_e64 s[0:1], 0, v55
	v_and_b32_e32 v26, 0xffffff80, v26
	v_bitop3_b32 v26, v94, s17, v26 bitop3:0x36
	v_cndmask_b32_e64 v27, -|v55|, v27, s[0:1]
	v_cmp_gt_i32_e64 s[0:1], 0, v56
	v_and_b32_e32 v27, 0xffffff80, v27
	v_bitop3_b32 v27, v94, s17, v27 bitop3:0x36
	v_cndmask_b32_e64 v28, -|v56|, v28, s[0:1]
	v_and_b32_e32 v28, 0xffffff80, v28
	v_bitop3_b32 v28, v94, s21, v28 bitop3:0x36
	ds_write2_b32 v29, v24, v28 offset0:143 offset1:159
	v_not_b32_e32 v24, v57
	v_cmp_gt_i32_e64 s[0:1], 0, v57
	v_add_u32_e32 v28, 0x2000, v103
	v_mfma_f32_16x16x32_bf16 v[8:11], v[108:111], v[120:123], v[82:85]
	v_cndmask_b32_e64 v24, -|v57|, v24, s[0:1]
	v_and_b32_e32 v24, 0xffffff80, v24
	v_bitop3_b32 v24, v94, s21, v24 bitop3:0x36
	ds_write2_b32 v28, v25, v24 offset0:16 offset1:32
	v_not_b32_e32 v24, v58
	v_cmp_gt_i32_e64 s[0:1], 0, v58
	v_add_u32_e32 v25, 0x2400, v103
	v_mfma_f32_16x16x32_bf16 v[0:3], v[108:111], v[128:131], v[86:89]
	v_cndmask_b32_e64 v24, -|v58|, v24, s[0:1]
	v_and_b32_e32 v24, 0xffffff80, v24
	v_bitop3_b32 v24, v94, s21, v24 bitop3:0x36
	ds_write2_b32 v28, v26, v24 offset0:145 offset1:161
	v_not_b32_e32 v24, v59
	v_cmp_gt_i32_e64 s[0:1], 0, v59
	s_nop 1
	v_cndmask_b32_e64 v24, -|v59|, v24, s[0:1]
	v_and_b32_e32 v24, 0xffffff80, v24
	v_bitop3_b32 v24, v94, s21, v24 bitop3:0x36
	ds_write2_b32 v25, v27, v24 offset0:18 offset1:34
	v_not_b32_e32 v24, v20
	v_cmp_gt_i32_e64 s[0:1], 0, v20
	s_nop 1
	v_cndmask_b32_e64 v20, -|v20|, v24, s[0:1]
	v_not_b32_e32 v24, v21
	v_cmp_gt_i32_e64 s[0:1], 0, v21
	v_and_b32_e32 v20, 0xffffff80, v20
	v_bitop3_b32 v20, v94, s22, v20 bitop3:0x36
	v_cndmask_b32_e64 v21, -|v21|, v24, s[0:1]
	v_not_b32_e32 v24, v22
	v_cmp_gt_i32_e64 s[0:1], 0, v22
	v_and_b32_e32 v21, 0xffffff80, v21
	v_bitop3_b32 v21, v94, s22, v21 bitop3:0x36
	v_cndmask_b32_e64 v22, -|v22|, v24, s[0:1]
	v_not_b32_e32 v24, v23
	v_cmp_gt_i32_e64 s[0:1], 0, v23
	v_and_b32_e32 v22, 0xffffff80, v22
	v_bitop3_b32 v22, v94, s22, v22 bitop3:0x36
	v_cndmask_b32_e64 v23, -|v23|, v24, s[0:1]
	v_not_b32_e32 v24, v16
	v_cmp_gt_i32_e64 s[0:1], 0, v16
	v_and_b32_e32 v23, 0xffffff80, v23
	v_bitop3_b32 v23, v94, s22, v23 bitop3:0x36
	v_cndmask_b32_e64 v16, -|v16|, v24, s[0:1]
	v_and_b32_e32 v16, 0xffffff80, v16
	v_bitop3_b32 v16, v94, s23, v16 bitop3:0x36
	ds_write2_b32 v29, v20, v16 offset0:175 offset1:191
	v_not_b32_e32 v16, v17
	v_cmp_gt_i32_e64 s[0:1], 0, v17
	s_nop 1
	v_cndmask_b32_e64 v16, -|v17|, v16, s[0:1]
	v_and_b32_e32 v16, 0xffffff80, v16
	v_bitop3_b32 v16, v94, s23, v16 bitop3:0x36
	ds_write2_b32 v28, v21, v16 offset0:48 offset1:64
	v_not_b32_e32 v16, v18
	v_cmp_gt_i32_e64 s[0:1], 0, v18
	s_nop 1
	v_cndmask_b32_e64 v16, -|v18|, v16, s[0:1]
	v_and_b32_e32 v16, 0xffffff80, v16
	v_bitop3_b32 v16, v94, s23, v16 bitop3:0x36
	ds_write2_b32 v28, v22, v16 offset0:177 offset1:193
	v_not_b32_e32 v16, v19
	v_cmp_gt_i32_e64 s[0:1], 0, v19
	s_nop 1
	v_cndmask_b32_e64 v16, -|v19|, v16, s[0:1]
	v_and_b32_e32 v16, 0xffffff80, v16
	v_bitop3_b32 v16, v94, s23, v16 bitop3:0x36
	ds_write2_b32 v25, v23, v16 offset0:50 offset1:66
	v_not_b32_e32 v16, v12
	v_cmp_gt_i32_e64 s[0:1], 0, v12
	s_nop 1
	v_cndmask_b32_e64 v12, -|v12|, v16, s[0:1]
	v_not_b32_e32 v16, v13
	v_cmp_gt_i32_e64 s[0:1], 0, v13
	v_and_b32_e32 v12, 0xffffff80, v12
	v_bitop3_b32 v12, v94, s17, v12 bitop3:0x36
	v_cndmask_b32_e64 v13, -|v13|, v16, s[0:1]
	v_not_b32_e32 v16, v14
	v_cmp_gt_i32_e64 s[0:1], 0, v14
	v_and_b32_e32 v13, 0xffffff80, v13
	v_bitop3_b32 v13, v94, s17, v13 bitop3:0x36
	v_cndmask_b32_e64 v14, -|v14|, v16, s[0:1]
	v_not_b32_e32 v16, v15
	v_cmp_gt_i32_e64 s[0:1], 0, v15
	v_and_b32_e32 v14, 0xffffff80, v14
	v_bitop3_b32 v14, v94, s17, v14 bitop3:0x36
	v_cndmask_b32_e64 v15, -|v15|, v16, s[0:1]
	v_not_b32_e32 v16, v8
	v_cmp_gt_i32_e64 s[0:1], 0, v8
	v_and_b32_e32 v15, 0xffffff80, v15
	v_bitop3_b32 v15, v94, s17, v15 bitop3:0x36
	v_cndmask_b32_e64 v8, -|v8|, v16, s[0:1]
	v_and_b32_e32 v8, 0xffffff80, v8
	v_bitop3_b32 v8, v94, s21, v8 bitop3:0x36
	v_add_u32_e32 v16, 0x3c00, v103
	ds_write2_b32 v16, v12, v8 offset0:159 offset1:175
	v_not_b32_e32 v8, v9
	v_cmp_gt_i32_e64 s[0:1], 0, v9
	s_nop 1
	v_cndmask_b32_e64 v8, -|v9|, v8, s[0:1]
	v_and_b32_e32 v8, 0xffffff80, v8
	v_bitop3_b32 v8, v94, s21, v8 bitop3:0x36
	v_add_u32_e32 v9, 0x4000, v103
	ds_write2_b32 v9, v13, v8 offset0:32 offset1:48
	v_not_b32_e32 v8, v10
	v_cmp_gt_i32_e64 s[0:1], 0, v10
	s_nop 1
	v_cndmask_b32_e64 v8, -|v10|, v8, s[0:1]
	v_and_b32_e32 v8, 0xffffff80, v8
	v_bitop3_b32 v8, v94, s21, v8 bitop3:0x36
	ds_write2_b32 v9, v14, v8 offset0:161 offset1:177
	v_not_b32_e32 v8, v11
	v_cmp_gt_i32_e64 s[0:1], 0, v11
	v_add_u32_e32 v10, 0x4400, v103
	s_nop 0
	v_cndmask_b32_e64 v8, -|v11|, v8, s[0:1]
	v_and_b32_e32 v8, 0xffffff80, v8
	v_bitop3_b32 v8, v94, s21, v8 bitop3:0x36
	ds_write2_b32 v10, v15, v8 offset0:34 offset1:50
	v_not_b32_e32 v8, v4
	v_cmp_gt_i32_e64 s[0:1], 0, v4
	s_nop 1
	v_cndmask_b32_e64 v4, -|v4|, v8, s[0:1]
	v_not_b32_e32 v8, v5
	v_cmp_gt_i32_e64 s[0:1], 0, v5
	v_and_b32_e32 v4, 0xffffff80, v4
	v_bitop3_b32 v4, v94, s22, v4 bitop3:0x36
	v_cndmask_b32_e64 v5, -|v5|, v8, s[0:1]
	v_not_b32_e32 v8, v6
	v_cmp_gt_i32_e64 s[0:1], 0, v6
	v_and_b32_e32 v5, 0xffffff80, v5
	v_bitop3_b32 v5, v94, s22, v5 bitop3:0x36
	v_cndmask_b32_e64 v6, -|v6|, v8, s[0:1]
	v_not_b32_e32 v8, v7
	v_cmp_gt_i32_e64 s[0:1], 0, v7
	v_and_b32_e32 v6, 0xffffff80, v6
	v_bitop3_b32 v6, v94, s22, v6 bitop3:0x36
	v_cndmask_b32_e64 v7, -|v7|, v8, s[0:1]
	v_not_b32_e32 v8, v0
	v_cmp_gt_i32_e64 s[0:1], 0, v0
	v_and_b32_e32 v7, 0xffffff80, v7
	v_bitop3_b32 v7, v94, s22, v7 bitop3:0x36
	v_cndmask_b32_e64 v0, -|v0|, v8, s[0:1]
	v_and_b32_e32 v0, 0xffffff80, v0
	v_bitop3_b32 v0, v94, s23, v0 bitop3:0x36
	ds_write2_b32 v16, v4, v0 offset0:191 offset1:207
	v_not_b32_e32 v0, v1
	v_cmp_gt_i32_e64 s[0:1], 0, v1
	s_nop 1
	v_cndmask_b32_e64 v0, -|v1|, v0, s[0:1]
	v_and_b32_e32 v0, 0xffffff80, v0
	v_bitop3_b32 v0, v94, s23, v0 bitop3:0x36
	ds_write2_b32 v9, v5, v0 offset0:64 offset1:80
	v_not_b32_e32 v0, v2
	v_cmp_gt_i32_e64 s[0:1], 0, v2
	s_nop 1
	v_cndmask_b32_e64 v0, -|v2|, v0, s[0:1]
	v_and_b32_e32 v0, 0xffffff80, v0
	v_bitop3_b32 v0, v94, s23, v0 bitop3:0x36
	ds_write2_b32 v9, v6, v0 offset0:193 offset1:209
	v_not_b32_e32 v0, v3
	v_cmp_gt_i32_e64 s[0:1], 0, v3
	s_nop 1
	v_cndmask_b32_e64 v0, -|v3|, v0, s[0:1]
	v_and_b32_e32 v0, 0xffffff80, v0
	v_bitop3_b32 v0, v94, s23, v0 bitop3:0x36
	ds_write2_b32 v10, v7, v0 offset0:66 offset1:82
	s_waitcnt lgkmcnt(0)
	s_barrier
	s_and_saveexec_b64 s[0:1], vcc
	s_cbranch_execz .LBB0_19
	ds_read2_b32 v[0:1], v95 offset1:1
	ds_read2_b32 v[2:3], v95 offset0:2 offset1:3
	ds_read2_b32 v[4:5], v95 offset0:4 offset1:5
	ds_read2_b32 v[6:7], v95 offset0:6 offset1:7
	ds_read2_b32 v[8:9], v95 offset0:8 offset1:9
	ds_read2_b32 v[10:11], v95 offset0:10 offset1:11
	ds_read2_b32 v[12:13], v95 offset0:12 offset1:13
	ds_read2_b32 v[14:15], v95 offset0:14 offset1:15
	ds_read2_b32 v[16:17], v95 offset0:16 offset1:17
	ds_read2_b32 v[18:19], v95 offset0:18 offset1:19
	ds_read2_b32 v[20:21], v95 offset0:20 offset1:21
	ds_read2_b32 v[22:23], v95 offset0:22 offset1:23
	ds_read2_b32 v[24:25], v95 offset0:24 offset1:25
	ds_read2_b32 v[26:27], v95 offset0:26 offset1:27
	ds_read2_b32 v[28:29], v95 offset0:28 offset1:29
	ds_read2_b32 v[30:31], v95 offset0:30 offset1:31
	ds_read2_b32 v[32:33], v95 offset0:32 offset1:33
	ds_read2_b32 v[34:35], v95 offset0:34 offset1:35
	ds_read2_b32 v[36:37], v95 offset0:36 offset1:37
	ds_read2_b32 v[38:39], v95 offset0:38 offset1:39
	ds_read2_b32 v[40:41], v95 offset0:40 offset1:41
	ds_read2_b32 v[42:43], v95 offset0:42 offset1:43
	ds_read2_b32 v[44:45], v95 offset0:44 offset1:45
	ds_read2_b32 v[46:47], v95 offset0:46 offset1:47
	ds_read2_b32 v[48:49], v95 offset0:48 offset1:49
	ds_read2_b32 v[50:51], v95 offset0:50 offset1:51
	ds_read2_b32 v[52:53], v95 offset0:52 offset1:53
	ds_read2_b32 v[54:55], v95 offset0:54 offset1:55
	ds_read2_b32 v[56:57], v95 offset0:56 offset1:57
	ds_read2_b32 v[58:59], v95 offset0:58 offset1:59
	ds_read2_b32 v[60:61], v95 offset0:60 offset1:61
	ds_read2_b32 v[62:63], v95 offset0:62 offset1:63
	ds_read2_b32 v[74:75], v95 offset0:64 offset1:65
	ds_read2_b32 v[76:77], v95 offset0:66 offset1:67
	ds_read2_b32 v[78:79], v95 offset0:68 offset1:69
	ds_read2_b32 v[82:83], v95 offset0:70 offset1:71
	ds_read2_b32 v[84:85], v95 offset0:72 offset1:73
	ds_read2_b32 v[86:87], v95 offset0:74 offset1:75
	ds_read2_b32 v[88:89], v95 offset0:76 offset1:77
	ds_read2_b32 v[90:91], v95 offset0:78 offset1:79
	ds_read2_b32 v[104:105], v95 offset0:80 offset1:81
	ds_read2_b32 v[106:107], v95 offset0:82 offset1:83
	ds_read2_b32 v[108:109], v95 offset0:84 offset1:85
	ds_read2_b32 v[110:111], v95 offset0:86 offset1:87
	ds_read2_b32 v[112:113], v95 offset0:88 offset1:89
	ds_read2_b32 v[116:117], v95 offset0:90 offset1:91
	ds_read2_b32 v[118:119], v95 offset0:92 offset1:93
	ds_read2_b32 v[120:121], v95 offset0:94 offset1:95
	ds_read2_b32 v[122:123], v95 offset0:96 offset1:97
	ds_read2_b32 v[124:125], v95 offset0:98 offset1:99
	ds_read2_b32 v[126:127], v95 offset0:100 offset1:101
	ds_read2_b32 v[128:129], v95 offset0:102 offset1:103
	ds_read2_b32 v[130:131], v95 offset0:104 offset1:105
	ds_read2_b32 v[132:133], v95 offset0:106 offset1:107
	ds_read2_b32 v[134:135], v95 offset0:108 offset1:109
	ds_read2_b32 v[136:137], v95 offset0:110 offset1:111
	ds_read2_b32 v[138:139], v95 offset0:112 offset1:113
	ds_read2_b32 v[140:141], v95 offset0:114 offset1:115
	ds_read2_b32 v[142:143], v95 offset0:116 offset1:117
	ds_read2_b32 v[144:145], v95 offset0:118 offset1:119
	ds_read2_b32 v[146:147], v95 offset0:120 offset1:121
	ds_read2_b32 v[148:149], v95 offset0:122 offset1:123
	ds_read2_b32 v[150:151], v95 offset0:124 offset1:125
	ds_read2_b32 v[152:153], v95 offset0:126 offset1:127
	s_waitcnt lgkmcnt(14)
	v_max_u32_e32 v73, v0, v1
	v_min_u32_e32 v0, v0, v1
	v_max_u32_e32 v1, v2, v3
	v_min_u32_e32 v2, v2, v3
	v_max_u32_e32 v3, v4, v5
	v_min_u32_e32 v4, v4, v5
	v_max_u32_e32 v5, v6, v7
	v_min_u32_e32 v6, v6, v7
	v_max_u32_e32 v7, v8, v9
	v_min_u32_e32 v8, v8, v9
	v_max_u32_e32 v9, v10, v11
	v_min_u32_e32 v10, v10, v11
	v_max_u32_e32 v11, v12, v13
	v_min_u32_e32 v12, v12, v13
	v_max_u32_e32 v13, v14, v15
	v_min_u32_e32 v14, v14, v15
	v_max_u32_e32 v15, v16, v17
	v_min_u32_e32 v16, v16, v17
	v_max_u32_e32 v17, v18, v19
	v_min_u32_e32 v18, v18, v19
	v_max_u32_e32 v19, v20, v21
	v_min_u32_e32 v20, v20, v21
	v_max_u32_e32 v21, v22, v23
	v_min_u32_e32 v22, v22, v23
	v_max_u32_e32 v23, v24, v25
	v_min_u32_e32 v24, v24, v25
	v_max_u32_e32 v25, v26, v27
	v_min_u32_e32 v26, v26, v27
	v_max_u32_e32 v27, v28, v29
	v_min_u32_e32 v28, v28, v29
	v_max_u32_e32 v29, v30, v31
	v_min_u32_e32 v30, v30, v31
	v_max_u32_e32 v31, v32, v33
	v_min_u32_e32 v32, v32, v33
	v_max_u32_e32 v33, v34, v35
	v_min_u32_e32 v34, v34, v35
	v_max_u32_e32 v35, v36, v37
	v_min_u32_e32 v36, v36, v37
	v_max_u32_e32 v37, v38, v39
	v_min_u32_e32 v38, v38, v39
	v_max_u32_e32 v39, v40, v41
	v_min_u32_e32 v40, v40, v41
	v_max_u32_e32 v41, v42, v43
	v_min_u32_e32 v42, v42, v43
	v_max_u32_e32 v43, v44, v45
	v_min_u32_e32 v44, v44, v45
	v_max_u32_e32 v45, v46, v47
	v_min_u32_e32 v46, v46, v47
	v_max_u32_e32 v47, v48, v49
	v_min_u32_e32 v48, v48, v49
	v_max_u32_e32 v49, v50, v51
	v_min_u32_e32 v50, v50, v51
	v_max_u32_e32 v51, v52, v53
	v_min_u32_e32 v52, v52, v53
	v_max_u32_e32 v53, v54, v55
	v_min_u32_e32 v54, v54, v55
	v_max_u32_e32 v55, v56, v57
	v_min_u32_e32 v56, v56, v57
	v_max_u32_e32 v57, v58, v59
	v_min_u32_e32 v58, v58, v59
	v_max_u32_e32 v59, v60, v61
	v_min_u32_e32 v60, v60, v61
	v_max_u32_e32 v61, v62, v63
	v_min_u32_e32 v62, v62, v63
	v_max_u32_e32 v63, v74, v75
	v_min_u32_e32 v74, v74, v75
	v_max_u32_e32 v75, v76, v77
	v_min_u32_e32 v76, v76, v77
	v_max_u32_e32 v77, v78, v79
	v_min_u32_e32 v78, v78, v79
	v_max_u32_e32 v79, v82, v83
	v_min_u32_e32 v82, v82, v83
	v_max_u32_e32 v83, v84, v85
	v_min_u32_e32 v84, v84, v85
	v_max_u32_e32 v85, v86, v87
	v_min_u32_e32 v86, v86, v87
	v_max_u32_e32 v87, v88, v89
	v_min_u32_e32 v88, v88, v89
	v_max_u32_e32 v89, v90, v91
	v_min_u32_e32 v90, v90, v91
	v_max_u32_e32 v91, v104, v105
	v_min_u32_e32 v104, v104, v105
	v_max_u32_e32 v105, v106, v107
	v_min_u32_e32 v106, v106, v107
	v_max_u32_e32 v107, v108, v109
	v_min_u32_e32 v108, v108, v109
	v_max_u32_e32 v109, v110, v111
	v_min_u32_e32 v110, v110, v111
	v_max_u32_e32 v111, v112, v113
	v_min_u32_e32 v112, v112, v113
	v_max_u32_e32 v113, v116, v117
	v_min_u32_e32 v116, v116, v117
	v_max_u32_e32 v117, v118, v119
	v_min_u32_e32 v118, v118, v119
	v_max_u32_e32 v119, v120, v121
	v_min_u32_e32 v120, v120, v121
	v_max_u32_e32 v121, v122, v123
	v_min_u32_e32 v122, v122, v123
	v_max_u32_e32 v123, v124, v125
	v_min_u32_e32 v124, v124, v125
	s_waitcnt lgkmcnt(13)
	v_max_u32_e32 v125, v126, v127
	v_min_u32_e32 v126, v126, v127
	s_waitcnt lgkmcnt(12)
	v_max_u32_e32 v127, v128, v129
	v_min_u32_e32 v128, v128, v129
	s_waitcnt lgkmcnt(11)
	v_max_u32_e32 v129, v130, v131
	v_min_u32_e32 v130, v130, v131
	s_waitcnt lgkmcnt(10)
	v_max_u32_e32 v131, v132, v133
	v_min_u32_e32 v132, v132, v133
	s_waitcnt lgkmcnt(9)
	v_max_u32_e32 v133, v134, v135
	v_min_u32_e32 v134, v134, v135
	s_waitcnt lgkmcnt(8)
	v_max_u32_e32 v135, v136, v137
	v_min_u32_e32 v136, v136, v137
	s_waitcnt lgkmcnt(7)
	v_max_u32_e32 v137, v138, v139
	v_min_u32_e32 v138, v138, v139
	s_waitcnt lgkmcnt(6)
	v_max_u32_e32 v139, v140, v141
	v_min_u32_e32 v140, v140, v141
	s_waitcnt lgkmcnt(5)
	v_max_u32_e32 v141, v142, v143
	v_min_u32_e32 v142, v142, v143
	s_waitcnt lgkmcnt(4)
	v_max_u32_e32 v143, v144, v145
	v_min_u32_e32 v144, v144, v145
	s_waitcnt lgkmcnt(3)
	v_max_u32_e32 v145, v146, v147
	v_min_u32_e32 v146, v146, v147
	s_waitcnt lgkmcnt(2)
	v_max_u32_e32 v147, v148, v149
	v_min_u32_e32 v148, v148, v149
	s_waitcnt lgkmcnt(1)
	v_max_u32_e32 v149, v150, v151
	v_min_u32_e32 v150, v150, v151
	s_waitcnt lgkmcnt(0)
	v_max_u32_e32 v151, v152, v153
	v_min_u32_e32 v152, v152, v153
	v_max_u32_e32 v153, v73, v2
	v_min_u32_e32 v2, v73, v2
	v_max_u32_e32 v73, v0, v1
	v_min_u32_e32 v0, v0, v1
	v_max_u32_e32 v1, v3, v6
	v_min_u32_e32 v3, v3, v6
	v_max_u32_e32 v6, v4, v5
	v_min_u32_e32 v4, v4, v5
	v_max_u32_e32 v5, v7, v10
	v_min_u32_e32 v7, v7, v10
	v_max_u32_e32 v10, v8, v9
	v_min_u32_e32 v8, v8, v9
	v_max_u32_e32 v9, v11, v14
	v_min_u32_e32 v11, v11, v14
	v_max_u32_e32 v14, v12, v13
	v_min_u32_e32 v12, v12, v13
	v_max_u32_e32 v13, v15, v18
	v_min_u32_e32 v15, v15, v18
	v_max_u32_e32 v18, v16, v17
	v_min_u32_e32 v16, v16, v17
	v_max_u32_e32 v17, v19, v22
	v_min_u32_e32 v19, v19, v22
	v_max_u32_e32 v22, v20, v21
	v_min_u32_e32 v20, v20, v21
	v_max_u32_e32 v21, v23, v26
	v_min_u32_e32 v23, v23, v26
	v_max_u32_e32 v26, v24, v25
	v_min_u32_e32 v24, v24, v25
	v_max_u32_e32 v25, v27, v30
	v_min_u32_e32 v27, v27, v30
	v_max_u32_e32 v30, v28, v29
	v_min_u32_e32 v28, v28, v29
	v_max_u32_e32 v29, v31, v34
	v_min_u32_e32 v31, v31, v34
	v_max_u32_e32 v34, v32, v33
	v_min_u32_e32 v32, v32, v33
	v_max_u32_e32 v33, v35, v38
	v_min_u32_e32 v35, v35, v38
	v_max_u32_e32 v38, v36, v37
	v_min_u32_e32 v36, v36, v37
	v_max_u32_e32 v37, v39, v42
	v_min_u32_e32 v39, v39, v42
	v_max_u32_e32 v42, v40, v41
	v_min_u32_e32 v40, v40, v41
	v_max_u32_e32 v41, v43, v46
	v_min_u32_e32 v43, v43, v46
	v_max_u32_e32 v46, v44, v45
	v_min_u32_e32 v44, v44, v45
	v_max_u32_e32 v45, v47, v50
	v_min_u32_e32 v47, v47, v50
	v_max_u32_e32 v50, v48, v49
	v_min_u32_e32 v48, v48, v49
	v_max_u32_e32 v49, v51, v54
	v_min_u32_e32 v51, v51, v54
	v_max_u32_e32 v54, v52, v53
	v_min_u32_e32 v52, v52, v53
	v_max_u32_e32 v53, v55, v58
	v_min_u32_e32 v55, v55, v58
	v_max_u32_e32 v58, v56, v57
	v_min_u32_e32 v56, v56, v57
	v_max_u32_e32 v57, v59, v62
	v_min_u32_e32 v59, v59, v62
	v_max_u32_e32 v62, v60, v61
	v_min_u32_e32 v60, v60, v61
	v_max_u32_e32 v61, v63, v76
	v_min_u32_e32 v63, v63, v76
	v_max_u32_e32 v76, v74, v75
	v_min_u32_e32 v74, v74, v75
	v_max_u32_e32 v75, v77, v82
	v_min_u32_e32 v77, v77, v82
	v_max_u32_e32 v82, v78, v79
	v_min_u32_e32 v78, v78, v79
	v_max_u32_e32 v79, v83, v86
	v_min_u32_e32 v83, v83, v86
	v_max_u32_e32 v86, v84, v85
	v_min_u32_e32 v84, v84, v85
	v_max_u32_e32 v85, v87, v90
	v_min_u32_e32 v87, v87, v90
	v_max_u32_e32 v90, v88, v89
	v_min_u32_e32 v88, v88, v89
	v_max_u32_e32 v89, v91, v106
	v_min_u32_e32 v91, v91, v106
	v_max_u32_e32 v106, v104, v105
	v_min_u32_e32 v104, v104, v105
	v_max_u32_e32 v105, v107, v110
	v_min_u32_e32 v107, v107, v110
	v_max_u32_e32 v110, v108, v109
	v_min_u32_e32 v108, v108, v109
	v_max_u32_e32 v109, v111, v116
	v_min_u32_e32 v111, v111, v116
	v_max_u32_e32 v116, v112, v113
	v_min_u32_e32 v112, v112, v113
	v_max_u32_e32 v113, v117, v120
	v_min_u32_e32 v117, v117, v120
	v_max_u32_e32 v120, v118, v119
	v_min_u32_e32 v118, v118, v119
	v_max_u32_e32 v119, v121, v124
	v_min_u32_e32 v121, v121, v124
	v_max_u32_e32 v124, v122, v123
	v_min_u32_e32 v122, v122, v123
	v_max_u32_e32 v123, v125, v128
	v_min_u32_e32 v125, v125, v128
	v_max_u32_e32 v128, v126, v127
	v_min_u32_e32 v126, v126, v127
	v_max_u32_e32 v127, v129, v132
	v_min_u32_e32 v129, v129, v132
	v_max_u32_e32 v132, v130, v131
	v_min_u32_e32 v130, v130, v131
	v_max_u32_e32 v131, v133, v136
	v_min_u32_e32 v133, v133, v136
	v_max_u32_e32 v136, v134, v135
	v_min_u32_e32 v134, v134, v135
	v_max_u32_e32 v135, v137, v140
	v_min_u32_e32 v137, v137, v140
	v_max_u32_e32 v140, v138, v139
	v_min_u32_e32 v138, v138, v139
	v_max_u32_e32 v139, v141, v144
	v_min_u32_e32 v141, v141, v144
	v_max_u32_e32 v144, v142, v143
	v_min_u32_e32 v142, v142, v143
	v_max_u32_e32 v143, v145, v148
	v_min_u32_e32 v145, v145, v148
	v_max_u32_e32 v148, v146, v147
	v_min_u32_e32 v146, v146, v147
	v_max_u32_e32 v147, v149, v152
	v_min_u32_e32 v149, v149, v152
	v_max_u32_e32 v152, v150, v151
	v_min_u32_e32 v150, v150, v151
	v_max_u32_e32 v151, v153, v73
	v_min_u32_e32 v73, v153, v73
	v_max_u32_e32 v153, v2, v0
	v_min_u32_e32 v0, v2, v0
	v_max_u32_e32 v2, v3, v4
	v_min_u32_e32 v3, v3, v4
	v_max_u32_e32 v4, v1, v6
	v_min_u32_e32 v1, v1, v6
	v_max_u32_e32 v6, v5, v10
	v_min_u32_e32 v5, v5, v10
	v_max_u32_e32 v10, v7, v8
	v_min_u32_e32 v7, v7, v8
	v_max_u32_e32 v8, v11, v12
	v_min_u32_e32 v11, v11, v12
	v_max_u32_e32 v12, v9, v14
	v_min_u32_e32 v9, v9, v14
	v_max_u32_e32 v14, v13, v18
	v_min_u32_e32 v13, v13, v18
	v_max_u32_e32 v18, v15, v16
	v_min_u32_e32 v15, v15, v16
	v_max_u32_e32 v16, v19, v20
	v_min_u32_e32 v19, v19, v20
	v_max_u32_e32 v20, v17, v22
	v_min_u32_e32 v17, v17, v22
	v_max_u32_e32 v22, v21, v26
	v_min_u32_e32 v21, v21, v26
	v_max_u32_e32 v26, v23, v24
	v_min_u32_e32 v23, v23, v24
	v_max_u32_e32 v24, v27, v28
	v_min_u32_e32 v27, v27, v28
	v_max_u32_e32 v28, v25, v30
	v_min_u32_e32 v25, v25, v30
	v_max_u32_e32 v30, v29, v34
	v_min_u32_e32 v29, v29, v34
	v_max_u32_e32 v34, v31, v32
	v_min_u32_e32 v31, v31, v32
	v_max_u32_e32 v32, v35, v36
	v_min_u32_e32 v35, v35, v36
	v_max_u32_e32 v36, v33, v38
	v_min_u32_e32 v33, v33, v38
	v_max_u32_e32 v38, v37, v42
	v_min_u32_e32 v37, v37, v42
	v_max_u32_e32 v42, v39, v40
	v_min_u32_e32 v39, v39, v40
	v_max_u32_e32 v40, v43, v44
	v_min_u32_e32 v43, v43, v44
	v_max_u32_e32 v44, v41, v46
	v_min_u32_e32 v41, v41, v46
	v_max_u32_e32 v46, v45, v50
	v_min_u32_e32 v45, v45, v50
	v_max_u32_e32 v50, v47, v48
	v_min_u32_e32 v47, v47, v48
	v_max_u32_e32 v48, v51, v52
	v_min_u32_e32 v51, v51, v52
	v_max_u32_e32 v52, v49, v54
	v_min_u32_e32 v49, v49, v54
	v_max_u32_e32 v54, v53, v58
	v_min_u32_e32 v53, v53, v58
	v_max_u32_e32 v58, v55, v56
	v_min_u32_e32 v55, v55, v56
	v_max_u32_e32 v56, v59, v60
	v_min_u32_e32 v59, v59, v60
	v_max_u32_e32 v60, v57, v62
	v_min_u32_e32 v57, v57, v62
	v_max_u32_e32 v62, v61, v76
	v_min_u32_e32 v61, v61, v76
	v_max_u32_e32 v76, v63, v74
	v_min_u32_e32 v63, v63, v74
	v_max_u32_e32 v74, v77, v78
	v_min_u32_e32 v77, v77, v78
	v_max_u32_e32 v78, v75, v82
	v_min_u32_e32 v75, v75, v82
	v_max_u32_e32 v82, v79, v86
	v_min_u32_e32 v79, v79, v86
	v_max_u32_e32 v86, v83, v84
	v_min_u32_e32 v83, v83, v84
	v_max_u32_e32 v84, v87, v88
	v_min_u32_e32 v87, v87, v88
	v_max_u32_e32 v88, v85, v90
	v_min_u32_e32 v85, v85, v90
	v_max_u32_e32 v90, v89, v106
	v_min_u32_e32 v89, v89, v106
	v_max_u32_e32 v106, v91, v104
	v_min_u32_e32 v91, v91, v104
	v_max_u32_e32 v104, v107, v108
	v_min_u32_e32 v107, v107, v108
	v_max_u32_e32 v108, v105, v110
	v_min_u32_e32 v105, v105, v110
	v_max_u32_e32 v110, v109, v116
	v_min_u32_e32 v109, v109, v116
	v_max_u32_e32 v116, v111, v112
	v_min_u32_e32 v111, v111, v112
	v_max_u32_e32 v112, v117, v118
	v_min_u32_e32 v117, v117, v118
	v_max_u32_e32 v118, v113, v120
	v_min_u32_e32 v113, v113, v120
	v_max_u32_e32 v120, v119, v124
	v_min_u32_e32 v119, v119, v124
	v_max_u32_e32 v124, v121, v122
	v_min_u32_e32 v121, v121, v122
	v_max_u32_e32 v122, v125, v126
	v_min_u32_e32 v125, v125, v126
	v_max_u32_e32 v126, v123, v128
	v_min_u32_e32 v123, v123, v128
	v_max_u32_e32 v128, v127, v132
	v_min_u32_e32 v127, v127, v132
	v_max_u32_e32 v132, v129, v130
	v_min_u32_e32 v129, v129, v130
	v_max_u32_e32 v130, v133, v134
	v_min_u32_e32 v133, v133, v134
	v_max_u32_e32 v134, v131, v136
	v_min_u32_e32 v131, v131, v136
	v_max_u32_e32 v136, v135, v140
	v_min_u32_e32 v135, v135, v140
	v_max_u32_e32 v140, v137, v138
	v_min_u32_e32 v137, v137, v138
	v_max_u32_e32 v138, v141, v142
	v_min_u32_e32 v141, v141, v142
	v_max_u32_e32 v142, v139, v144
	v_min_u32_e32 v139, v139, v144
	v_max_u32_e32 v144, v143, v148
	v_min_u32_e32 v143, v143, v148
	v_max_u32_e32 v148, v145, v146
	v_min_u32_e32 v145, v145, v146
	v_max_u32_e32 v146, v149, v150
	v_min_u32_e32 v149, v149, v150
	v_max_u32_e32 v150, v147, v152
	v_min_u32_e32 v147, v147, v152
	v_max_u32_e32 v152, v151, v3
	v_min_u32_e32 v3, v151, v3
	v_max_u32_e32 v151, v73, v2
	v_min_u32_e32 v2, v73, v2
	v_max_u32_e32 v73, v153, v1
	v_min_u32_e32 v1, v153, v1
	v_max_u32_e32 v153, v0, v4
	v_min_u32_e32 v0, v0, v4
	v_max_u32_e32 v4, v6, v11
	v_min_u32_e32 v6, v6, v11
	v_max_u32_e32 v11, v5, v8
	v_min_u32_e32 v5, v5, v8
	v_max_u32_e32 v8, v10, v9
	v_min_u32_e32 v9, v10, v9
	v_max_u32_e32 v10, v7, v12
	v_min_u32_e32 v7, v7, v12
	v_max_u32_e32 v12, v14, v19
	v_min_u32_e32 v14, v14, v19
	v_max_u32_e32 v19, v13, v16
	v_min_u32_e32 v13, v13, v16
	v_max_u32_e32 v16, v18, v17
	v_min_u32_e32 v17, v18, v17
	v_max_u32_e32 v18, v15, v20
	v_min_u32_e32 v15, v15, v20
	v_max_u32_e32 v20, v22, v27
	v_min_u32_e32 v22, v22, v27
	v_max_u32_e32 v27, v21, v24
	v_min_u32_e32 v21, v21, v24
	v_max_u32_e32 v24, v26, v25
	v_min_u32_e32 v25, v26, v25
	v_max_u32_e32 v26, v23, v28
	v_min_u32_e32 v23, v23, v28
	v_max_u32_e32 v28, v30, v35
	v_min_u32_e32 v30, v30, v35
	v_max_u32_e32 v35, v29, v32
	v_min_u32_e32 v29, v29, v32
	v_max_u32_e32 v32, v34, v33
	v_min_u32_e32 v33, v34, v33
	v_max_u32_e32 v34, v31, v36
	v_min_u32_e32 v31, v31, v36
	v_max_u32_e32 v36, v38, v43
	v_min_u32_e32 v38, v38, v43
	v_max_u32_e32 v43, v37, v40
	v_min_u32_e32 v37, v37, v40
	v_max_u32_e32 v40, v42, v41
	v_min_u32_e32 v41, v42, v41
	v_max_u32_e32 v42, v39, v44
	v_min_u32_e32 v39, v39, v44
	v_max_u32_e32 v44, v46, v51
	v_min_u32_e32 v46, v46, v51
	v_max_u32_e32 v51, v45, v48
	v_min_u32_e32 v45, v45, v48
	v_max_u32_e32 v48, v50, v49
	v_min_u32_e32 v49, v50, v49
	v_max_u32_e32 v50, v47, v52
	v_min_u32_e32 v47, v47, v52
	v_max_u32_e32 v52, v54, v59
	v_min_u32_e32 v54, v54, v59
	v_max_u32_e32 v59, v53, v56
	v_min_u32_e32 v53, v53, v56
	v_max_u32_e32 v56, v58, v57
	v_min_u32_e32 v57, v58, v57
	v_max_u32_e32 v58, v55, v60
	v_min_u32_e32 v55, v55, v60
	v_max_u32_e32 v60, v62, v77
	v_min_u32_e32 v62, v62, v77
	v_max_u32_e32 v77, v61, v74
	v_min_u32_e32 v61, v61, v74
	v_max_u32_e32 v74, v76, v75
	v_min_u32_e32 v75, v76, v75
	v_max_u32_e32 v76, v63, v78
	v_min_u32_e32 v63, v63, v78
	v_max_u32_e32 v78, v82, v87
	v_min_u32_e32 v82, v82, v87
	v_max_u32_e32 v87, v79, v84
	v_min_u32_e32 v79, v79, v84
	v_max_u32_e32 v84, v86, v85
	v_min_u32_e32 v85, v86, v85
	v_max_u32_e32 v86, v83, v88
	v_min_u32_e32 v83, v83, v88
	v_max_u32_e32 v88, v90, v107
	v_min_u32_e32 v90, v90, v107
	v_max_u32_e32 v107, v89, v104
	v_min_u32_e32 v89, v89, v104
	v_max_u32_e32 v104, v106, v105
	v_min_u32_e32 v105, v106, v105
	v_max_u32_e32 v106, v91, v108
	v_min_u32_e32 v91, v91, v108
	v_max_u32_e32 v108, v110, v117
	v_min_u32_e32 v110, v110, v117
	v_max_u32_e32 v117, v109, v112
	v_min_u32_e32 v109, v109, v112
	v_max_u32_e32 v112, v116, v113
	v_min_u32_e32 v113, v116, v113
	v_max_u32_e32 v116, v111, v118
	v_min_u32_e32 v111, v111, v118
	v_max_u32_e32 v118, v120, v125
	v_min_u32_e32 v120, v120, v125
	v_max_u32_e32 v125, v119, v122
	v_min_u32_e32 v119, v119, v122
	v_max_u32_e32 v122, v124, v123
	v_min_u32_e32 v123, v124, v123
	v_max_u32_e32 v124, v121, v126
	v_min_u32_e32 v121, v121, v126
	v_max_u32_e32 v126, v128, v133
	v_min_u32_e32 v128, v128, v133
	v_max_u32_e32 v133, v127, v130
	v_min_u32_e32 v127, v127, v130
	v_max_u32_e32 v130, v132, v131
	v_min_u32_e32 v131, v132, v131
	v_max_u32_e32 v132, v129, v134
	v_min_u32_e32 v129, v129, v134
	v_max_u32_e32 v134, v136, v141
	v_min_u32_e32 v136, v136, v141
	v_max_u32_e32 v141, v135, v138
	v_min_u32_e32 v135, v135, v138
	v_max_u32_e32 v138, v140, v139
	v_min_u32_e32 v139, v140, v139
	v_max_u32_e32 v140, v137, v142
	v_min_u32_e32 v137, v137, v142
	v_max_u32_e32 v142, v144, v149
	v_min_u32_e32 v144, v144, v149
	v_max_u32_e32 v149, v143, v146
	v_min_u32_e32 v143, v143, v146
	v_max_u32_e32 v146, v148, v147
	v_min_u32_e32 v147, v148, v147
	v_max_u32_e32 v148, v145, v150
	v_min_u32_e32 v145, v145, v150
	v_max_u32_e32 v150, v152, v73
	v_min_u32_e32 v73, v152, v73
	v_max_u32_e32 v152, v151, v153
	v_min_u32_e32 v151, v151, v153
	v_max_u32_e32 v153, v3, v1
	v_min_u32_e32 v1, v3, v1
	v_max_u32_e32 v3, v2, v0
	v_min_u32_e32 v0, v2, v0
	v_max_u32_e32 v2, v6, v9
	v_min_u32_e32 v6, v6, v9
	v_max_u32_e32 v9, v5, v7
	v_min_u32_e32 v5, v5, v7
	v_max_u32_e32 v7, v4, v8
	v_min_u32_e32 v4, v4, v8
	v_max_u32_e32 v8, v11, v10
	v_min_u32_e32 v10, v11, v10
	v_max_u32_e32 v11, v12, v16
	v_min_u32_e32 v12, v12, v16
	v_max_u32_e32 v16, v19, v18
	v_min_u32_e32 v18, v19, v18
	v_max_u32_e32 v19, v14, v17
	v_min_u32_e32 v14, v14, v17
	v_max_u32_e32 v17, v13, v15
	v_min_u32_e32 v13, v13, v15
	v_max_u32_e32 v15, v22, v25
	v_min_u32_e32 v22, v22, v25
	v_max_u32_e32 v25, v21, v23
	v_min_u32_e32 v21, v21, v23
	v_max_u32_e32 v23, v20, v24
	v_min_u32_e32 v20, v20, v24
	v_max_u32_e32 v24, v27, v26
	v_min_u32_e32 v26, v27, v26
	v_max_u32_e32 v27, v28, v32
	v_min_u32_e32 v28, v28, v32
	v_max_u32_e32 v32, v35, v34
	v_min_u32_e32 v34, v35, v34
	v_max_u32_e32 v35, v30, v33
	v_min_u32_e32 v30, v30, v33
	v_max_u32_e32 v33, v29, v31
	v_min_u32_e32 v29, v29, v31
	v_max_u32_e32 v31, v38, v41
	v_min_u32_e32 v38, v38, v41
	v_max_u32_e32 v41, v37, v39
	v_min_u32_e32 v37, v37, v39
	v_max_u32_e32 v39, v36, v40
	v_min_u32_e32 v36, v36, v40
	v_max_u32_e32 v40, v43, v42
	v_min_u32_e32 v42, v43, v42
	v_max_u32_e32 v43, v44, v48
	v_min_u32_e32 v44, v44, v48
	v_max_u32_e32 v48, v51, v50
	v_min_u32_e32 v50, v51, v50
	v_max_u32_e32 v51, v46, v49
	v_min_u32_e32 v46, v46, v49
	v_max_u32_e32 v49, v45, v47
	v_min_u32_e32 v45, v45, v47
	v_max_u32_e32 v47, v54, v57
	v_min_u32_e32 v54, v54, v57
	v_max_u32_e32 v57, v53, v55
	v_min_u32_e32 v53, v53, v55
	v_max_u32_e32 v55, v52, v56
	v_min_u32_e32 v52, v52, v56
	v_max_u32_e32 v56, v59, v58
	v_min_u32_e32 v58, v59, v58
	v_max_u32_e32 v59, v60, v74
	v_min_u32_e32 v60, v60, v74
	v_max_u32_e32 v74, v77, v76
	v_min_u32_e32 v76, v77, v76
	v_max_u32_e32 v77, v62, v75
	v_min_u32_e32 v62, v62, v75
	v_max_u32_e32 v75, v61, v63
	v_min_u32_e32 v61, v61, v63
	v_max_u32_e32 v63, v82, v85
	v_min_u32_e32 v82, v82, v85
	v_max_u32_e32 v85, v79, v83
	v_min_u32_e32 v79, v79, v83
	v_max_u32_e32 v83, v78, v84
	v_min_u32_e32 v78, v78, v84
	v_max_u32_e32 v84, v87, v86
	v_min_u32_e32 v86, v87, v86
	v_max_u32_e32 v87, v88, v104
	v_min_u32_e32 v88, v88, v104
	v_max_u32_e32 v104, v107, v106
	v_min_u32_e32 v106, v107, v106
	v_max_u32_e32 v107, v90, v105
	v_min_u32_e32 v90, v90, v105
	v_max_u32_e32 v105, v89, v91
	v_min_u32_e32 v89, v89, v91
	v_max_u32_e32 v91, v110, v113
	v_min_u32_e32 v110, v110, v113
	v_max_u32_e32 v113, v109, v111
	v_min_u32_e32 v109, v109, v111
	v_max_u32_e32 v111, v108, v112
	v_min_u32_e32 v108, v108, v112
	v_max_u32_e32 v112, v117, v116
	v_min_u32_e32 v116, v117, v116
	v_max_u32_e32 v117, v118, v122
	v_min_u32_e32 v118, v118, v122
	v_max_u32_e32 v122, v125, v124
	v_min_u32_e32 v124, v125, v124
	v_max_u32_e32 v125, v120, v123
	v_min_u32_e32 v120, v120, v123
	v_max_u32_e32 v123, v119, v121
	v_min_u32_e32 v119, v119, v121
	v_max_u32_e32 v121, v128, v131
	v_min_u32_e32 v128, v128, v131
	v_max_u32_e32 v131, v127, v129
	v_min_u32_e32 v127, v127, v129
	v_max_u32_e32 v129, v126, v130
	v_min_u32_e32 v126, v126, v130
	v_max_u32_e32 v130, v133, v132
	v_min_u32_e32 v132, v133, v132
	v_max_u32_e32 v133, v134, v138
	v_min_u32_e32 v134, v134, v138
	v_max_u32_e32 v138, v141, v140
	v_min_u32_e32 v140, v141, v140
	v_max_u32_e32 v141, v136, v139
	v_min_u32_e32 v136, v136, v139
	v_max_u32_e32 v139, v135, v137
	v_min_u32_e32 v135, v135, v137
	v_max_u32_e32 v137, v144, v147
	v_min_u32_e32 v144, v144, v147
	v_max_u32_e32 v147, v143, v145
	v_min_u32_e32 v143, v143, v145
	v_max_u32_e32 v145, v142, v146
	v_min_u32_e32 v142, v142, v146
	v_max_u32_e32 v146, v149, v148
	v_min_u32_e32 v148, v149, v148
	v_max_u32_e32 v149, v150, v152
	v_min_u32_e32 v150, v150, v152
	v_max_u32_e32 v152, v73, v151
	v_min_u32_e32 v73, v73, v151
	v_max_u32_e32 v151, v153, v3
	v_min_u32_e32 v3, v153, v3
	v_max_u32_e32 v153, v1, v0
	v_min_u32_e32 v0, v1, v0
	v_max_u32_e32 v1, v6, v5
	v_min_u32_e32 v5, v6, v5
	v_max_u32_e32 v6, v2, v9
	v_min_u32_e32 v2, v2, v9
	v_max_u32_e32 v9, v4, v10
	v_min_u32_e32 v4, v4, v10
	v_max_u32_e32 v10, v7, v8
	v_min_u32_e32 v7, v7, v8
	v_max_u32_e32 v8, v11, v16
	v_min_u32_e32 v11, v11, v16
	v_max_u32_e32 v16, v12, v18
	v_min_u32_e32 v12, v12, v18
	v_max_u32_e32 v18, v19, v17
	v_min_u32_e32 v17, v19, v17
	v_max_u32_e32 v19, v14, v13
	v_min_u32_e32 v13, v14, v13
	v_max_u32_e32 v14, v22, v21
	v_min_u32_e32 v21, v22, v21
	v_max_u32_e32 v22, v15, v25
	v_min_u32_e32 v15, v15, v25
	v_max_u32_e32 v25, v20, v26
	v_min_u32_e32 v20, v20, v26
	v_max_u32_e32 v26, v23, v24
	v_min_u32_e32 v23, v23, v24
	v_max_u32_e32 v24, v27, v32
	v_min_u32_e32 v27, v27, v32
	v_max_u32_e32 v32, v28, v34
	v_min_u32_e32 v28, v28, v34
	v_max_u32_e32 v34, v35, v33
	v_min_u32_e32 v33, v35, v33
	v_max_u32_e32 v35, v30, v29
	v_min_u32_e32 v29, v30, v29
	v_max_u32_e32 v30, v38, v37
	v_min_u32_e32 v37, v38, v37
	v_max_u32_e32 v38, v31, v41
	v_min_u32_e32 v31, v31, v41
	v_max_u32_e32 v41, v36, v42
	v_min_u32_e32 v36, v36, v42
	v_max_u32_e32 v42, v39, v40
	v_min_u32_e32 v39, v39, v40
	v_max_u32_e32 v40, v43, v48
	v_min_u32_e32 v43, v43, v48
	v_max_u32_e32 v48, v44, v50
	v_min_u32_e32 v44, v44, v50
	v_max_u32_e32 v50, v51, v49
	v_min_u32_e32 v49, v51, v49
	v_max_u32_e32 v51, v46, v45
	v_min_u32_e32 v45, v46, v45
	v_max_u32_e32 v46, v54, v53
	v_min_u32_e32 v53, v54, v53
	v_max_u32_e32 v54, v47, v57
	v_min_u32_e32 v47, v47, v57
	v_max_u32_e32 v57, v52, v58
	v_min_u32_e32 v52, v52, v58
	v_max_u32_e32 v58, v55, v56
	v_min_u32_e32 v55, v55, v56
	v_max_u32_e32 v56, v59, v74
	v_min_u32_e32 v59, v59, v74
	v_max_u32_e32 v74, v60, v76
	v_min_u32_e32 v60, v60, v76
	v_max_u32_e32 v76, v77, v75
	v_min_u32_e32 v75, v77, v75
	v_max_u32_e32 v77, v62, v61
	v_min_u32_e32 v61, v62, v61
	v_max_u32_e32 v62, v82, v79
	v_min_u32_e32 v79, v82, v79
	v_max_u32_e32 v82, v63, v85
	v_min_u32_e32 v63, v63, v85
	v_max_u32_e32 v85, v78, v86
	v_min_u32_e32 v78, v78, v86
	v_max_u32_e32 v86, v83, v84
	v_min_u32_e32 v83, v83, v84
	v_max_u32_e32 v84, v87, v104
	v_min_u32_e32 v87, v87, v104
	v_max_u32_e32 v104, v88, v106
	v_min_u32_e32 v88, v88, v106
	v_max_u32_e32 v106, v107, v105
	v_min_u32_e32 v105, v107, v105
	v_max_u32_e32 v107, v90, v89
	v_min_u32_e32 v89, v90, v89
	v_max_u32_e32 v90, v110, v109
	v_min_u32_e32 v109, v110, v109
	v_max_u32_e32 v110, v91, v113
	v_min_u32_e32 v91, v91, v113
	v_max_u32_e32 v113, v108, v116
	v_min_u32_e32 v108, v108, v116
	v_max_u32_e32 v116, v111, v112
	v_min_u32_e32 v111, v111, v112
	v_max_u32_e32 v112, v117, v122
	v_min_u32_e32 v117, v117, v122
	v_max_u32_e32 v122, v118, v124
	v_min_u32_e32 v118, v118, v124
	v_max_u32_e32 v124, v125, v123
	v_min_u32_e32 v123, v125, v123
	v_max_u32_e32 v125, v120, v119
	v_min_u32_e32 v119, v120, v119
	v_max_u32_e32 v120, v128, v127
	v_min_u32_e32 v127, v128, v127
	v_max_u32_e32 v128, v121, v131
	v_min_u32_e32 v121, v121, v131
	v_max_u32_e32 v131, v126, v132
	v_min_u32_e32 v126, v126, v132
	v_max_u32_e32 v132, v129, v130
	v_min_u32_e32 v129, v129, v130
	v_max_u32_e32 v130, v133, v138
	v_min_u32_e32 v133, v133, v138
	v_max_u32_e32 v138, v134, v140
	v_min_u32_e32 v134, v134, v140
	v_max_u32_e32 v140, v141, v139
	v_min_u32_e32 v139, v141, v139
	v_max_u32_e32 v141, v136, v135
	v_min_u32_e32 v135, v136, v135
	v_max_u32_e32 v136, v144, v143
	v_min_u32_e32 v143, v144, v143
	v_max_u32_e32 v144, v137, v147
	v_min_u32_e32 v137, v137, v147
	v_max_u32_e32 v147, v142, v148
	v_min_u32_e32 v142, v142, v148
	v_max_u32_e32 v148, v145, v146
	v_min_u32_e32 v145, v145, v146
	v_max_u32_e32 v146, v149, v5
	v_min_u32_e32 v5, v149, v5
	v_max_u32_e32 v149, v150, v1
	v_min_u32_e32 v1, v150, v1
	v_max_u32_e32 v150, v152, v2
	v_min_u32_e32 v2, v152, v2
	v_max_u32_e32 v152, v73, v6
	v_min_u32_e32 v6, v73, v6
	v_max_u32_e32 v73, v151, v4
	v_min_u32_e32 v4, v151, v4
	v_max_u32_e32 v151, v3, v9
	v_min_u32_e32 v3, v3, v9
	v_max_u32_e32 v9, v153, v7
	v_min_u32_e32 v7, v153, v7
	v_max_u32_e32 v153, v0, v10
	v_min_u32_e32 v0, v0, v10
	v_max_u32_e32 v10, v8, v21
	v_min_u32_e32 v8, v8, v21
	v_max_u32_e32 v21, v11, v14
	v_min_u32_e32 v11, v11, v14
	v_max_u32_e32 v14, v16, v15
	v_min_u32_e32 v15, v16, v15
	v_max_u32_e32 v16, v12, v22
	v_min_u32_e32 v12, v12, v22
	v_max_u32_e32 v22, v18, v20
	v_min_u32_e32 v18, v18, v20
	v_max_u32_e32 v20, v17, v25
	v_min_u32_e32 v17, v17, v25
	v_max_u32_e32 v25, v19, v23
	v_min_u32_e32 v19, v19, v23
	v_max_u32_e32 v23, v13, v26
	v_min_u32_e32 v13, v13, v26
	v_max_u32_e32 v26, v24, v37
	v_min_u32_e32 v24, v24, v37
	v_max_u32_e32 v37, v27, v30
	v_min_u32_e32 v27, v27, v30
	v_max_u32_e32 v30, v32, v31
	v_min_u32_e32 v31, v32, v31
	v_max_u32_e32 v32, v28, v38
	v_min_u32_e32 v28, v28, v38
	v_max_u32_e32 v38, v34, v36
	v_min_u32_e32 v34, v34, v36
	v_max_u32_e32 v36, v33, v41
	v_min_u32_e32 v33, v33, v41
	v_max_u32_e32 v41, v35, v39
	v_min_u32_e32 v35, v35, v39
	v_max_u32_e32 v39, v29, v42
	v_min_u32_e32 v29, v29, v42
	v_max_u32_e32 v42, v40, v53
	v_min_u32_e32 v40, v40, v53
	v_max_u32_e32 v53, v43, v46
	v_min_u32_e32 v43, v43, v46
	v_max_u32_e32 v46, v48, v47
	v_min_u32_e32 v47, v48, v47
	v_max_u32_e32 v48, v44, v54
	v_min_u32_e32 v44, v44, v54
	v_max_u32_e32 v54, v50, v52
	v_min_u32_e32 v50, v50, v52
	v_max_u32_e32 v52, v49, v57
	v_min_u32_e32 v49, v49, v57
	v_max_u32_e32 v57, v51, v55
	v_min_u32_e32 v51, v51, v55
	v_max_u32_e32 v55, v45, v58
	v_min_u32_e32 v45, v45, v58
	v_max_u32_e32 v58, v56, v79
	v_min_u32_e32 v56, v56, v79
	v_max_u32_e32 v79, v59, v62
	v_min_u32_e32 v59, v59, v62
	v_max_u32_e32 v62, v74, v63
	v_min_u32_e32 v63, v74, v63
	v_max_u32_e32 v74, v60, v82
	v_min_u32_e32 v60, v60, v82
	v_max_u32_e32 v82, v76, v78
	v_min_u32_e32 v76, v76, v78
	v_max_u32_e32 v78, v75, v85
	v_min_u32_e32 v75, v75, v85
	v_max_u32_e32 v85, v77, v83
	v_min_u32_e32 v77, v77, v83
	v_max_u32_e32 v83, v61, v86
	v_min_u32_e32 v61, v61, v86
	v_max_u32_e32 v86, v84, v109
	v_min_u32_e32 v84, v84, v109
	v_max_u32_e32 v109, v87, v90
	v_min_u32_e32 v87, v87, v90
	v_max_u32_e32 v90, v104, v91
	v_min_u32_e32 v91, v104, v91
	v_max_u32_e32 v104, v88, v110
	v_min_u32_e32 v88, v88, v110
	v_max_u32_e32 v110, v106, v108
	v_min_u32_e32 v106, v106, v108
	v_max_u32_e32 v108, v105, v113
	v_min_u32_e32 v105, v105, v113
	v_max_u32_e32 v113, v107, v111
	v_min_u32_e32 v107, v107, v111
	v_max_u32_e32 v111, v89, v116
	v_min_u32_e32 v89, v89, v116
	v_max_u32_e32 v116, v112, v127
	v_min_u32_e32 v112, v112, v127
	v_max_u32_e32 v127, v117, v120
	v_min_u32_e32 v117, v117, v120
	v_max_u32_e32 v120, v122, v121
	v_min_u32_e32 v121, v122, v121
	v_max_u32_e32 v122, v118, v128
	v_min_u32_e32 v118, v118, v128
	v_max_u32_e32 v128, v124, v126
	v_min_u32_e32 v124, v124, v126
	v_max_u32_e32 v126, v123, v131
	v_min_u32_e32 v123, v123, v131
	v_max_u32_e32 v131, v125, v129
	v_min_u32_e32 v125, v125, v129
	v_max_u32_e32 v129, v119, v132
	v_min_u32_e32 v119, v119, v132
	v_max_u32_e32 v132, v130, v143
	v_min_u32_e32 v130, v130, v143
	v_max_u32_e32 v143, v133, v136
	v_min_u32_e32 v133, v133, v136
	v_max_u32_e32 v136, v138, v137
	v_min_u32_e32 v137, v138, v137
	v_max_u32_e32 v138, v134, v144
	v_min_u32_e32 v134, v134, v144
	v_max_u32_e32 v144, v140, v142
	v_min_u32_e32 v140, v140, v142
	v_max_u32_e32 v142, v139, v147
	v_min_u32_e32 v139, v139, v147
	v_max_u32_e32 v147, v141, v145
	v_min_u32_e32 v141, v141, v145
	v_max_u32_e32 v145, v135, v148
	v_min_u32_e32 v135, v135, v148
	v_max_u32_e32 v148, v146, v73
	v_min_u32_e32 v73, v146, v73
	v_max_u32_e32 v146, v149, v151
	v_min_u32_e32 v149, v149, v151
	v_max_u32_e32 v151, v150, v9
	v_min_u32_e32 v9, v150, v9
	v_max_u32_e32 v150, v152, v153
	v_min_u32_e32 v152, v152, v153
	v_max_u32_e32 v153, v5, v4
	v_min_u32_e32 v4, v5, v4
	v_max_u32_e32 v5, v1, v3
	v_min_u32_e32 v1, v1, v3
	v_max_u32_e32 v3, v2, v7
	v_min_u32_e32 v2, v2, v7
	v_max_u32_e32 v7, v6, v0
	v_min_u32_e32 v0, v6, v0
	v_max_u32_e32 v6, v8, v18
	v_min_u32_e32 v8, v8, v18
	v_max_u32_e32 v18, v11, v17
	v_min_u32_e32 v11, v11, v17
	v_max_u32_e32 v17, v15, v19
	v_min_u32_e32 v15, v15, v19
	v_max_u32_e32 v19, v12, v13
	v_min_u32_e32 v12, v12, v13
	v_max_u32_e32 v13, v10, v22
	v_min_u32_e32 v10, v10, v22
	v_max_u32_e32 v22, v21, v20
	v_min_u32_e32 v20, v21, v20
	v_max_u32_e32 v21, v14, v25
	v_min_u32_e32 v14, v14, v25
	v_max_u32_e32 v25, v16, v23
	v_min_u32_e32 v16, v16, v23
	v_max_u32_e32 v23, v26, v38
	v_min_u32_e32 v26, v26, v38
	v_max_u32_e32 v38, v37, v36
	v_min_u32_e32 v36, v37, v36
	v_max_u32_e32 v37, v30, v41
	v_min_u32_e32 v30, v30, v41
	v_max_u32_e32 v41, v32, v39
	v_min_u32_e32 v32, v32, v39
	v_max_u32_e32 v39, v24, v34
	v_min_u32_e32 v24, v24, v34
	v_max_u32_e32 v34, v27, v33
	v_min_u32_e32 v27, v27, v33
	v_max_u32_e32 v33, v31, v35
	v_min_u32_e32 v31, v31, v35
	v_max_u32_e32 v35, v28, v29
	v_min_u32_e32 v28, v28, v29
	v_max_u32_e32 v29, v40, v50
	v_min_u32_e32 v40, v40, v50
	v_max_u32_e32 v50, v43, v49
	v_min_u32_e32 v43, v43, v49
	v_max_u32_e32 v49, v47, v51
	v_min_u32_e32 v47, v47, v51
	v_max_u32_e32 v51, v44, v45
	v_min_u32_e32 v44, v44, v45
	v_max_u32_e32 v45, v42, v54
	v_min_u32_e32 v42, v42, v54
	v_max_u32_e32 v54, v53, v52
	v_min_u32_e32 v52, v53, v52
	v_max_u32_e32 v53, v46, v57
	v_min_u32_e32 v46, v46, v57
	v_max_u32_e32 v57, v48, v55
	v_min_u32_e32 v48, v48, v55
	v_max_u32_e32 v55, v58, v82
	v_min_u32_e32 v58, v58, v82
	v_max_u32_e32 v82, v79, v78
	v_min_u32_e32 v78, v79, v78
	v_max_u32_e32 v79, v62, v85
	v_min_u32_e32 v62, v62, v85
	v_max_u32_e32 v85, v74, v83
	v_min_u32_e32 v74, v74, v83
	v_max_u32_e32 v83, v56, v76
	v_min_u32_e32 v56, v56, v76
	v_max_u32_e32 v76, v59, v75
	v_min_u32_e32 v59, v59, v75
	v_max_u32_e32 v75, v63, v77
	v_min_u32_e32 v63, v63, v77
	v_max_u32_e32 v77, v60, v61
	v_min_u32_e32 v60, v60, v61
	v_max_u32_e32 v61, v84, v106
	v_min_u32_e32 v84, v84, v106
	v_max_u32_e32 v106, v87, v105
	v_min_u32_e32 v87, v87, v105
	v_max_u32_e32 v105, v91, v107
	v_min_u32_e32 v91, v91, v107
	v_max_u32_e32 v107, v88, v89
	v_min_u32_e32 v88, v88, v89
	v_max_u32_e32 v89, v86, v110
	v_min_u32_e32 v86, v86, v110
	v_max_u32_e32 v110, v109, v108
	v_min_u32_e32 v108, v109, v108
	v_max_u32_e32 v109, v90, v113
	v_min_u32_e32 v90, v90, v113
	v_max_u32_e32 v113, v104, v111
	v_min_u32_e32 v104, v104, v111
	v_max_u32_e32 v111, v116, v128
	v_min_u32_e32 v116, v116, v128
	v_max_u32_e32 v128, v127, v126
	v_min_u32_e32 v126, v127, v126
	v_max_u32_e32 v127, v120, v131
	v_min_u32_e32 v120, v120, v131
	v_max_u32_e32 v131, v122, v129
	v_min_u32_e32 v122, v122, v129
	v_max_u32_e32 v129, v112, v124
	v_min_u32_e32 v112, v112, v124
	v_max_u32_e32 v124, v117, v123
	v_min_u32_e32 v117, v117, v123
	v_max_u32_e32 v123, v121, v125
	v_min_u32_e32 v121, v121, v125
	v_max_u32_e32 v125, v118, v119
	v_min_u32_e32 v118, v118, v119
	v_max_u32_e32 v119, v130, v140
	v_min_u32_e32 v130, v130, v140
	v_max_u32_e32 v140, v133, v139
	v_min_u32_e32 v133, v133, v139
	v_max_u32_e32 v139, v137, v141
	v_min_u32_e32 v137, v137, v141
	v_max_u32_e32 v141, v134, v135
	v_min_u32_e32 v134, v134, v135
	v_max_u32_e32 v135, v132, v144
	v_min_u32_e32 v132, v132, v144
	v_max_u32_e32 v144, v143, v142
	v_min_u32_e32 v142, v143, v142
	v_max_u32_e32 v143, v136, v147
	v_min_u32_e32 v136, v136, v147
	v_max_u32_e32 v147, v138, v145
	v_min_u32_e32 v138, v138, v145
	v_max_u32_e32 v145, v148, v151
	v_min_u32_e32 v148, v148, v151
	v_max_u32_e32 v151, v146, v150
	v_min_u32_e32 v146, v146, v150
	v_max_u32_e32 v150, v73, v9
	v_min_u32_e32 v9, v73, v9
	v_max_u32_e32 v73, v149, v152
	v_min_u32_e32 v149, v149, v152
	v_max_u32_e32 v152, v153, v3
	v_min_u32_e32 v3, v153, v3
	v_max_u32_e32 v153, v5, v7
	v_min_u32_e32 v5, v5, v7
	v_max_u32_e32 v7, v4, v2
	v_min_u32_e32 v2, v4, v2
	v_max_u32_e32 v4, v1, v0
	v_min_u32_e32 v0, v1, v0
	v_max_u32_e32 v1, v8, v15
	v_min_u32_e32 v8, v8, v15
	v_max_u32_e32 v15, v11, v12
	v_min_u32_e32 v11, v11, v12
	v_max_u32_e32 v12, v6, v17
	v_min_u32_e32 v6, v6, v17
	v_max_u32_e32 v17, v18, v19
	v_min_u32_e32 v18, v18, v19
	v_max_u32_e32 v19, v10, v14
	v_min_u32_e32 v10, v10, v14
	v_max_u32_e32 v14, v20, v16
	v_min_u32_e32 v16, v20, v16
	v_max_u32_e32 v20, v13, v21
	v_min_u32_e32 v13, v13, v21
	v_max_u32_e32 v21, v22, v25
	v_min_u32_e32 v22, v22, v25
	v_max_u32_e32 v25, v23, v37
	v_min_u32_e32 v23, v23, v37
	v_max_u32_e32 v37, v38, v41
	v_min_u32_e32 v38, v38, v41
	v_max_u32_e32 v41, v26, v30
	v_min_u32_e32 v26, v26, v30
	v_max_u32_e32 v30, v36, v32
	v_min_u32_e32 v32, v36, v32
	v_max_u32_e32 v36, v39, v33
	v_min_u32_e32 v33, v39, v33
	v_max_u32_e32 v39, v34, v35
	v_min_u32_e32 v34, v34, v35
	v_max_u32_e32 v35, v24, v31
	v_min_u32_e32 v24, v24, v31
	v_max_u32_e32 v31, v27, v28
	v_min_u32_e32 v27, v27, v28
	v_max_u32_e32 v28, v40, v47
	v_min_u32_e32 v40, v40, v47
	v_max_u32_e32 v47, v43, v44
	v_min_u32_e32 v43, v43, v44
	v_max_u32_e32 v44, v29, v49
	v_min_u32_e32 v29, v29, v49
	v_max_u32_e32 v49, v50, v51
	v_min_u32_e32 v50, v50, v51
	v_max_u32_e32 v51, v42, v46
	v_min_u32_e32 v42, v42, v46
	v_max_u32_e32 v46, v52, v48
	v_min_u32_e32 v48, v52, v48
	v_max_u32_e32 v52, v45, v53
	v_min_u32_e32 v45, v45, v53
	v_max_u32_e32 v53, v54, v57
	v_min_u32_e32 v54, v54, v57
	v_max_u32_e32 v57, v55, v79
	v_min_u32_e32 v55, v55, v79
	v_max_u32_e32 v79, v82, v85
	v_min_u32_e32 v82, v82, v85
	v_max_u32_e32 v85, v58, v62
	v_min_u32_e32 v58, v58, v62
	v_max_u32_e32 v62, v78, v74
	v_min_u32_e32 v74, v78, v74
	v_max_u32_e32 v78, v83, v75
	v_min_u32_e32 v75, v83, v75
	v_max_u32_e32 v83, v76, v77
	v_min_u32_e32 v76, v76, v77
	v_max_u32_e32 v77, v56, v63
	v_min_u32_e32 v56, v56, v63
	v_max_u32_e32 v63, v59, v60
	v_min_u32_e32 v59, v59, v60
	v_max_u32_e32 v60, v84, v91
	v_min_u32_e32 v84, v84, v91
	v_max_u32_e32 v91, v87, v88
	v_min_u32_e32 v87, v87, v88
	v_max_u32_e32 v88, v61, v105
	v_min_u32_e32 v61, v61, v105
	v_max_u32_e32 v105, v106, v107
	v_min_u32_e32 v106, v106, v107
	v_max_u32_e32 v107, v86, v90
	v_min_u32_e32 v86, v86, v90
	v_max_u32_e32 v90, v108, v104
	v_min_u32_e32 v104, v108, v104
	v_max_u32_e32 v108, v89, v109
	v_min_u32_e32 v89, v89, v109
	v_max_u32_e32 v109, v110, v113
	v_min_u32_e32 v110, v110, v113
	v_max_u32_e32 v113, v111, v127
	v_min_u32_e32 v111, v111, v127
	v_max_u32_e32 v127, v128, v131
	v_min_u32_e32 v128, v128, v131
	v_max_u32_e32 v131, v116, v120
	v_min_u32_e32 v116, v116, v120
	v_max_u32_e32 v120, v126, v122
	v_min_u32_e32 v122, v126, v122
	v_max_u32_e32 v126, v129, v123
	v_min_u32_e32 v123, v129, v123
	v_max_u32_e32 v129, v124, v125
	v_min_u32_e32 v124, v124, v125
	v_max_u32_e32 v125, v112, v121
	v_min_u32_e32 v112, v112, v121
	v_max_u32_e32 v121, v117, v118
	v_min_u32_e32 v117, v117, v118
	v_max_u32_e32 v118, v130, v137
	v_min_u32_e32 v130, v130, v137
	v_max_u32_e32 v137, v133, v134
	v_min_u32_e32 v133, v133, v134
	v_max_u32_e32 v134, v119, v139
	v_min_u32_e32 v119, v119, v139
	v_max_u32_e32 v139, v140, v141
	v_min_u32_e32 v140, v140, v141
	v_max_u32_e32 v141, v132, v136
	v_min_u32_e32 v132, v132, v136
	v_max_u32_e32 v136, v142, v138
	v_min_u32_e32 v138, v142, v138
	v_max_u32_e32 v142, v135, v143
	v_min_u32_e32 v135, v135, v143
	v_max_u32_e32 v143, v144, v147
	v_min_u32_e32 v144, v144, v147
	v_min_u32_e32 v147, v145, v151
	v_min_u32_e32 v154, v148, v146
	v_min_u32_e32 v155, v150, v73
	v_min_u32_e32 v156, v9, v149
	v_min_u32_e32 v157, v152, v153
	v_min_u32_e32 v158, v3, v5
	v_min_u32_e32 v159, v7, v4
	v_min_u32_e32 v160, v2, v0
	v_min_u32_e32 v161, v8, v11
	v_min_u32_e32 v162, v1, v15
	v_min_u32_e32 v163, v6, v18
	v_min_u32_e32 v164, v12, v17
	v_min_u32_e32 v165, v10, v16
	v_min_u32_e32 v166, v19, v14
	v_min_u32_e32 v167, v13, v22
	v_min_u32_e32 v168, v20, v21
	v_min_u32_e32 v169, v25, v37
	v_min_u32_e32 v170, v23, v38
	v_min_u32_e32 v171, v41, v30
	v_min_u32_e32 v172, v26, v32
	v_min_u32_e32 v173, v36, v39
	v_min_u32_e32 v174, v33, v34
	v_min_u32_e32 v175, v35, v31
	v_min_u32_e32 v176, v24, v27
	v_min_u32_e32 v177, v40, v43
	v_min_u32_e32 v178, v28, v47
	v_min_u32_e32 v179, v29, v50
	v_min_u32_e32 v180, v44, v49
	v_min_u32_e32 v181, v42, v48
	v_min_u32_e32 v182, v51, v46
	v_min_u32_e32 v183, v45, v54
	v_min_u32_e32 v184, v52, v53
	v_min_u32_e32 v185, v57, v79
	v_min_u32_e32 v186, v55, v82
	v_min_u32_e32 v187, v85, v62
	v_min_u32_e32 v188, v58, v74
	v_min_u32_e32 v189, v78, v83
	v_min_u32_e32 v190, v75, v76
	v_min_u32_e32 v191, v77, v63
	v_min_u32_e32 v192, v56, v59
	v_min_u32_e32 v193, v84, v87
	v_min_u32_e32 v194, v60, v91
	v_min_u32_e32 v195, v61, v106
	v_min_u32_e32 v196, v88, v105
	v_min_u32_e32 v197, v86, v104
	v_min_u32_e32 v198, v107, v90
	v_min_u32_e32 v199, v89, v110
	v_min_u32_e32 v200, v108, v109
	v_min_u32_e32 v201, v113, v127
	v_min_u32_e32 v202, v111, v128
	v_min_u32_e32 v203, v131, v120
	v_min_u32_e32 v204, v116, v122
	v_min_u32_e32 v205, v126, v129
	v_min_u32_e32 v206, v123, v124
	v_min_u32_e32 v207, v125, v121
	v_min_u32_e32 v208, v112, v117
	v_min_u32_e32 v209, v130, v133
	v_min_u32_e32 v210, v118, v137
	v_min_u32_e32 v211, v119, v140
	v_min_u32_e32 v212, v134, v139
	v_min_u32_e32 v213, v132, v138
	v_min_u32_e32 v214, v141, v136
	v_min_u32_e32 v215, v135, v144
	v_min_u32_e32 v216, v142, v143
	v_max3_u32 v145, v145, v151, v161
	v_max3_u32 v8, v147, v8, v11
	v_max3_u32 v11, v148, v146, v162
	v_max3_u32 v1, v154, v1, v15
	v_max3_u32 v15, v150, v73, v163
	v_max3_u32 v6, v155, v6, v18
	v_max3_u32 v9, v9, v149, v164
	v_max3_u32 v12, v156, v12, v17
	v_max3_u32 v17, v152, v153, v165
	v_max3_u32 v10, v157, v10, v16
	v_max3_u32 v3, v3, v5, v166
	v_max3_u32 v5, v158, v19, v14
	v_max3_u32 v4, v7, v4, v167
	v_max3_u32 v7, v159, v13, v22
	v_max3_u32 v0, v2, v0, v168
	v_max3_u32 v2, v160, v20, v21
	v_max3_u32 v13, v25, v37, v177
	v_max3_u32 v14, v169, v40, v43
	v_max3_u32 v16, v23, v38, v178
	v_max3_u32 v18, v170, v28, v47
	v_max3_u32 v19, v41, v30, v179
	v_max3_u32 v20, v171, v29, v50
	v_max3_u32 v21, v26, v32, v180
	v_max3_u32 v22, v172, v44, v49
	v_max3_u32 v23, v36, v39, v181
	v_max3_u32 v25, v173, v42, v48
	v_max3_u32 v26, v33, v34, v182
	v_max3_u32 v28, v174, v51, v46
	v_max3_u32 v29, v35, v31, v183
	v_max3_u32 v30, v175, v45, v54
	v_max3_u32 v24, v24, v27, v184
	v_max3_u32 v27, v176, v52, v53
	v_max3_u32 v31, v57, v79, v193
	v_max3_u32 v32, v185, v84, v87
	v_max3_u32 v33, v55, v82, v194
	v_max3_u32 v34, v186, v60, v91
	v_max3_u32 v35, v85, v62, v195
	v_max3_u32 v36, v187, v61, v106
	v_max3_u32 v37, v58, v74, v196
	v_max3_u32 v38, v188, v88, v105
	v_max3_u32 v39, v78, v83, v197
	v_max3_u32 v40, v189, v86, v104
	v_max3_u32 v41, v75, v76, v198
	v_max3_u32 v42, v190, v107, v90
	v_max3_u32 v43, v77, v63, v199
	v_max3_u32 v44, v191, v89, v110
	v_max3_u32 v45, v56, v59, v200
	v_max3_u32 v46, v192, v108, v109
	v_max3_u32 v47, v113, v127, v209
	v_max3_u32 v48, v201, v130, v133
	v_max3_u32 v49, v111, v128, v210
	v_max3_u32 v50, v202, v118, v137
	v_max3_u32 v51, v131, v120, v211
	v_max3_u32 v52, v203, v119, v140
	v_max3_u32 v53, v116, v122, v212
	v_max3_u32 v54, v204, v134, v139
	v_max3_u32 v55, v126, v129, v213
	v_max3_u32 v56, v205, v132, v138
	v_max3_u32 v57, v123, v124, v214
	v_max3_u32 v58, v206, v141, v136
	v_max3_u32 v59, v125, v121, v215
	v_max3_u32 v60, v207, v135, v144
	v_max3_u32 v61, v112, v117, v216
	v_max3_u32 v62, v208, v142, v143
	v_max_u32_e32 v63, v145, v17
	v_min_u32_e32 v17, v145, v17
	v_max_u32_e32 v73, v8, v10
	v_min_u32_e32 v8, v8, v10
	v_max_u32_e32 v10, v11, v3
	v_min_u32_e32 v3, v11, v3
	v_max_u32_e32 v11, v1, v5
	v_min_u32_e32 v1, v1, v5
	v_max_u32_e32 v5, v15, v4
	v_min_u32_e32 v4, v15, v4
	v_max_u32_e32 v15, v6, v7
	v_min_u32_e32 v6, v6, v7
	v_max_u32_e32 v7, v9, v0
	v_min_u32_e32 v0, v9, v0
	v_max_u32_e32 v9, v12, v2
	v_min_u32_e32 v2, v12, v2
	v_max_u32_e32 v12, v13, v23
	v_min_u32_e32 v13, v13, v23
	v_max_u32_e32 v23, v14, v25
	v_min_u32_e32 v14, v14, v25
	v_max_u32_e32 v25, v16, v26
	v_min_u32_e32 v16, v16, v26
	v_max_u32_e32 v26, v18, v28
	v_min_u32_e32 v18, v18, v28
	v_max_u32_e32 v28, v19, v29
	v_min_u32_e32 v19, v19, v29
	v_max_u32_e32 v29, v20, v30
	v_min_u32_e32 v20, v20, v30
	v_max_u32_e32 v30, v21, v24
	v_min_u32_e32 v21, v21, v24
	v_max_u32_e32 v24, v22, v27
	v_min_u32_e32 v22, v22, v27
	v_max_u32_e32 v27, v31, v39
	v_min_u32_e32 v31, v31, v39
	v_max_u32_e32 v39, v32, v40
	v_min_u32_e32 v32, v32, v40
	v_max_u32_e32 v40, v33, v41
	v_min_u32_e32 v33, v33, v41
	v_max_u32_e32 v41, v34, v42
	v_min_u32_e32 v34, v34, v42
	v_max_u32_e32 v42, v35, v43
	v_min_u32_e32 v35, v35, v43
	v_max_u32_e32 v43, v36, v44
	v_min_u32_e32 v36, v36, v44
	v_max_u32_e32 v44, v37, v45
	v_min_u32_e32 v37, v37, v45
	v_max_u32_e32 v45, v38, v46
	v_min_u32_e32 v38, v38, v46
	v_max_u32_e32 v46, v47, v55
	v_min_u32_e32 v47, v47, v55
	v_max_u32_e32 v55, v48, v56
	v_min_u32_e32 v48, v48, v56
	v_max_u32_e32 v56, v49, v57
	v_min_u32_e32 v49, v49, v57
	v_max_u32_e32 v57, v50, v58
	v_min_u32_e32 v50, v50, v58
	v_max_u32_e32 v58, v51, v59
	v_min_u32_e32 v51, v51, v59
	v_max_u32_e32 v59, v52, v60
	v_min_u32_e32 v52, v52, v60
	v_max_u32_e32 v60, v53, v61
	v_min_u32_e32 v53, v53, v61
	v_max_u32_e32 v61, v54, v62
	v_min_u32_e32 v54, v54, v62
	v_max_u32_e32 v62, v63, v5
	v_min_u32_e32 v5, v63, v5
	v_max_u32_e32 v63, v73, v15
	v_min_u32_e32 v15, v73, v15
	v_max_u32_e32 v73, v10, v7
	v_min_u32_e32 v7, v10, v7
	v_max_u32_e32 v10, v11, v9
	v_min_u32_e32 v9, v11, v9
	v_max_u32_e32 v11, v17, v4
	v_min_u32_e32 v4, v17, v4
	v_max_u32_e32 v17, v8, v6
	v_min_u32_e32 v6, v8, v6
	v_max_u32_e32 v8, v3, v0
	v_min_u32_e32 v0, v3, v0
	v_max_u32_e32 v3, v1, v2
	v_min_u32_e32 v1, v1, v2
	v_max_u32_e32 v2, v13, v19
	v_min_u32_e32 v13, v13, v19
	v_max_u32_e32 v19, v14, v20
	v_min_u32_e32 v14, v14, v20
	v_max_u32_e32 v20, v16, v21
	v_min_u32_e32 v16, v16, v21
	v_max_u32_e32 v21, v18, v22
	v_min_u32_e32 v18, v18, v22
	v_max_u32_e32 v22, v12, v28
	v_min_u32_e32 v12, v12, v28
	v_max_u32_e32 v28, v23, v29
	v_min_u32_e32 v23, v23, v29
	v_max_u32_e32 v29, v25, v30
	v_min_u32_e32 v25, v25, v30
	v_max_u32_e32 v30, v26, v24
	v_min_u32_e32 v24, v26, v24
	v_max_u32_e32 v26, v27, v42
	v_min_u32_e32 v27, v27, v42
	v_max_u32_e32 v42, v39, v43
	v_min_u32_e32 v39, v39, v43
	v_max_u32_e32 v43, v40, v44
	v_min_u32_e32 v40, v40, v44
	v_max_u32_e32 v44, v41, v45
	v_min_u32_e32 v41, v41, v45
	v_max_u32_e32 v45, v31, v35
	v_min_u32_e32 v31, v31, v35
	v_max_u32_e32 v35, v32, v36
	v_min_u32_e32 v32, v32, v36
	v_max_u32_e32 v36, v33, v37
	v_min_u32_e32 v33, v33, v37
	v_max_u32_e32 v37, v34, v38
	v_min_u32_e32 v34, v34, v38
	v_max_u32_e32 v38, v47, v51
	v_min_u32_e32 v47, v47, v51
	v_max_u32_e32 v51, v48, v52
	v_min_u32_e32 v48, v48, v52
	v_max_u32_e32 v52, v49, v53
	v_min_u32_e32 v49, v49, v53
	v_max_u32_e32 v53, v50, v54
	v_min_u32_e32 v50, v50, v54
	v_max_u32_e32 v54, v46, v58
	v_min_u32_e32 v46, v46, v58
	v_max_u32_e32 v58, v55, v59
	v_min_u32_e32 v55, v55, v59
	v_max_u32_e32 v59, v56, v60
	v_min_u32_e32 v56, v56, v60
	v_max_u32_e32 v60, v57, v61
	v_min_u32_e32 v57, v57, v61
	v_max_u32_e32 v61, v62, v73
	v_min_u32_e32 v62, v62, v73
	v_max_u32_e32 v73, v63, v10
	v_min_u32_e32 v10, v63, v10
	v_max_u32_e32 v63, v5, v7
	v_min_u32_e32 v5, v5, v7
	v_max_u32_e32 v7, v15, v9
	v_min_u32_e32 v9, v15, v9
	v_max_u32_e32 v15, v11, v8
	v_min_u32_e32 v8, v11, v8
	v_max_u32_e32 v11, v17, v3
	v_min_u32_e32 v3, v17, v3
	v_max_u32_e32 v17, v4, v0
	v_min_u32_e32 v0, v4, v0
	v_max_u32_e32 v4, v6, v1
	v_min_u32_e32 v1, v6, v1
	v_max_u32_e32 v6, v13, v16
	v_min_u32_e32 v13, v13, v16
	v_max_u32_e32 v16, v14, v18
	v_min_u32_e32 v14, v14, v18
	v_max_u32_e32 v18, v2, v20
	v_min_u32_e32 v2, v2, v20
	v_max_u32_e32 v20, v19, v21
	v_min_u32_e32 v19, v19, v21
	v_max_u32_e32 v21, v12, v25
	v_min_u32_e32 v12, v12, v25
	v_max_u32_e32 v25, v23, v24
	v_min_u32_e32 v23, v23, v24
	v_max_u32_e32 v24, v22, v29
	v_min_u32_e32 v22, v22, v29
	v_max_u32_e32 v29, v28, v30
	v_min_u32_e32 v28, v28, v30
	v_max_u32_e32 v30, v26, v43
	v_min_u32_e32 v26, v26, v43
	v_max_u32_e32 v43, v42, v44
	v_min_u32_e32 v42, v42, v44
	v_max_u32_e32 v44, v27, v40
	v_min_u32_e32 v27, v27, v40
	v_max_u32_e32 v40, v39, v41
	v_min_u32_e32 v39, v39, v41
	v_max_u32_e32 v41, v45, v36
	v_min_u32_e32 v36, v45, v36
	v_max_u32_e32 v45, v35, v37
	v_min_u32_e32 v35, v35, v37
	v_max_u32_e32 v37, v31, v33
	v_min_u32_e32 v31, v31, v33
	v_max_u32_e32 v33, v32, v34
	v_min_u32_e32 v32, v32, v34
	v_max_u32_e32 v34, v47, v49
	v_min_u32_e32 v47, v47, v49
	v_max_u32_e32 v49, v48, v50
	v_min_u32_e32 v48, v48, v50
	v_max_u32_e32 v50, v38, v52
	v_min_u32_e32 v38, v38, v52
	v_max_u32_e32 v52, v51, v53
	v_min_u32_e32 v51, v51, v53
	v_max_u32_e32 v53, v46, v56
	v_min_u32_e32 v46, v46, v56
	v_max_u32_e32 v56, v55, v57
	v_min_u32_e32 v55, v55, v57
	v_max_u32_e32 v57, v54, v59
	v_min_u32_e32 v54, v54, v59
	v_max_u32_e32 v59, v58, v60
	v_min_u32_e32 v58, v58, v60
	v_min_u32_e32 v60, v61, v73
	v_min_u32_e32 v74, v62, v10
	v_min_u32_e32 v75, v63, v7
	v_min_u32_e32 v76, v5, v9
	v_min_u32_e32 v77, v15, v11
	v_min_u32_e32 v78, v8, v3
	v_min_u32_e32 v79, v17, v4
	v_min_u32_e32 v82, v0, v1
	v_min_u32_e32 v83, v13, v14
	v_min_u32_e32 v84, v6, v16
	v_min_u32_e32 v85, v2, v19
	v_min_u32_e32 v86, v18, v20
	v_min_u32_e32 v87, v12, v23
	v_min_u32_e32 v88, v21, v25
	v_min_u32_e32 v89, v22, v28
	v_min_u32_e32 v90, v24, v29
	v_min_u32_e32 v91, v30, v43
	v_min_u32_e32 v104, v26, v42
	v_min_u32_e32 v105, v44, v40
	v_min_u32_e32 v106, v27, v39
	v_min_u32_e32 v107, v41, v45
	v_min_u32_e32 v108, v36, v35
	v_min_u32_e32 v109, v37, v33
	v_min_u32_e32 v110, v31, v32
	v_min_u32_e32 v111, v47, v48
	v_min_u32_e32 v112, v34, v49
	v_min_u32_e32 v113, v38, v51
	v_min_u32_e32 v116, v50, v52
	v_min_u32_e32 v117, v46, v55
	v_min_u32_e32 v118, v53, v56
	v_min_u32_e32 v119, v54, v58
	v_min_u32_e32 v120, v57, v59
	v_max3_u32 v61, v61, v73, v83
	v_max3_u32 v13, v60, v13, v14
	v_max3_u32 v10, v62, v10, v84
	v_max3_u32 v6, v74, v6, v16
	v_max3_u32 v7, v63, v7, v85
	v_max3_u32 v2, v75, v2, v19
	v_max3_u32 v5, v5, v9, v86
	v_max3_u32 v9, v76, v18, v20
	v_max3_u32 v11, v15, v11, v87
	v_max3_u32 v12, v77, v12, v23
	v_max3_u32 v3, v8, v3, v88
	v_max3_u32 v8, v78, v21, v25
	v_max3_u32 v4, v17, v4, v89
	v_max3_u32 v14, v79, v22, v28
	v_max3_u32 v0, v0, v1, v90
	v_max3_u32 v1, v82, v24, v29
	v_max3_u32 v15, v30, v43, v111
	v_max3_u32 v16, v91, v47, v48
	v_max3_u32 v17, v26, v42, v112
	v_max3_u32 v18, v104, v34, v49
	v_max3_u32 v19, v44, v40, v113
	v_max3_u32 v20, v105, v38, v51
	v_max3_u32 v21, v27, v39, v116
	v_max3_u32 v22, v106, v50, v52
	v_max3_u32 v23, v41, v45, v117
	v_max3_u32 v24, v107, v46, v55
	v_max3_u32 v25, v36, v35, v118
	v_max3_u32 v26, v108, v53, v56
	v_max3_u32 v27, v37, v33, v119
	v_max3_u32 v28, v109, v54, v58
	v_max3_u32 v29, v31, v32, v120
	v_max3_u32 v30, v110, v57, v59
	v_max_u32_e32 v31, v61, v11
	v_min_u32_e32 v11, v61, v11
	v_max_u32_e32 v32, v13, v12
	v_min_u32_e32 v12, v13, v12
	v_max_u32_e32 v13, v10, v3
	v_min_u32_e32 v3, v10, v3
	v_max_u32_e32 v10, v6, v8
	v_min_u32_e32 v6, v6, v8
	v_max_u32_e32 v8, v7, v4
	v_min_u32_e32 v4, v7, v4
	v_max_u32_e32 v7, v2, v14
	v_min_u32_e32 v2, v2, v14
	v_max_u32_e32 v14, v5, v0
	v_min_u32_e32 v0, v5, v0
	v_max_u32_e32 v5, v9, v1
	v_min_u32_e32 v1, v9, v1
	v_max_u32_e32 v9, v15, v23
	v_min_u32_e32 v15, v15, v23
	v_max_u32_e32 v23, v16, v24
	v_min_u32_e32 v16, v16, v24
	v_max_u32_e32 v24, v17, v25
	v_min_u32_e32 v17, v17, v25
	v_max_u32_e32 v25, v18, v26
	v_min_u32_e32 v18, v18, v26
	v_max_u32_e32 v26, v19, v27
	v_min_u32_e32 v19, v19, v27
	v_max_u32_e32 v27, v20, v28
	v_min_u32_e32 v20, v20, v28
	v_max_u32_e32 v28, v21, v29
	v_min_u32_e32 v21, v21, v29
	v_max_u32_e32 v29, v22, v30
	v_min_u32_e32 v22, v22, v30
	v_max_u32_e32 v30, v31, v8
	v_min_u32_e32 v8, v31, v8
	v_max_u32_e32 v31, v32, v7
	v_min_u32_e32 v7, v32, v7
	v_max_u32_e32 v32, v13, v14
	v_min_u32_e32 v13, v13, v14
	v_max_u32_e32 v14, v10, v5
	v_min_u32_e32 v5, v10, v5
	v_max_u32_e32 v10, v11, v4
	v_min_u32_e32 v4, v11, v4
	v_max_u32_e32 v11, v12, v2
	v_min_u32_e32 v2, v12, v2
	v_max_u32_e32 v12, v3, v0
	v_min_u32_e32 v0, v3, v0
	v_max_u32_e32 v3, v6, v1
	v_min_u32_e32 v1, v6, v1
	v_max_u32_e32 v6, v15, v19
	v_min_u32_e32 v15, v15, v19
	v_max_u32_e32 v19, v16, v20
	v_min_u32_e32 v16, v16, v20
	v_max_u32_e32 v20, v17, v21
	v_min_u32_e32 v17, v17, v21
	v_max_u32_e32 v21, v18, v22
	v_min_u32_e32 v18, v18, v22
	v_max_u32_e32 v22, v9, v26
	v_min_u32_e32 v9, v9, v26
	v_max_u32_e32 v26, v23, v27
	v_min_u32_e32 v23, v23, v27
	v_max_u32_e32 v27, v24, v28
	v_min_u32_e32 v24, v24, v28
	v_max_u32_e32 v28, v25, v29
	v_min_u32_e32 v25, v25, v29
	v_max_u32_e32 v29, v30, v32
	v_min_u32_e32 v30, v30, v32
	v_max_u32_e32 v32, v31, v14
	v_min_u32_e32 v14, v31, v14
	v_max_u32_e32 v31, v8, v13
	v_min_u32_e32 v8, v8, v13
	v_max_u32_e32 v13, v7, v5
	v_min_u32_e32 v5, v7, v5
	v_max_u32_e32 v7, v10, v12
	v_min_u32_e32 v10, v10, v12
	v_max_u32_e32 v12, v11, v3
	v_min_u32_e32 v3, v11, v3
	v_max_u32_e32 v11, v4, v0
	v_min_u32_e32 v0, v4, v0
	v_max_u32_e32 v4, v2, v1
	v_min_u32_e32 v1, v2, v1
	v_max_u32_e32 v2, v15, v17
	v_min_u32_e32 v15, v15, v17
	v_max_u32_e32 v17, v16, v18
	v_min_u32_e32 v16, v16, v18
	v_max_u32_e32 v18, v6, v20
	v_min_u32_e32 v6, v6, v20
	v_max_u32_e32 v20, v19, v21
	v_min_u32_e32 v19, v19, v21
	v_max_u32_e32 v21, v9, v24
	v_min_u32_e32 v9, v9, v24
	v_max_u32_e32 v24, v23, v25
	v_min_u32_e32 v23, v23, v25
	v_max_u32_e32 v25, v22, v27
	v_min_u32_e32 v22, v22, v27
	v_max_u32_e32 v27, v26, v28
	v_min_u32_e32 v26, v26, v28
	v_min_u32_e32 v28, v29, v32
	v_min_u32_e32 v33, v30, v14
	v_min_u32_e32 v34, v31, v13
	v_min_u32_e32 v35, v8, v5
	v_min_u32_e32 v36, v7, v12
	v_min_u32_e32 v37, v10, v3
	v_min_u32_e32 v38, v11, v4
	v_min_u32_e32 v39, v0, v1
	v_min_u32_e32 v40, v15, v16
	v_min_u32_e32 v41, v2, v17
	v_min_u32_e32 v42, v6, v19
	v_min_u32_e32 v43, v18, v20
	v_min_u32_e32 v44, v9, v23
	v_min_u32_e32 v45, v21, v24
	v_min_u32_e32 v46, v22, v26
	v_min_u32_e32 v47, v25, v27
	v_max3_u32 v29, v29, v32, v40
	v_max3_u32 v15, v28, v15, v16
	v_max3_u32 v14, v30, v14, v41
	v_max3_u32 v2, v33, v2, v17
	v_max3_u32 v13, v31, v13, v42
	v_max3_u32 v6, v34, v6, v19
	v_max3_u32 v5, v8, v5, v43
	v_max3_u32 v8, v35, v18, v20
	v_max3_u32 v7, v7, v12, v44
	v_max3_u32 v9, v36, v9, v23
	v_max3_u32 v3, v10, v3, v45
	v_max3_u32 v10, v37, v21, v24
	v_max3_u32 v4, v11, v4, v46
	v_max3_u32 v11, v38, v22, v26
	v_max3_u32 v0, v0, v1, v47
	v_max3_u32 v1, v39, v25, v27
	v_readlane_b32 s22, v249, 30
	v_max_u32_e32 v12, v29, v7
	v_min_u32_e32 v7, v29, v7
	v_max_u32_e32 v16, v15, v9
	v_min_u32_e32 v9, v15, v9
	v_max_u32_e32 v15, v14, v3
	v_min_u32_e32 v3, v14, v3
	v_max_u32_e32 v14, v2, v10
	v_min_u32_e32 v2, v2, v10
	v_max_u32_e32 v10, v13, v4
	v_min_u32_e32 v4, v13, v4
	v_max_u32_e32 v13, v6, v11
	v_min_u32_e32 v6, v6, v11
	v_max_u32_e32 v11, v5, v0
	v_min_u32_e32 v0, v5, v0
	v_max_u32_e32 v5, v8, v1
	v_min_u32_e32 v1, v8, v1
	v_readlane_b32 s23, v249, 31
	v_max_u32_e32 v8, v12, v10
	v_min_u32_e32 v10, v12, v10
	v_max_u32_e32 v12, v16, v13
	v_min_u32_e32 v13, v16, v13
	v_max_u32_e32 v16, v15, v11
	v_min_u32_e32 v11, v15, v11
	v_max_u32_e32 v15, v14, v5
	v_min_u32_e32 v5, v14, v5
	v_max_u32_e32 v14, v7, v4
	v_min_u32_e32 v4, v7, v4
	v_max_u32_e32 v7, v9, v6
	v_min_u32_e32 v6, v9, v6
	v_max_u32_e32 v9, v3, v0
	v_min_u32_e32 v0, v3, v0
	v_max_u32_e32 v3, v2, v1
	v_min_u32_e32 v1, v2, v1
	s_load_dwordx2 s[22:23], s[22:23], 0x180
	v_max_u32_e32 v2, v8, v16
	v_min_u32_e32 v8, v8, v16
	v_max_u32_e32 v16, v12, v15
	v_min_u32_e32 v12, v12, v15
	v_max_u32_e32 v15, v10, v11
	v_min_u32_e32 v10, v10, v11
	v_max_u32_e32 v11, v13, v5
	v_min_u32_e32 v5, v13, v5
	v_max_u32_e32 v13, v14, v9
	v_min_u32_e32 v9, v14, v9
	v_max_u32_e32 v14, v7, v3
	v_min_u32_e32 v3, v7, v3
	v_max_u32_e32 v7, v4, v0
	v_min_u32_e32 v0, v4, v0
	v_max_u32_e32 v4, v6, v1
	v_min_u32_e32 v1, v6, v1
	v_max_u32_e32 v19, v0, v1
	v_min_u32_e32 v20, v0, v1
	v_lshl_add_u32 v0, s16, 7, v81
	v_ashrrev_i32_e32 v1, 31, v0
	v_readlane_b32 s16, v249, 19
	v_lshlrev_b64 v[0:1], 10, v[0:1]
	v_readlane_b32 s17, v249, 20
	v_max_u32_e32 v6, v2, v16
	v_min_u32_e32 v2, v2, v16
	v_max_u32_e32 v16, v8, v12
	v_min_u32_e32 v8, v8, v12
	s_waitcnt lgkmcnt(0)
	v_lshl_add_u64 v[0:1], s[22:23], 0, v[0:1]
	s_mov_b32 s21, s17
	s_lshl_b32 s20, s20, 6
	v_max_u32_e32 v12, v15, v11
	v_min_u32_e32 v11, v15, v11
	v_max_u32_e32 v15, v10, v5
	v_min_u32_e32 v10, v10, v5
	v_max_u32_e32 v17, v13, v14
	v_min_u32_e32 v13, v13, v14
	v_max_u32_e32 v14, v9, v3
	v_min_u32_e32 v9, v9, v3
	v_max_u32_e32 v18, v7, v4
	v_min_u32_e32 v7, v7, v4
	v_lshl_add_u64 v[4:5], v[0:1], 0, s[20:21]
	v_xor_b32_e32 v0, 0x7f, v6
	v_xor_b32_e32 v1, 0x7f, v2
	v_xor_b32_e32 v2, 0x7f, v16
	v_xor_b32_e32 v3, 0x7f, v8
	global_store_dwordx4 v[4:5], v[0:3], off
	v_writelane_b32 v249, s16, 19
	s_nop 0
	v_xor_b32_e32 v0, 0x7f, v12
	v_xor_b32_e32 v1, 0x7f, v11
	v_xor_b32_e32 v2, 0x7f, v15
	v_xor_b32_e32 v3, 0x7f, v10
	global_store_dwordx4 v[4:5], v[0:3], off offset:16
	v_writelane_b32 v249, s17, 20
	s_nop 0
	v_xor_b32_e32 v0, 0x7f, v17
	v_xor_b32_e32 v1, 0x7f, v13
	v_xor_b32_e32 v2, 0x7f, v14
	v_xor_b32_e32 v3, 0x7f, v9
	global_store_dwordx4 v[4:5], v[0:3], off offset:32
	s_nop 1
	v_xor_b32_e32 v0, 0x7f, v18
	v_xor_b32_e32 v1, 0x7f, v7
	v_xor_b32_e32 v2, 0x7f, v19
	v_xor_b32_e32 v3, 0x7f, v20
	global_store_dwordx4 v[4:5], v[0:3], off offset:48
	s_branch .LBB0_19

.LBB0_328:
	v_ashrrev_i32_e32 v117, 31, v116
	v_lshlrev_b64 v[0:1], 11, v[116:117]
	v_lshl_add_u64 v[134:135], v[122:123], 0, v[0:1]
	global_load_dwordx4 v[12:15], v[134:135], off
	global_load_dwordx4 v[0:3], v[134:135], off offset:16
	v_readlane_b32 s2, v249, 30
	v_readlane_b32 s3, v249, 31
	s_load_dwordx2 s[2:3], s[2:3], 0x180
	v_lshlrev_b64 v[136:137], 10, v[116:117]
	v_mov_b32_e32 v131, v80
	v_mov_b32_e32 v133, v80
	s_movk_i32 s43, 0x80
	s_waitcnt lgkmcnt(0)
	v_lshl_add_u64 v[4:5], s[2:3], 0, v[136:137]
	v_lshl_add_u64 v[18:19], v[4:5], 0, v[130:131]
	v_lshl_add_u64 v[16:17], v[4:5], 0, v[132:133]
	global_load_dword v26, v[16:17], off offset:64
	global_load_dword v28, v[18:19], off
	global_load_dword v25, v[16:17], off offset:192
	global_load_dword v27, v[18:19], off offset:128
	global_load_dwordx4 v[4:7], v[134:135], off offset:48
	global_load_dwordx4 v[8:11], v[134:135], off offset:32
	global_load_dword v21, v[18:19], off offset:256
	global_load_dword v23, v[18:19], off offset:384
	global_load_dword v22, v[18:19], off offset:512
	global_load_dword v24, v[18:19], off offset:640
	global_load_dword v20, v[18:19], off offset:768
	s_nop 0
	global_load_dword v18, v[18:19], off offset:896
	s_nop 0
	global_load_dword v117, v[16:17], off offset:320
	global_load_dword v31, v[16:17], off offset:448
	global_load_dword v30, v[16:17], off offset:576
	global_load_dword v29, v[16:17], off offset:704
	global_load_dword v19, v[16:17], off offset:832
	s_nop 0
	global_load_dword v16, v[16:17], off offset:960
	s_movk_i32 s44, 0x3f80
	v_mov_b32_e32 v176, 0
	v_mov_b32_e32 v177, v176
	v_mov_b32_e32 v216, v176
	v_mov_b32_e32 v217, v176
	v_mov_b32_e32 v214, v176
	v_mov_b32_e32 v215, v176
	v_mov_b32_e32 v212, v176
	v_mov_b32_e32 v213, v176
	v_mov_b32_e32 v210, v176
	v_mov_b32_e32 v211, v176
	v_mov_b32_e32 v208, v176
	v_mov_b32_e32 v209, v176
	v_mov_b32_e32 v206, v176
	v_mov_b32_e32 v207, v176
	v_mov_b32_e32 v204, v176
	v_mov_b32_e32 v205, v176
	v_mov_b32_e32 v202, v176
	v_mov_b32_e32 v203, v176
	v_mov_b32_e32 v200, v176
	v_mov_b32_e32 v201, v176
	v_mov_b32_e32 v198, v176
	v_mov_b32_e32 v199, v176
	v_mov_b32_e32 v196, v176
	v_mov_b32_e32 v197, v176
	v_mov_b32_e32 v194, v176
	v_mov_b32_e32 v195, v176
	v_mov_b32_e32 v192, v176
	v_mov_b32_e32 v193, v176
	v_mov_b32_e32 v190, v176
	v_mov_b32_e32 v191, v176
	v_mov_b32_e32 v188, v176
	v_mov_b32_e32 v189, v176
	s_waitcnt vmcnt(17)
	v_cmp_lt_i32_e32 vcc, -1, v26
	s_waitcnt vmcnt(13)
	v_lshlrev_b32_e32 v160, 16, v4
	v_lshlrev_b32_e32 v152, 16, v12
	v_lshlrev_b32_e32 v174, 16, v1
	v_and_b32_e32 v143, 0xffff0000, v1
	v_cndmask_b32_e64 v1, v232, -1, vcc
	v_cmp_lt_i32_e32 vcc, -1, v28
	v_and_b32_e32 v150, 0xffff0000, v12
	v_lshlrev_b32_e32 v148, 16, v14
	v_cndmask_b32_e64 v12, v232, -1, vcc
	v_cmp_lt_i32_e32 vcc, -1, v25
	v_and_b32_e32 v146, 0xffff0000, v14
	v_lshlrev_b32_e32 v172, 16, v15
	v_cndmask_b32_e64 v17, v232, -1, vcc
	v_cmp_lt_i32_e32 vcc, -1, v27
	v_and_b32_e32 v147, 0xffff0000, v15
	v_lshlrev_b32_e32 v144, 16, v0
	v_and_b32_e32 v142, 0xffff0000, v0
	v_lshlrev_b32_e32 v140, 16, v2
	v_and_b32_e32 v138, 0xffff0000, v2
	v_and_b32_e32 v0, 0xffffff80, v26
	v_and_b32_e32 v2, 0xffffff80, v28
	v_and_b32_e32 v14, 0xffffff80, v25
	v_and_b32_e32 v15, 0xffffff80, v27
	v_cndmask_b32_e64 v32, v232, -1, vcc
	v_lshlrev_b32_e32 v170, 16, v13
	v_and_b32_e32 v151, 0xffff0000, v13
	v_xor_b32_e32 v1, v1, v0
	v_xor_b32_e32 v13, v12, v2
	v_xor_b32_e32 v0, v17, v14
	v_xor_b32_e32 v12, v32, v15
	v_pk_add_f32 v[0:1], v[12:13], v[0:1]
	v_lshlrev_b32_e32 v178, 16, v3
	v_or_b32_e32 v2, 0x80000000, v1
	v_not_b32_e32 v12, v1
	v_cmp_gt_i32_e32 vcc, 0, v1
	v_and_b32_e32 v139, 0xffff0000, v3
	s_waitcnt vmcnt(12)
	v_lshlrev_b32_e32 v168, 16, v8
	v_cndmask_b32_e32 v2, v2, v12, vcc
	v_and_b32_e32 v2, 0xffffffc0, v2
	v_bitop3_b32 v2, v2, 63, v81 bitop3:0x36
	v_cndmask_b32_e64 v2, 0, v2, s[10:11]
	v_and_b32_e32 v166, 0xffff0000, v8
	v_readlane_b32 s3, v2, 1
	v_readlane_b32 s24, v2, 2
	v_readlane_b32 s26, v2, 4
	v_cmp_gt_u32_e32 vcc, s3, v2
	v_readlane_b32 s30, v2, 6
	v_readlane_b32 s34, v2, 8
	v_cndmask_b32_e64 v12, 0, 1, vcc
	v_cmp_gt_u32_e32 vcc, s24, v2
	v_readlane_b32 s2, v2, 0
	v_readlane_b32 s25, v2, 3
	v_cndmask_b32_e64 v13, 0, 1, vcc
	v_cmp_gt_u32_e32 vcc, s26, v2
	v_readlane_b32 s27, v2, 5
	v_readlane_b32 s31, v2, 7
	v_cndmask_b32_e64 v14, 0, 1, vcc
	v_cmp_gt_u32_e32 vcc, s30, v2
	v_and_b32_e32 v158, 0xffff0000, v4
	v_lshlrev_b32_e32 v184, 16, v5
	v_cndmask_b32_e64 v15, 0, 1, vcc
	v_cmp_gt_u32_e32 vcc, s34, v2
	v_and_b32_e32 v159, 0xffff0000, v5
	v_lshlrev_b32_e32 v156, 16, v6
	v_cndmask_b32_e64 v17, 0, 1, vcc
	v_cmp_gt_u32_e32 vcc, s2, v2
	v_readlane_b32 s2, v2, 9
	v_and_b32_e32 v154, 0xffff0000, v6
	v_addc_co_u32_e32 v12, vcc, 0, v12, vcc
	v_cmp_gt_u32_e32 vcc, s25, v2
	v_lshlrev_b32_e32 v5, 7, v28
	v_and_b32_e32 v6, 0x7f, v26
	v_addc_co_u32_e32 v12, vcc, v12, v13, vcc
	v_cmp_gt_u32_e32 vcc, s27, v2
	v_and_or_b32 v5, v5, s44, v6
	v_lshlrev_b32_e32 v186, 16, v7
	v_addc_co_u32_e32 v12, vcc, v12, v14, vcc
	v_cmp_gt_u32_e32 vcc, s31, v2
	v_and_b32_e32 v155, 0xffff0000, v7
	v_lshlrev_b32_e32 v164, 16, v10
	v_addc_co_u32_e32 v12, vcc, v12, v15, vcc
	v_cmp_gt_u32_e32 vcc, s2, v2
	v_readlane_b32 s2, v2, 10
	v_and_b32_e32 v162, 0xffff0000, v10
	v_addc_co_u32_e32 v12, vcc, v12, v17, vcc
	v_cmp_gt_u32_e32 vcc, s2, v2
	v_readlane_b32 s2, v2, 11
	v_lshlrev_b32_e32 v182, 16, v11
	v_cndmask_b32_e64 v13, 0, 1, vcc
	v_cmp_gt_u32_e32 vcc, s2, v2
	v_readlane_b32 s2, v2, 12
	v_and_b32_e32 v163, 0xffff0000, v11
	v_addc_co_u32_e32 v12, vcc, v12, v13, vcc
	v_cmp_gt_u32_e32 vcc, s2, v2
	v_readlane_b32 s2, v2, 13
	v_not_b32_e32 v17, v0
	v_cndmask_b32_e64 v13, 0, 1, vcc
	v_cmp_gt_u32_e32 vcc, s2, v2
	v_readlane_b32 s2, v2, 14
	v_lshlrev_b32_e32 v180, 16, v9
	v_addc_co_u32_e32 v12, vcc, v12, v13, vcc
	v_cmp_gt_u32_e32 vcc, s2, v2
	v_readlane_b32 s2, v2, 15
	v_and_b32_e32 v167, 0xffff0000, v9
	v_cndmask_b32_e64 v13, 0, 1, vcc
	v_cmp_gt_u32_e32 vcc, s2, v2
	v_readlane_b32 s2, v2, 16
	v_and_b32_e32 v9, 0x7f, v25
	v_addc_co_u32_e32 v12, vcc, v12, v13, vcc
	v_cmp_gt_u32_e32 vcc, s2, v2
	v_readlane_b32 s2, v2, 17
	s_mov_b32 s24, 0
	v_cndmask_b32_e64 v13, 0, 1, vcc
	v_cmp_gt_u32_e32 vcc, s2, v2
	v_readlane_b32 s2, v2, 18
	v_mov_b32_e32 v153, v150
	v_addc_co_u32_e32 v12, vcc, v12, v13, vcc
	v_cmp_gt_u32_e32 vcc, s2, v2
	v_readlane_b32 s2, v2, 19
	v_mov_b32_e32 v171, v151
	v_cndmask_b32_e64 v13, 0, 1, vcc
	v_cmp_gt_u32_e32 vcc, s2, v2
	v_readlane_b32 s2, v2, 20
	v_mov_b32_e32 v149, v146
	v_addc_co_u32_e32 v12, vcc, v12, v13, vcc
	v_cmp_gt_u32_e32 vcc, s2, v2
	v_readlane_b32 s2, v2, 21
	v_mov_b32_e32 v173, v147
	v_cndmask_b32_e64 v13, 0, 1, vcc
	v_cmp_gt_u32_e32 vcc, s2, v2
	v_readlane_b32 s2, v2, 22
	v_mov_b32_e32 v145, v142
	v_addc_co_u32_e32 v12, vcc, v12, v13, vcc
	v_cmp_gt_u32_e32 vcc, s2, v2
	v_readlane_b32 s2, v2, 23
	v_mov_b32_e32 v175, v143
	v_cndmask_b32_e64 v13, 0, 1, vcc
	v_cmp_gt_u32_e32 vcc, s2, v2
	v_readlane_b32 s2, v2, 24
	v_mov_b32_e32 v141, v138
	v_addc_co_u32_e32 v12, vcc, v12, v13, vcc
	v_cmp_gt_u32_e32 vcc, s2, v2
	v_readlane_b32 s2, v2, 25
	v_mov_b32_e32 v179, v139
	v_cndmask_b32_e64 v13, 0, 1, vcc
	v_cmp_gt_u32_e32 vcc, s2, v2
	v_readlane_b32 s2, v2, 26
	v_mov_b32_e32 v169, v166
	v_addc_co_u32_e32 v12, vcc, v12, v13, vcc
	v_cmp_gt_u32_e32 vcc, s2, v2
	v_readlane_b32 s2, v2, 27
	v_mov_b32_e32 v181, v167
	v_cndmask_b32_e64 v13, 0, 1, vcc
	v_cmp_gt_u32_e32 vcc, s2, v2
	v_readlane_b32 s2, v2, 28
	v_mov_b32_e32 v165, v162
	v_addc_co_u32_e32 v12, vcc, v12, v13, vcc
	v_cmp_gt_u32_e32 vcc, s2, v2
	v_readlane_b32 s2, v2, 29
	v_mov_b32_e32 v183, v163
	v_cndmask_b32_e64 v13, 0, 1, vcc
	v_cmp_gt_u32_e32 vcc, s2, v2
	v_readlane_b32 s2, v2, 30
	v_mov_b32_e32 v161, v158
	v_addc_co_u32_e32 v12, vcc, v12, v13, vcc
	v_cmp_gt_u32_e32 vcc, s2, v2
	v_readlane_b32 s2, v2, 31
	v_mov_b32_e32 v185, v159
	v_cndmask_b32_e64 v13, 0, 1, vcc
	v_cmp_gt_u32_e32 vcc, s2, v2
	v_readlane_b32 s2, v2, 32
	v_mov_b32_e32 v157, v154
	v_addc_co_u32_e32 v12, vcc, v12, v13, vcc
	v_cmp_gt_u32_e32 vcc, s2, v2
	v_readlane_b32 s2, v2, 33
	v_mov_b32_e32 v187, v155
	v_cndmask_b32_e64 v13, 0, 1, vcc
	v_cmp_gt_u32_e32 vcc, s2, v2
	v_readlane_b32 s2, v2, 34
	s_nop 0
	v_addc_co_u32_e32 v12, vcc, v12, v13, vcc
	v_cmp_gt_u32_e32 vcc, s2, v2
	v_readlane_b32 s2, v2, 35
	s_nop 0
	v_cndmask_b32_e64 v13, 0, 1, vcc
	v_cmp_gt_u32_e32 vcc, s2, v2
	v_readlane_b32 s2, v2, 36
	s_nop 0
	v_addc_co_u32_e32 v12, vcc, v12, v13, vcc
	v_cmp_gt_u32_e32 vcc, s2, v2
	v_readlane_b32 s2, v2, 37
	s_nop 0
	v_cndmask_b32_e64 v13, 0, 1, vcc
	v_cmp_gt_u32_e32 vcc, s2, v2
	v_readlane_b32 s2, v2, 38
	s_nop 0
	v_addc_co_u32_e32 v12, vcc, v12, v13, vcc
	v_cmp_gt_u32_e32 vcc, s2, v2
	v_readlane_b32 s2, v2, 39
	s_nop 0
	v_cndmask_b32_e64 v13, 0, 1, vcc
	v_cmp_gt_u32_e32 vcc, s2, v2
	v_readlane_b32 s2, v2, 40
	s_nop 0
	v_addc_co_u32_e32 v12, vcc, v12, v13, vcc
	v_cmp_gt_u32_e32 vcc, s2, v2
	v_readlane_b32 s2, v2, 41
	s_nop 0
	v_cndmask_b32_e64 v13, 0, 1, vcc
	v_cmp_gt_u32_e32 vcc, s2, v2
	v_readlane_b32 s2, v2, 42
	s_nop 0
	v_addc_co_u32_e32 v12, vcc, v12, v13, vcc
	v_cmp_gt_u32_e32 vcc, s2, v2
	v_readlane_b32 s2, v2, 43
	s_nop 0
	v_cndmask_b32_e64 v13, 0, 1, vcc
	v_cmp_gt_u32_e32 vcc, s2, v2
	v_readlane_b32 s2, v2, 44
	s_nop 0
	v_addc_co_u32_e32 v12, vcc, v12, v13, vcc
	v_cmp_gt_u32_e32 vcc, s2, v2
	v_readlane_b32 s2, v2, 45
	s_nop 0
	v_cndmask_b32_e64 v13, 0, 1, vcc
	v_cmp_gt_u32_e32 vcc, s2, v2
	v_readlane_b32 s2, v2, 46
	s_nop 0
	v_addc_co_u32_e32 v12, vcc, v12, v13, vcc
	v_cmp_gt_u32_e32 vcc, s2, v2
	v_readlane_b32 s2, v2, 47
	s_nop 0
	v_cndmask_b32_e64 v13, 0, 1, vcc
	v_cmp_gt_u32_e32 vcc, s2, v2
	v_readlane_b32 s2, v2, 48
	s_nop 0
	v_addc_co_u32_e32 v12, vcc, v12, v13, vcc
	v_cmp_gt_u32_e32 vcc, s2, v2
	v_readlane_b32 s2, v2, 49
	s_nop 0
	v_cndmask_b32_e64 v13, 0, 1, vcc
	v_cmp_gt_u32_e32 vcc, s2, v2
	s_nop 1
	v_addc_co_u32_e32 v2, vcc, v12, v13, vcc
	v_lshlrev_b32_e32 v13, 3, v2
	v_lshlrev_b32_e32 v12, 7, v2
	v_and_b32_e32 v13, 0x70, v13
	v_and_or_b32 v12, v12, s43, v13
	v_cmp_gt_u32_e32 vcc, 16, v2
	s_nop 1
	v_cndmask_b32_e32 v2, 4, v12, vcc
	ds_permute_b32 v1, v2, v1
	ds_permute_b32 v2, v2, v5
	s_waitcnt lgkmcnt(1)
	v_readlane_b32 s2, v1, 0
	s_nop 1
	v_subrev_f32_e32 v1, s2, v1
	v_mul_f32_e32 v1, 0x3fb8aa3b, v1
	v_exp_f32_e32 v1, v1
	s_waitcnt lgkmcnt(0)
	v_readlane_b32 s25, v2, 4
	v_readlane_b32 s26, v2, 36
	v_readlane_b32 s27, v2, 8
	v_cndmask_b32_e64 v1, 0, v1, s[12:13]
	ds_bpermute_b32 v3, v240, v1
	v_readlane_b32 s30, v2, 40
	v_readlane_b32 s31, v2, 12
	v_readlane_b32 s34, v2, 44
	v_readlane_b32 s35, v2, 16
	s_waitcnt lgkmcnt(0)
	v_add_f32_e32 v3, v1, v3
	ds_bpermute_b32 v8, v241, v3
	v_readlane_b32 s36, v2, 48
	v_readlane_b32 s37, v2, 20
	v_readlane_b32 s38, v2, 52
	v_readlane_b32 s39, v2, 24
	s_waitcnt lgkmcnt(0)
	v_add_f32_e32 v3, v3, v8
	ds_bpermute_b32 v4, v242, v3
	v_readlane_b32 s40, v2, 56
	v_readlane_b32 s41, v2, 28
	v_readlane_b32 s42, v2, 60
	v_lshlrev_b32_e32 v8, 7, v27
	s_waitcnt lgkmcnt(0)
	v_add_f32_e32 v3, v3, v4
	ds_bpermute_b32 v4, v243, v3
	v_and_or_b32 v8, v8, s44, v9
	s_waitcnt lgkmcnt(0)
	v_add_f32_e32 v3, v3, v4
	v_div_scale_f32 v4, s[2:3], v3, v3, v1
	v_rcp_f32_e32 v6, v4
	v_readlane_b32 s2, v2, 0
	v_readlane_b32 s3, v2, 32
	v_fma_f32 v5, -v4, v6, 1.0
	v_fmac_f32_e32 v6, v5, v6
	v_div_scale_f32 v5, vcc, v1, v3, v1
	v_mul_f32_e32 v7, v5, v6
	v_fma_f32 v10, -v4, v7, v5
	v_fmac_f32_e32 v7, v10, v6
	v_fma_f32 v4, -v4, v7, v5
	v_div_fmas_f32 v4, v4, v6, v7
	v_div_fixup_f32 v3, v4, v3, v1
	v_mov_b32_e32 v1, s2
	v_mov_b32_e32 v4, s3
	v_cndmask_b32_e64 v1, v1, v4, s[6:7]
	v_mad_i64_i32 v[4:5], s[2:3], v1, s28, v[118:119]
	global_load_dwordx2 v[36:37], v[4:5], off offset:16
	global_load_dwordx4 v[32:35], v[4:5], off
	v_mov_b32_e32 v4, s25
	v_mov_b32_e32 v5, s26
	v_cndmask_b32_e64 v6, v4, v5, s[6:7]
	v_mad_i64_i32 v[4:5], s[2:3], v6, s28, v[118:119]
	global_load_dwordx2 v[42:43], v[4:5], off offset:16
	global_load_dwordx4 v[38:41], v[4:5], off
	v_mov_b32_e32 v4, s27
	v_mov_b32_e32 v5, s30
	v_cndmask_b32_e64 v10, v4, v5, s[6:7]
	v_mad_i64_i32 v[4:5], s[2:3], v10, s28, v[118:119]
	global_load_dwordx2 v[48:49], v[4:5], off offset:16
	global_load_dwordx4 v[44:47], v[4:5], off
	v_mov_b32_e32 v4, s31
	v_mov_b32_e32 v5, s34
	v_cndmask_b32_e64 v11, v4, v5, s[6:7]
	v_mad_i64_i32 v[4:5], s[2:3], v11, s28, v[118:119]
	global_load_dwordx2 v[54:55], v[4:5], off offset:16
	global_load_dwordx4 v[50:53], v[4:5], off
	v_mov_b32_e32 v4, s35
	v_mov_b32_e32 v5, s36
	v_cndmask_b32_e64 v12, v4, v5, s[6:7]
	v_mad_i64_i32 v[4:5], s[2:3], v12, s28, v[118:119]
	global_load_dwordx2 v[60:61], v[4:5], off offset:16
	global_load_dwordx4 v[56:59], v[4:5], off
	v_mov_b32_e32 v4, s37
	v_mov_b32_e32 v5, s38
	v_cndmask_b32_e64 v13, v4, v5, s[6:7]
	v_mad_i64_i32 v[4:5], s[2:3], v13, s28, v[118:119]
	global_load_dwordx2 v[66:67], v[4:5], off offset:16
	global_load_dwordx4 v[62:65], v[4:5], off
	v_mov_b32_e32 v4, s39
	v_mov_b32_e32 v5, s40
	v_cndmask_b32_e64 v14, v4, v5, s[6:7]
	v_mad_i64_i32 v[4:5], s[2:3], v14, s28, v[118:119]
	global_load_dwordx2 v[72:73], v[4:5], off offset:16
	global_load_dwordx4 v[68:71], v[4:5], off
	v_mov_b32_e32 v4, s41
	v_mov_b32_e32 v5, s42
	v_cndmask_b32_e64 v15, v4, v5, s[6:7]
	v_mad_i64_i32 v[4:5], s[2:3], v15, s28, v[118:119]
	global_load_dwordx2 v[78:79], v[4:5], off offset:16
	global_load_dwordx4 v[74:77], v[4:5], off
	v_mad_i64_i32 v[4:5], s[2:3], v1, s28, v[120:121]
	v_or_b32_e32 v1, 0x80000000, v0
	v_cmp_gt_i32_e32 vcc, 0, v0
	v_mad_i64_i32 v[6:7], s[2:3], v6, s28, v[120:121]
	s_nop 0
	v_cndmask_b32_e32 v1, v1, v17, vcc
	v_and_b32_e32 v1, 0xffffffc0, v1
	v_bitop3_b32 v1, v1, 63, v81 bitop3:0x36
	v_cndmask_b32_e64 v1, 0, v1, s[10:11]
	global_load_dwordx4 v[110:113], v[4:5], off offset:768
	global_load_dwordx4 v[106:109], v[6:7], off offset:768
	v_readlane_b32 s2, v1, 0
	v_readlane_b32 s50, v1, 1
	v_mov_b32_e32 v17, 0
	v_cmp_gt_u32_e32 vcc, s2, v1
	v_readlane_b32 s2, v1, 2
	v_cmp_gt_u32_e64 s[48:49], s50, v1
	v_readlane_b32 s50, v1, 3
	v_addc_co_u32_e32 v17, vcc, 0, v17, vcc
	v_cmp_gt_u32_e32 vcc, s2, v1
	v_readlane_b32 s2, v1, 4
	v_addc_co_u32_e64 v17, s[48:49], 0, v17, s[48:49]
	v_cmp_gt_u32_e64 s[48:49], s50, v1
	v_readlane_b32 s50, v1, 5
	v_addc_co_u32_e32 v17, vcc, 0, v17, vcc
	v_cmp_gt_u32_e32 vcc, s2, v1
	v_readlane_b32 s2, v1, 6
	v_addc_co_u32_e64 v17, s[48:49], 0, v17, s[48:49]
	v_cmp_gt_u32_e64 s[48:49], s50, v1
	v_readlane_b32 s50, v1, 7
	v_addc_co_u32_e32 v17, vcc, 0, v17, vcc
	v_cmp_gt_u32_e32 vcc, s2, v1
	v_readlane_b32 s2, v1, 8
	v_addc_co_u32_e64 v17, s[48:49], 0, v17, s[48:49]
	v_cmp_gt_u32_e64 s[48:49], s50, v1
	v_readlane_b32 s50, v1, 9
	v_addc_co_u32_e32 v17, vcc, 0, v17, vcc
	v_cmp_gt_u32_e32 vcc, s2, v1
	v_readlane_b32 s2, v1, 10
	v_addc_co_u32_e64 v17, s[48:49], 0, v17, s[48:49]
	v_cmp_gt_u32_e64 s[48:49], s50, v1
	v_readlane_b32 s50, v1, 11
	v_addc_co_u32_e32 v17, vcc, 0, v17, vcc
	v_cmp_gt_u32_e32 vcc, s2, v1
	v_readlane_b32 s2, v1, 12
	v_addc_co_u32_e64 v17, s[48:49], 0, v17, s[48:49]
	v_cmp_gt_u32_e64 s[48:49], s50, v1
	v_readlane_b32 s50, v1, 13
	v_addc_co_u32_e32 v17, vcc, 0, v17, vcc
	v_cmp_gt_u32_e32 vcc, s2, v1
	v_readlane_b32 s2, v1, 14
	v_addc_co_u32_e64 v17, s[48:49], 0, v17, s[48:49]
	v_cmp_gt_u32_e64 s[48:49], s50, v1
	v_readlane_b32 s50, v1, 15
	v_addc_co_u32_e32 v17, vcc, 0, v17, vcc
	v_cmp_gt_u32_e32 vcc, s2, v1
	v_readlane_b32 s2, v1, 16
	v_addc_co_u32_e64 v17, s[48:49], 0, v17, s[48:49]
	v_cmp_gt_u32_e64 s[48:49], s50, v1
	v_readlane_b32 s50, v1, 17
	v_addc_co_u32_e32 v17, vcc, 0, v17, vcc
	v_cmp_gt_u32_e32 vcc, s2, v1
	v_readlane_b32 s2, v1, 18
	v_addc_co_u32_e64 v17, s[48:49], 0, v17, s[48:49]
	v_cmp_gt_u32_e64 s[48:49], s50, v1
	v_readlane_b32 s50, v1, 19
	v_addc_co_u32_e32 v17, vcc, 0, v17, vcc
	v_cmp_gt_u32_e32 vcc, s2, v1
	v_readlane_b32 s2, v1, 20
	v_addc_co_u32_e64 v17, s[48:49], 0, v17, s[48:49]
	v_cmp_gt_u32_e64 s[48:49], s50, v1
	v_readlane_b32 s50, v1, 21
	v_addc_co_u32_e32 v17, vcc, 0, v17, vcc
	v_cmp_gt_u32_e32 vcc, s2, v1
	v_readlane_b32 s2, v1, 22
	v_addc_co_u32_e64 v17, s[48:49], 0, v17, s[48:49]
	v_cmp_gt_u32_e64 s[48:49], s50, v1
	v_readlane_b32 s50, v1, 23
	v_addc_co_u32_e32 v17, vcc, 0, v17, vcc
	v_cmp_gt_u32_e32 vcc, s2, v1
	v_readlane_b32 s2, v1, 24
	v_addc_co_u32_e64 v17, s[48:49], 0, v17, s[48:49]
	v_cmp_gt_u32_e64 s[48:49], s50, v1
	v_readlane_b32 s50, v1, 25
	v_addc_co_u32_e32 v17, vcc, 0, v17, vcc
	v_cmp_gt_u32_e32 vcc, s2, v1
	v_readlane_b32 s2, v1, 26
	v_addc_co_u32_e64 v17, s[48:49], 0, v17, s[48:49]
	v_cmp_gt_u32_e64 s[48:49], s50, v1
	v_readlane_b32 s50, v1, 27
	v_addc_co_u32_e32 v17, vcc, 0, v17, vcc
	v_cmp_gt_u32_e32 vcc, s2, v1
	v_readlane_b32 s2, v1, 28
	v_addc_co_u32_e64 v17, s[48:49], 0, v17, s[48:49]
	v_cmp_gt_u32_e64 s[48:49], s50, v1
	v_readlane_b32 s50, v1, 29
	v_addc_co_u32_e32 v17, vcc, 0, v17, vcc
	v_cmp_gt_u32_e32 vcc, s2, v1
	v_readlane_b32 s2, v1, 30
	v_addc_co_u32_e64 v17, s[48:49], 0, v17, s[48:49]
	v_cmp_gt_u32_e64 s[48:49], s50, v1
	v_readlane_b32 s50, v1, 31
	v_addc_co_u32_e32 v17, vcc, 0, v17, vcc
	v_cmp_gt_u32_e32 vcc, s2, v1
	v_readlane_b32 s2, v1, 32
	v_addc_co_u32_e64 v17, s[48:49], 0, v17, s[48:49]
	v_cmp_gt_u32_e64 s[48:49], s50, v1
	v_readlane_b32 s50, v1, 33
	v_addc_co_u32_e32 v17, vcc, 0, v17, vcc
	v_cmp_gt_u32_e32 vcc, s2, v1
	v_readlane_b32 s2, v1, 34
	v_addc_co_u32_e64 v17, s[48:49], 0, v17, s[48:49]
	v_cmp_gt_u32_e64 s[48:49], s50, v1
	v_readlane_b32 s50, v1, 35
	v_addc_co_u32_e32 v17, vcc, 0, v17, vcc
	v_cmp_gt_u32_e32 vcc, s2, v1
	v_readlane_b32 s2, v1, 36
	v_addc_co_u32_e64 v17, s[48:49], 0, v17, s[48:49]
	v_cmp_gt_u32_e64 s[48:49], s50, v1
	v_readlane_b32 s50, v1, 37
	v_addc_co_u32_e32 v17, vcc, 0, v17, vcc
	v_cmp_gt_u32_e32 vcc, s2, v1
	v_readlane_b32 s2, v1, 38
	v_addc_co_u32_e64 v17, s[48:49], 0, v17, s[48:49]
	v_cmp_gt_u32_e64 s[48:49], s50, v1
	v_readlane_b32 s50, v1, 39
	v_addc_co_u32_e32 v17, vcc, 0, v17, vcc
	v_cmp_gt_u32_e32 vcc, s2, v1
	v_readlane_b32 s2, v1, 40
	v_addc_co_u32_e64 v17, s[48:49], 0, v17, s[48:49]
	v_cmp_gt_u32_e64 s[48:49], s50, v1
	v_readlane_b32 s50, v1, 41
	v_addc_co_u32_e32 v17, vcc, 0, v17, vcc
	v_cmp_gt_u32_e32 vcc, s2, v1
	v_readlane_b32 s2, v1, 42
	v_addc_co_u32_e64 v17, s[48:49], 0, v17, s[48:49]
	v_cmp_gt_u32_e64 s[48:49], s50, v1
	v_readlane_b32 s50, v1, 43
	v_addc_co_u32_e32 v17, vcc, 0, v17, vcc
	v_cmp_gt_u32_e32 vcc, s2, v1
	v_readlane_b32 s2, v1, 44
	v_addc_co_u32_e64 v17, s[48:49], 0, v17, s[48:49]
	v_cmp_gt_u32_e64 s[48:49], s50, v1
	v_readlane_b32 s50, v1, 45
	v_addc_co_u32_e32 v17, vcc, 0, v17, vcc
	v_cmp_gt_u32_e32 vcc, s2, v1
	v_readlane_b32 s2, v1, 46
	v_addc_co_u32_e64 v17, s[48:49], 0, v17, s[48:49]
	v_cmp_gt_u32_e64 s[48:49], s50, v1
	v_readlane_b32 s50, v1, 47
	v_addc_co_u32_e32 v17, vcc, 0, v17, vcc
	v_cmp_gt_u32_e32 vcc, s2, v1
	v_readlane_b32 s2, v1, 48
	v_addc_co_u32_e64 v17, s[48:49], 0, v17, s[48:49]
	v_cmp_gt_u32_e64 s[48:49], s50, v1
	v_readlane_b32 s50, v1, 49
	v_addc_co_u32_e32 v17, vcc, 0, v17, vcc
	v_cmp_gt_u32_e32 vcc, s2, v1
	v_addc_co_u32_e64 v17, s[48:49], 0, v17, s[48:49]
	v_cmp_gt_u32_e64 s[48:49], s50, v1
	v_addc_co_u32_e32 v17, vcc, 0, v17, vcc
	s_nop 0
	v_addc_co_u32_e64 v1, s[48:49], 0, v17, s[48:49]
	v_lshlrev_b32_e32 v25, 3, v1
	v_lshlrev_b32_e32 v17, 7, v1
	v_and_b32_e32 v25, 0x70, v25
	v_and_or_b32 v17, v17, s43, v25
	v_cmp_gt_u32_e32 vcc, 16, v1
	s_nop 1
	v_cndmask_b32_e32 v17, 4, v17, vcc
	ds_permute_b32 v25, v17, v0
	v_mad_i64_i32 v[0:1], s[2:3], v10, s28, v[120:121]
	s_waitcnt vmcnt(23)
	v_cmp_lt_i32_e32 vcc, -1, v117
	s_waitcnt lgkmcnt(0)
	v_readlane_b32 s2, v25, 0
	s_nop 1
	v_subrev_f32_e32 v4, s2, v25
	v_mul_f32_e32 v4, 0x3fb8aa3b, v4
	v_exp_f32_e32 v6, v4
	v_mad_i64_i32 v[4:5], s[2:3], v11, s28, v[120:121]
	global_load_dwordx4 v[102:105], v[0:1], off offset:768
	global_load_dwordx4 v[98:101], v[4:5], off offset:768
	v_cndmask_b32_e64 v6, 0, v6, s[12:13]
	ds_bpermute_b32 v7, v240, v6
	v_mad_i64_i32 v[0:1], s[2:3], v12, s28, v[120:121]
	v_mad_i64_i32 v[4:5], s[2:3], v13, s28, v[120:121]
	s_waitcnt lgkmcnt(0)
	v_add_f32_e32 v7, v6, v7
	ds_bpermute_b32 v10, v241, v7
	global_load_dwordx4 v[94:97], v[0:1], off offset:768
	global_load_dwordx4 v[90:93], v[4:5], off offset:768
	v_mad_i64_i32 v[0:1], s[2:3], v14, s28, v[120:121]
	v_mad_i64_i32 v[4:5], s[2:3], v15, s28, v[120:121]
	s_waitcnt lgkmcnt(0)
	v_add_f32_e32 v7, v7, v10
	ds_bpermute_b32 v10, v242, v7
	global_load_dwordx4 v[86:89], v[0:1], off offset:768
	global_load_dwordx4 v[82:85], v[4:5], off offset:768
	v_cndmask_b32_e64 v1, v232, -1, vcc
	v_cmp_lt_i32_e32 vcc, -1, v21
	v_and_b32_e32 v0, 0xffffff80, v117
	s_waitcnt lgkmcnt(0)
	v_add_f32_e32 v7, v7, v10
	v_cndmask_b32_e64 v5, v232, -1, vcc
	s_waitcnt vmcnt(28)
	v_cmp_lt_i32_e32 vcc, -1, v31
	v_and_b32_e32 v4, 0xffffff80, v21
	v_xor_b32_e32 v1, v1, v0
	v_cndmask_b32_e64 v10, v232, -1, vcc
	v_cmp_lt_i32_e32 vcc, -1, v23
	v_xor_b32_e32 v5, v5, v4
	v_and_b32_e32 v0, 0xffffff80, v31
	v_and_b32_e32 v4, 0xffffff80, v23
	v_cndmask_b32_e64 v11, v232, -1, vcc
	v_xor_b32_e32 v0, v10, v0
	v_xor_b32_e32 v4, v11, v4
	v_pk_add_f32 v[0:1], v[4:5], v[0:1]
	ds_bpermute_b32 v9, v243, v7
	v_or_b32_e32 v4, 0x80000000, v1
	v_not_b32_e32 v5, v1
	v_cmp_gt_i32_e32 vcc, 0, v1
	s_nop 1
	v_cndmask_b32_e32 v4, v4, v5, vcc
	v_and_b32_e32 v4, 0xffffffc0, v4
	v_bitop3_b32 v4, v4, 63, v81 bitop3:0x36
	v_cndmask_b32_e64 v4, 0, v4, s[10:11]
	s_nop 0
	v_readlane_b32 s2, v4, 0
	v_readlane_b32 s50, v4, 1
	v_mov_b32_e32 v5, 0
	v_cmp_gt_u32_e32 vcc, s2, v4
	v_readlane_b32 s2, v4, 2
	v_cmp_gt_u32_e64 s[48:49], s50, v4
	v_readlane_b32 s50, v4, 3
	v_addc_co_u32_e32 v5, vcc, 0, v5, vcc
	v_cmp_gt_u32_e32 vcc, s2, v4
	v_readlane_b32 s2, v4, 4
	v_addc_co_u32_e64 v5, s[48:49], 0, v5, s[48:49]
	v_cmp_gt_u32_e64 s[48:49], s50, v4
	v_readlane_b32 s50, v4, 5
	v_addc_co_u32_e32 v5, vcc, 0, v5, vcc
	v_cmp_gt_u32_e32 vcc, s2, v4
	v_readlane_b32 s2, v4, 6
	v_addc_co_u32_e64 v5, s[48:49], 0, v5, s[48:49]
	v_cmp_gt_u32_e64 s[48:49], s50, v4
	v_readlane_b32 s50, v4, 7
	v_addc_co_u32_e32 v5, vcc, 0, v5, vcc
	v_cmp_gt_u32_e32 vcc, s2, v4
	v_readlane_b32 s2, v4, 8
	v_addc_co_u32_e64 v5, s[48:49], 0, v5, s[48:49]
	v_cmp_gt_u32_e64 s[48:49], s50, v4
	v_readlane_b32 s50, v4, 9
	v_addc_co_u32_e32 v5, vcc, 0, v5, vcc
	v_cmp_gt_u32_e32 vcc, s2, v4
	v_readlane_b32 s2, v4, 10
	v_addc_co_u32_e64 v5, s[48:49], 0, v5, s[48:49]
	v_cmp_gt_u32_e64 s[48:49], s50, v4
	v_readlane_b32 s50, v4, 11
	v_addc_co_u32_e32 v5, vcc, 0, v5, vcc
	v_cmp_gt_u32_e32 vcc, s2, v4
	v_readlane_b32 s2, v4, 12
	v_addc_co_u32_e64 v5, s[48:49], 0, v5, s[48:49]
	v_cmp_gt_u32_e64 s[48:49], s50, v4
	v_readlane_b32 s50, v4, 13
	v_addc_co_u32_e32 v5, vcc, 0, v5, vcc
	v_cmp_gt_u32_e32 vcc, s2, v4
	v_readlane_b32 s2, v4, 14
	v_addc_co_u32_e64 v5, s[48:49], 0, v5, s[48:49]
	v_cmp_gt_u32_e64 s[48:49], s50, v4
	v_readlane_b32 s50, v4, 15
	v_addc_co_u32_e32 v5, vcc, 0, v5, vcc
	v_cmp_gt_u32_e32 vcc, s2, v4
	v_readlane_b32 s2, v4, 16
	v_addc_co_u32_e64 v5, s[48:49], 0, v5, s[48:49]
	v_cmp_gt_u32_e64 s[48:49], s50, v4
	v_readlane_b32 s50, v4, 17
	v_addc_co_u32_e32 v5, vcc, 0, v5, vcc
	v_cmp_gt_u32_e32 vcc, s2, v4
	v_readlane_b32 s2, v4, 18
	v_addc_co_u32_e64 v5, s[48:49], 0, v5, s[48:49]
	v_cmp_gt_u32_e64 s[48:49], s50, v4
	v_readlane_b32 s50, v4, 19
	v_addc_co_u32_e32 v5, vcc, 0, v5, vcc
	v_cmp_gt_u32_e32 vcc, s2, v4
	v_readlane_b32 s2, v4, 20
	v_addc_co_u32_e64 v5, s[48:49], 0, v5, s[48:49]
	v_cmp_gt_u32_e64 s[48:49], s50, v4
	v_readlane_b32 s50, v4, 21
	v_addc_co_u32_e32 v5, vcc, 0, v5, vcc
	v_cmp_gt_u32_e32 vcc, s2, v4
	v_readlane_b32 s2, v4, 22
	v_addc_co_u32_e64 v5, s[48:49], 0, v5, s[48:49]
	v_cmp_gt_u32_e64 s[48:49], s50, v4
	v_readlane_b32 s50, v4, 23
	v_addc_co_u32_e32 v5, vcc, 0, v5, vcc
	v_cmp_gt_u32_e32 vcc, s2, v4
	v_readlane_b32 s2, v4, 24
	v_addc_co_u32_e64 v5, s[48:49], 0, v5, s[48:49]
	v_cmp_gt_u32_e64 s[48:49], s50, v4
	v_readlane_b32 s50, v4, 25
	v_addc_co_u32_e32 v5, vcc, 0, v5, vcc
	v_cmp_gt_u32_e32 vcc, s2, v4
	v_readlane_b32 s2, v4, 26
	v_addc_co_u32_e64 v5, s[48:49], 0, v5, s[48:49]
	v_cmp_gt_u32_e64 s[48:49], s50, v4
	v_readlane_b32 s50, v4, 27
	v_addc_co_u32_e32 v5, vcc, 0, v5, vcc
	v_cmp_gt_u32_e32 vcc, s2, v4
	v_readlane_b32 s2, v4, 28
	v_addc_co_u32_e64 v5, s[48:49], 0, v5, s[48:49]
	v_cmp_gt_u32_e64 s[48:49], s50, v4
	v_readlane_b32 s50, v4, 29
	v_addc_co_u32_e32 v5, vcc, 0, v5, vcc
	v_cmp_gt_u32_e32 vcc, s2, v4
	v_readlane_b32 s2, v4, 30
	v_addc_co_u32_e64 v5, s[48:49], 0, v5, s[48:49]
	v_cmp_gt_u32_e64 s[48:49], s50, v4
	v_readlane_b32 s50, v4, 31
	v_addc_co_u32_e32 v5, vcc, 0, v5, vcc
	v_cmp_gt_u32_e32 vcc, s2, v4
	v_readlane_b32 s2, v4, 32
	v_addc_co_u32_e64 v5, s[48:49], 0, v5, s[48:49]
	v_cmp_gt_u32_e64 s[48:49], s50, v4
	v_readlane_b32 s50, v4, 33
	v_addc_co_u32_e32 v5, vcc, 0, v5, vcc
	v_cmp_gt_u32_e32 vcc, s2, v4
	v_readlane_b32 s2, v4, 34
	v_addc_co_u32_e64 v5, s[48:49], 0, v5, s[48:49]
	v_cmp_gt_u32_e64 s[48:49], s50, v4
	v_readlane_b32 s50, v4, 35
	v_addc_co_u32_e32 v5, vcc, 0, v5, vcc
	v_cmp_gt_u32_e32 vcc, s2, v4
	v_readlane_b32 s2, v4, 36
	v_addc_co_u32_e64 v5, s[48:49], 0, v5, s[48:49]
	v_cmp_gt_u32_e64 s[48:49], s50, v4
	v_readlane_b32 s50, v4, 37
	v_addc_co_u32_e32 v5, vcc, 0, v5, vcc
	v_cmp_gt_u32_e32 vcc, s2, v4
	v_readlane_b32 s2, v4, 38
	v_addc_co_u32_e64 v5, s[48:49], 0, v5, s[48:49]
	v_cmp_gt_u32_e64 s[48:49], s50, v4
	v_readlane_b32 s50, v4, 39
	v_addc_co_u32_e32 v5, vcc, 0, v5, vcc
	v_cmp_gt_u32_e32 vcc, s2, v4
	v_readlane_b32 s2, v4, 40
	v_addc_co_u32_e64 v5, s[48:49], 0, v5, s[48:49]
	v_cmp_gt_u32_e64 s[48:49], s50, v4
	v_readlane_b32 s50, v4, 41
	v_addc_co_u32_e32 v5, vcc, 0, v5, vcc
	v_cmp_gt_u32_e32 vcc, s2, v4
	v_readlane_b32 s2, v4, 42
	v_addc_co_u32_e64 v5, s[48:49], 0, v5, s[48:49]
	v_cmp_gt_u32_e64 s[48:49], s50, v4
	v_readlane_b32 s50, v4, 43
	v_addc_co_u32_e32 v5, vcc, 0, v5, vcc
	v_cmp_gt_u32_e32 vcc, s2, v4
	v_readlane_b32 s2, v4, 44
	v_addc_co_u32_e64 v5, s[48:49], 0, v5, s[48:49]
	v_cmp_gt_u32_e64 s[48:49], s50, v4
	v_readlane_b32 s50, v4, 45
	v_addc_co_u32_e32 v5, vcc, 0, v5, vcc
	v_cmp_gt_u32_e32 vcc, s2, v4
	v_readlane_b32 s2, v4, 46
	v_addc_co_u32_e64 v5, s[48:49], 0, v5, s[48:49]
	v_cmp_gt_u32_e64 s[48:49], s50, v4
	v_readlane_b32 s50, v4, 47
	v_addc_co_u32_e32 v5, vcc, 0, v5, vcc
	v_cmp_gt_u32_e32 vcc, s2, v4
	v_readlane_b32 s2, v4, 48
	v_addc_co_u32_e64 v5, s[48:49], 0, v5, s[48:49]
	v_cmp_gt_u32_e64 s[48:49], s50, v4
	v_readlane_b32 s50, v4, 49
	v_addc_co_u32_e32 v5, vcc, 0, v5, vcc
	v_cmp_gt_u32_e32 vcc, s2, v4
	v_addc_co_u32_e64 v5, s[48:49], 0, v5, s[48:49]
	v_cmp_gt_u32_e64 s[48:49], s50, v4
	v_addc_co_u32_e32 v5, vcc, 0, v5, vcc
	s_nop 0
	v_addc_co_u32_e64 v4, s[48:49], 0, v5, s[48:49]
	v_lshlrev_b32_e32 v10, 3, v4
	v_lshlrev_b32_e32 v5, 7, v4
	v_and_b32_e32 v10, 0x70, v10
	v_and_or_b32 v5, v5, s43, v10
	v_cmp_gt_u32_e32 vcc, 16, v4
	ds_permute_b32 v4, v17, v8
	s_nop 0
	v_cndmask_b32_e32 v10, 4, v5, vcc
	ds_permute_b32 v1, v10, v1
	s_waitcnt lgkmcnt(2)
	v_add_f32_e32 v5, v7, v9
	v_div_scale_f32 v7, s[2:3], v5, v5, v6
	v_rcp_f32_e32 v9, v7
	s_waitcnt lgkmcnt(0)
	v_readlane_b32 s2, v1, 0
	v_div_scale_f32 v11, vcc, v6, v5, v6
	s_nop 0
	v_subrev_f32_e32 v1, s2, v1
	v_mul_f32_e32 v1, 0x3fb8aa3b, v1
	v_exp_f32_e32 v1, v1
	v_fma_f32 v8, -v7, v9, 1.0
	v_fmac_f32_e32 v9, v8, v9
	v_mul_f32_e32 v12, v11, v9
	v_cndmask_b32_e64 v1, 0, v1, s[12:13]
	ds_bpermute_b32 v8, v240, v1
	v_fma_f32 v13, -v7, v12, v11
	v_fmac_f32_e32 v12, v13, v9
	v_fma_f32 v7, -v7, v12, v11
	v_div_fmas_f32 v7, v7, v9, v12
	s_waitcnt lgkmcnt(0)
	v_add_f32_e32 v8, v1, v8
	ds_bpermute_b32 v14, v241, v8
	v_div_fixup_f32 v5, v7, v5, v6
	v_or_b32_e32 v6, 0x80000000, v0
	v_not_b32_e32 v7, v0
	v_cmp_gt_i32_e32 vcc, 0, v0
	s_waitcnt lgkmcnt(0)
	v_add_f32_e32 v8, v8, v14
	ds_bpermute_b32 v9, v242, v8
	v_cndmask_b32_e32 v6, v6, v7, vcc
	v_and_b32_e32 v6, 0xffffffc0, v6
	v_bitop3_b32 v6, v6, 63, v81 bitop3:0x36
	v_cndmask_b32_e64 v6, 0, v6, s[10:11]
	ds_write2st64_b64 v239, v[2:3], v[4:5] offset1:1
	v_readlane_b32 s2, v6, 0
	s_waitcnt lgkmcnt(1)
	v_add_f32_e32 v4, v8, v9
	v_readlane_b32 s50, v6, 1
	ds_bpermute_b32 v5, v243, v4
	v_mov_b32_e32 v7, 0
	v_cmp_gt_u32_e32 vcc, s2, v6
	v_lshlrev_b32_e32 v2, 7, v21
	v_readlane_b32 s2, v6, 2
	v_cmp_gt_u32_e64 s[48:49], s50, v6
	v_readlane_b32 s50, v6, 3
	v_and_b32_e32 v3, 0x7f, v117
	v_addc_co_u32_e32 v7, vcc, 0, v7, vcc
	v_cmp_gt_u32_e32 vcc, s2, v6
	v_readlane_b32 s2, v6, 4
	v_and_or_b32 v2, v2, s44, v3
	v_addc_co_u32_e64 v7, s[48:49], 0, v7, s[48:49]
	v_cmp_gt_u32_e64 s[48:49], s50, v6
	v_readlane_b32 s50, v6, 5
	s_waitcnt lgkmcnt(0)
	v_addc_co_u32_e32 v7, vcc, 0, v7, vcc
	v_add_f32_e32 v3, v4, v5
	v_cmp_gt_u32_e32 vcc, s2, v6
	v_readlane_b32 s2, v6, 6
	v_addc_co_u32_e64 v7, s[48:49], 0, v7, s[48:49]
	ds_permute_b32 v2, v10, v2
	v_cmp_gt_u32_e64 s[48:49], s50, v6
	v_readlane_b32 s50, v6, 7
	v_addc_co_u32_e32 v7, vcc, 0, v7, vcc
	v_cmp_gt_u32_e32 vcc, s2, v6
	v_readlane_b32 s2, v6, 8
	v_addc_co_u32_e64 v7, s[48:49], 0, v7, s[48:49]
	v_cmp_gt_u32_e64 s[48:49], s50, v6
	v_readlane_b32 s50, v6, 9
	v_addc_co_u32_e32 v7, vcc, 0, v7, vcc
	v_cmp_gt_u32_e32 vcc, s2, v6
	v_readlane_b32 s2, v6, 10
	v_addc_co_u32_e64 v7, s[48:49], 0, v7, s[48:49]
	v_cmp_gt_u32_e64 s[48:49], s50, v6
	v_readlane_b32 s50, v6, 11
	v_addc_co_u32_e32 v7, vcc, 0, v7, vcc
	v_cmp_gt_u32_e32 vcc, s2, v6
	v_readlane_b32 s2, v6, 12
	v_addc_co_u32_e64 v7, s[48:49], 0, v7, s[48:49]
	v_cmp_gt_u32_e64 s[48:49], s50, v6
	v_readlane_b32 s50, v6, 13
	v_addc_co_u32_e32 v7, vcc, 0, v7, vcc
	v_cmp_gt_u32_e32 vcc, s2, v6
	v_readlane_b32 s2, v6, 14
	v_addc_co_u32_e64 v7, s[48:49], 0, v7, s[48:49]
	v_cmp_gt_u32_e64 s[48:49], s50, v6
	v_readlane_b32 s50, v6, 15
	v_addc_co_u32_e32 v7, vcc, 0, v7, vcc
	v_cmp_gt_u32_e32 vcc, s2, v6
	v_readlane_b32 s2, v6, 16
	v_addc_co_u32_e64 v7, s[48:49], 0, v7, s[48:49]
	v_cmp_gt_u32_e64 s[48:49], s50, v6
	v_readlane_b32 s50, v6, 17
	v_addc_co_u32_e32 v7, vcc, 0, v7, vcc
	v_cmp_gt_u32_e32 vcc, s2, v6
	v_readlane_b32 s2, v6, 18
	v_addc_co_u32_e64 v7, s[48:49], 0, v7, s[48:49]
	v_cmp_gt_u32_e64 s[48:49], s50, v6
	v_readlane_b32 s50, v6, 19
	v_addc_co_u32_e32 v7, vcc, 0, v7, vcc
	v_cmp_gt_u32_e32 vcc, s2, v6
	v_readlane_b32 s2, v6, 20
	v_addc_co_u32_e64 v7, s[48:49], 0, v7, s[48:49]
	v_cmp_gt_u32_e64 s[48:49], s50, v6
	v_readlane_b32 s50, v6, 21
	v_addc_co_u32_e32 v7, vcc, 0, v7, vcc
	v_cmp_gt_u32_e32 vcc, s2, v6
	v_readlane_b32 s2, v6, 22
	v_addc_co_u32_e64 v7, s[48:49], 0, v7, s[48:49]
	v_cmp_gt_u32_e64 s[48:49], s50, v6
	v_readlane_b32 s50, v6, 23
	v_addc_co_u32_e32 v7, vcc, 0, v7, vcc
	v_cmp_gt_u32_e32 vcc, s2, v6
	v_readlane_b32 s2, v6, 24
	v_addc_co_u32_e64 v7, s[48:49], 0, v7, s[48:49]
	v_cmp_gt_u32_e64 s[48:49], s50, v6
	v_readlane_b32 s50, v6, 25
	v_addc_co_u32_e32 v7, vcc, 0, v7, vcc
	v_cmp_gt_u32_e32 vcc, s2, v6
	v_readlane_b32 s2, v6, 26
	v_addc_co_u32_e64 v7, s[48:49], 0, v7, s[48:49]
	v_cmp_gt_u32_e64 s[48:49], s50, v6
	v_readlane_b32 s50, v6, 27
	v_addc_co_u32_e32 v7, vcc, 0, v7, vcc
	v_cmp_gt_u32_e32 vcc, s2, v6
	v_readlane_b32 s2, v6, 28
	v_addc_co_u32_e64 v7, s[48:49], 0, v7, s[48:49]
	v_cmp_gt_u32_e64 s[48:49], s50, v6
	v_readlane_b32 s50, v6, 29
	v_addc_co_u32_e32 v7, vcc, 0, v7, vcc
	v_cmp_gt_u32_e32 vcc, s2, v6
	v_readlane_b32 s2, v6, 30
	v_addc_co_u32_e64 v7, s[48:49], 0, v7, s[48:49]
	v_cmp_gt_u32_e64 s[48:49], s50, v6
	v_readlane_b32 s50, v6, 31
	v_addc_co_u32_e32 v7, vcc, 0, v7, vcc
	v_cmp_gt_u32_e32 vcc, s2, v6
	v_readlane_b32 s2, v6, 32
	v_addc_co_u32_e64 v7, s[48:49], 0, v7, s[48:49]
	v_cmp_gt_u32_e64 s[48:49], s50, v6
	v_readlane_b32 s50, v6, 33
	v_addc_co_u32_e32 v7, vcc, 0, v7, vcc
	v_cmp_gt_u32_e32 vcc, s2, v6
	v_readlane_b32 s2, v6, 34
	v_addc_co_u32_e64 v7, s[48:49], 0, v7, s[48:49]
	v_cmp_gt_u32_e64 s[48:49], s50, v6
	v_readlane_b32 s50, v6, 35
	v_addc_co_u32_e32 v7, vcc, 0, v7, vcc
	v_cmp_gt_u32_e32 vcc, s2, v6
	v_readlane_b32 s2, v6, 36
	v_addc_co_u32_e64 v7, s[48:49], 0, v7, s[48:49]
	v_cmp_gt_u32_e64 s[48:49], s50, v6
	v_readlane_b32 s50, v6, 37
	v_addc_co_u32_e32 v7, vcc, 0, v7, vcc
	v_cmp_gt_u32_e32 vcc, s2, v6
	v_readlane_b32 s2, v6, 38
	v_addc_co_u32_e64 v7, s[48:49], 0, v7, s[48:49]
	v_cmp_gt_u32_e64 s[48:49], s50, v6
	v_readlane_b32 s50, v6, 39
	v_addc_co_u32_e32 v7, vcc, 0, v7, vcc
	v_cmp_gt_u32_e32 vcc, s2, v6
	v_readlane_b32 s2, v6, 40
	v_addc_co_u32_e64 v7, s[48:49], 0, v7, s[48:49]
	v_cmp_gt_u32_e64 s[48:49], s50, v6
	v_readlane_b32 s50, v6, 41
	v_addc_co_u32_e32 v7, vcc, 0, v7, vcc
	v_cmp_gt_u32_e32 vcc, s2, v6
	v_readlane_b32 s2, v6, 42
	v_addc_co_u32_e64 v7, s[48:49], 0, v7, s[48:49]
	v_cmp_gt_u32_e64 s[48:49], s50, v6
	v_readlane_b32 s50, v6, 43
	v_addc_co_u32_e32 v7, vcc, 0, v7, vcc
	v_cmp_gt_u32_e32 vcc, s2, v6
	v_readlane_b32 s2, v6, 44
	v_addc_co_u32_e64 v7, s[48:49], 0, v7, s[48:49]
	v_cmp_gt_u32_e64 s[48:49], s50, v6
	v_readlane_b32 s50, v6, 45
	v_addc_co_u32_e32 v7, vcc, 0, v7, vcc
	v_cmp_gt_u32_e32 vcc, s2, v6
	v_readlane_b32 s2, v6, 46
	v_addc_co_u32_e64 v7, s[48:49], 0, v7, s[48:49]
	v_cmp_gt_u32_e64 s[48:49], s50, v6
	v_readlane_b32 s50, v6, 47
	v_addc_co_u32_e32 v7, vcc, 0, v7, vcc
	v_cmp_gt_u32_e32 vcc, s2, v6
	v_readlane_b32 s2, v6, 48
	v_addc_co_u32_e64 v7, s[48:49], 0, v7, s[48:49]
	v_cmp_gt_u32_e64 s[48:49], s50, v6
	v_readlane_b32 s50, v6, 49
	v_addc_co_u32_e32 v7, vcc, 0, v7, vcc
	v_cmp_gt_u32_e32 vcc, s2, v6
	v_addc_co_u32_e64 v7, s[48:49], 0, v7, s[48:49]
	v_cmp_gt_u32_e64 s[48:49], s50, v6
	v_addc_co_u32_e32 v7, vcc, 0, v7, vcc
	s_nop 0
	v_addc_co_u32_e64 v6, s[48:49], 0, v7, s[48:49]
	v_lshlrev_b32_e32 v8, 3, v6
	v_lshlrev_b32_e32 v7, 7, v6
	v_and_b32_e32 v8, 0x70, v8
	v_and_or_b32 v7, v7, s43, v8
	v_cmp_gt_u32_e32 vcc, 16, v6
	v_and_b32_e32 v8, 0x7f, v31
	s_nop 0
	v_cndmask_b32_e32 v6, 4, v7, vcc
	ds_permute_b32 v0, v6, v0
	v_lshlrev_b32_e32 v7, 7, v23
	v_and_or_b32 v7, v7, s44, v8
	s_waitcnt lgkmcnt(0)
	v_readlane_b32 s2, v0, 0
	s_nop 1
	v_subrev_f32_e32 v0, s2, v0
	v_mul_f32_e32 v0, 0x3fb8aa3b, v0
	v_exp_f32_e32 v0, v0
	v_div_scale_f32 v4, s[2:3], v3, v3, v1
	v_rcp_f32_e32 v5, v4
	v_cndmask_b32_e64 v9, 0, v0, s[12:13]
	ds_bpermute_b32 v0, v240, v9
	v_fma_f32 v10, -v4, v5, 1.0
	v_fmac_f32_e32 v5, v10, v5
	v_div_scale_f32 v10, vcc, v1, v3, v1
	s_waitcnt lgkmcnt(0)
	v_add_f32_e32 v0, v9, v0
	ds_bpermute_b32 v11, v241, v0
	v_mul_f32_e32 v12, v10, v5
	v_fma_f32 v13, -v4, v12, v10
	v_fmac_f32_e32 v12, v13, v5
	v_fma_f32 v4, -v4, v12, v10
	s_waitcnt lgkmcnt(0)
	v_add_f32_e32 v0, v0, v11
	ds_bpermute_b32 v10, v242, v0
	v_div_fmas_f32 v4, v4, v5, v12
	s_waitcnt vmcnt(27)
	v_cmp_lt_i32_e32 vcc, -1, v30
	v_div_fixup_f32 v3, v4, v3, v1
	v_and_b32_e32 v4, 0xffffff80, v22
	v_cndmask_b32_e64 v1, v232, -1, vcc
	v_cmp_lt_i32_e32 vcc, -1, v22
	s_waitcnt lgkmcnt(0)
	v_add_f32_e32 v8, v0, v10
	v_and_b32_e32 v0, 0xffffff80, v30
	v_cndmask_b32_e64 v5, v232, -1, vcc
	s_waitcnt vmcnt(26)
	v_cmp_lt_i32_e32 vcc, -1, v29
	v_xor_b32_e32 v1, v1, v0
	v_xor_b32_e32 v5, v5, v4
	v_cndmask_b32_e64 v11, v232, -1, vcc
	v_cmp_lt_i32_e32 vcc, -1, v24
	v_and_b32_e32 v0, 0xffffff80, v29
	v_and_b32_e32 v4, 0xffffff80, v24
	v_cndmask_b32_e64 v12, v232, -1, vcc
	v_xor_b32_e32 v0, v11, v0
	v_xor_b32_e32 v4, v12, v4
	v_pk_add_f32 v[0:1], v[4:5], v[0:1]
	ds_bpermute_b32 v10, v243, v8
	v_or_b32_e32 v4, 0x80000000, v1
	v_not_b32_e32 v5, v1
	v_cmp_gt_i32_e32 vcc, 0, v1
	s_nop 1
	v_cndmask_b32_e32 v4, v4, v5, vcc
	v_and_b32_e32 v4, 0xffffffc0, v4
	v_bitop3_b32 v4, v4, 63, v81 bitop3:0x36
	v_cndmask_b32_e64 v4, 0, v4, s[10:11]
	s_nop 0
	v_readlane_b32 s2, v4, 0
	v_readlane_b32 s50, v4, 1
	v_mov_b32_e32 v5, 0
	v_cmp_gt_u32_e32 vcc, s2, v4
	v_readlane_b32 s2, v4, 2
	v_cmp_gt_u32_e64 s[48:49], s50, v4
	v_readlane_b32 s50, v4, 3
	v_addc_co_u32_e32 v5, vcc, 0, v5, vcc
	v_cmp_gt_u32_e32 vcc, s2, v4
	v_readlane_b32 s2, v4, 4
	v_addc_co_u32_e64 v5, s[48:49], 0, v5, s[48:49]
	v_cmp_gt_u32_e64 s[48:49], s50, v4
	v_readlane_b32 s50, v4, 5
	v_addc_co_u32_e32 v5, vcc, 0, v5, vcc
	v_cmp_gt_u32_e32 vcc, s2, v4
	v_readlane_b32 s2, v4, 6
	v_addc_co_u32_e64 v5, s[48:49], 0, v5, s[48:49]
	v_cmp_gt_u32_e64 s[48:49], s50, v4
	v_readlane_b32 s50, v4, 7
	v_addc_co_u32_e32 v5, vcc, 0, v5, vcc
	v_cmp_gt_u32_e32 vcc, s2, v4
	v_readlane_b32 s2, v4, 8
	v_addc_co_u32_e64 v5, s[48:49], 0, v5, s[48:49]
	v_cmp_gt_u32_e64 s[48:49], s50, v4
	v_readlane_b32 s50, v4, 9
	v_addc_co_u32_e32 v5, vcc, 0, v5, vcc
	v_cmp_gt_u32_e32 vcc, s2, v4
	v_readlane_b32 s2, v4, 10
	v_addc_co_u32_e64 v5, s[48:49], 0, v5, s[48:49]
	v_cmp_gt_u32_e64 s[48:49], s50, v4
	v_readlane_b32 s50, v4, 11
	v_addc_co_u32_e32 v5, vcc, 0, v5, vcc
	v_cmp_gt_u32_e32 vcc, s2, v4
	v_readlane_b32 s2, v4, 12
	v_addc_co_u32_e64 v5, s[48:49], 0, v5, s[48:49]
	v_cmp_gt_u32_e64 s[48:49], s50, v4
	v_readlane_b32 s50, v4, 13
	v_addc_co_u32_e32 v5, vcc, 0, v5, vcc
	v_cmp_gt_u32_e32 vcc, s2, v4
	v_readlane_b32 s2, v4, 14
	v_addc_co_u32_e64 v5, s[48:49], 0, v5, s[48:49]
	v_cmp_gt_u32_e64 s[48:49], s50, v4
	v_readlane_b32 s50, v4, 15
	v_addc_co_u32_e32 v5, vcc, 0, v5, vcc
	v_cmp_gt_u32_e32 vcc, s2, v4
	v_readlane_b32 s2, v4, 16
	v_addc_co_u32_e64 v5, s[48:49], 0, v5, s[48:49]
	v_cmp_gt_u32_e64 s[48:49], s50, v4
	v_readlane_b32 s50, v4, 17
	v_addc_co_u32_e32 v5, vcc, 0, v5, vcc
	v_cmp_gt_u32_e32 vcc, s2, v4
	v_readlane_b32 s2, v4, 18
	v_addc_co_u32_e64 v5, s[48:49], 0, v5, s[48:49]
	v_cmp_gt_u32_e64 s[48:49], s50, v4
	v_readlane_b32 s50, v4, 19
	v_addc_co_u32_e32 v5, vcc, 0, v5, vcc
	v_cmp_gt_u32_e32 vcc, s2, v4
	v_readlane_b32 s2, v4, 20
	v_addc_co_u32_e64 v5, s[48:49], 0, v5, s[48:49]
	v_cmp_gt_u32_e64 s[48:49], s50, v4
	v_readlane_b32 s50, v4, 21
	v_addc_co_u32_e32 v5, vcc, 0, v5, vcc
	v_cmp_gt_u32_e32 vcc, s2, v4
	v_readlane_b32 s2, v4, 22
	v_addc_co_u32_e64 v5, s[48:49], 0, v5, s[48:49]
	v_cmp_gt_u32_e64 s[48:49], s50, v4
	v_readlane_b32 s50, v4, 23
	v_addc_co_u32_e32 v5, vcc, 0, v5, vcc
	v_cmp_gt_u32_e32 vcc, s2, v4
	v_readlane_b32 s2, v4, 24
	v_addc_co_u32_e64 v5, s[48:49], 0, v5, s[48:49]
	v_cmp_gt_u32_e64 s[48:49], s50, v4
	v_readlane_b32 s50, v4, 25
	v_addc_co_u32_e32 v5, vcc, 0, v5, vcc
	v_cmp_gt_u32_e32 vcc, s2, v4
	v_readlane_b32 s2, v4, 26
	v_addc_co_u32_e64 v5, s[48:49], 0, v5, s[48:49]
	v_cmp_gt_u32_e64 s[48:49], s50, v4
	v_readlane_b32 s50, v4, 27
	v_addc_co_u32_e32 v5, vcc, 0, v5, vcc
	v_cmp_gt_u32_e32 vcc, s2, v4
	v_readlane_b32 s2, v4, 28
	v_addc_co_u32_e64 v5, s[48:49], 0, v5, s[48:49]
	v_cmp_gt_u32_e64 s[48:49], s50, v4
	v_readlane_b32 s50, v4, 29
	v_addc_co_u32_e32 v5, vcc, 0, v5, vcc
	v_cmp_gt_u32_e32 vcc, s2, v4
	v_readlane_b32 s2, v4, 30
	v_addc_co_u32_e64 v5, s[48:49], 0, v5, s[48:49]
	v_cmp_gt_u32_e64 s[48:49], s50, v4
	v_readlane_b32 s50, v4, 31
	v_addc_co_u32_e32 v5, vcc, 0, v5, vcc
	v_cmp_gt_u32_e32 vcc, s2, v4
	v_readlane_b32 s2, v4, 32
	v_addc_co_u32_e64 v5, s[48:49], 0, v5, s[48:49]
	v_cmp_gt_u32_e64 s[48:49], s50, v4
	v_readlane_b32 s50, v4, 33
	v_addc_co_u32_e32 v5, vcc, 0, v5, vcc
	v_cmp_gt_u32_e32 vcc, s2, v4
	v_readlane_b32 s2, v4, 34
	v_addc_co_u32_e64 v5, s[48:49], 0, v5, s[48:49]
	v_cmp_gt_u32_e64 s[48:49], s50, v4
	v_readlane_b32 s50, v4, 35
	v_addc_co_u32_e32 v5, vcc, 0, v5, vcc
	v_cmp_gt_u32_e32 vcc, s2, v4
	v_readlane_b32 s2, v4, 36
	v_addc_co_u32_e64 v5, s[48:49], 0, v5, s[48:49]
	v_cmp_gt_u32_e64 s[48:49], s50, v4
	v_readlane_b32 s50, v4, 37
	v_addc_co_u32_e32 v5, vcc, 0, v5, vcc
	v_cmp_gt_u32_e32 vcc, s2, v4
	v_readlane_b32 s2, v4, 38
	v_addc_co_u32_e64 v5, s[48:49], 0, v5, s[48:49]
	v_cmp_gt_u32_e64 s[48:49], s50, v4
	v_readlane_b32 s50, v4, 39
	v_addc_co_u32_e32 v5, vcc, 0, v5, vcc
	v_cmp_gt_u32_e32 vcc, s2, v4
	v_readlane_b32 s2, v4, 40
	v_addc_co_u32_e64 v5, s[48:49], 0, v5, s[48:49]
	v_cmp_gt_u32_e64 s[48:49], s50, v4
	v_readlane_b32 s50, v4, 41
	v_addc_co_u32_e32 v5, vcc, 0, v5, vcc
	v_cmp_gt_u32_e32 vcc, s2, v4
	v_readlane_b32 s2, v4, 42
	v_addc_co_u32_e64 v5, s[48:49], 0, v5, s[48:49]
	v_cmp_gt_u32_e64 s[48:49], s50, v4
	v_readlane_b32 s50, v4, 43
	v_addc_co_u32_e32 v5, vcc, 0, v5, vcc
	v_cmp_gt_u32_e32 vcc, s2, v4
	v_readlane_b32 s2, v4, 44
	v_addc_co_u32_e64 v5, s[48:49], 0, v5, s[48:49]
	v_cmp_gt_u32_e64 s[48:49], s50, v4
	v_readlane_b32 s50, v4, 45
	v_addc_co_u32_e32 v5, vcc, 0, v5, vcc
	v_cmp_gt_u32_e32 vcc, s2, v4
	v_readlane_b32 s2, v4, 46
	v_addc_co_u32_e64 v5, s[48:49], 0, v5, s[48:49]
	v_cmp_gt_u32_e64 s[48:49], s50, v4
	v_readlane_b32 s50, v4, 47
	v_addc_co_u32_e32 v5, vcc, 0, v5, vcc
	v_cmp_gt_u32_e32 vcc, s2, v4
	v_readlane_b32 s2, v4, 48
	v_addc_co_u32_e64 v5, s[48:49], 0, v5, s[48:49]
	v_cmp_gt_u32_e64 s[48:49], s50, v4
	v_readlane_b32 s50, v4, 49
	v_addc_co_u32_e32 v5, vcc, 0, v5, vcc
	v_cmp_gt_u32_e32 vcc, s2, v4
	v_addc_co_u32_e64 v5, s[48:49], 0, v5, s[48:49]
	v_cmp_gt_u32_e64 s[48:49], s50, v4
	v_addc_co_u32_e32 v5, vcc, 0, v5, vcc
	s_nop 0
	v_addc_co_u32_e64 v4, s[48:49], 0, v5, s[48:49]
	v_lshlrev_b32_e32 v11, 3, v4
	v_lshlrev_b32_e32 v5, 7, v4
	v_and_b32_e32 v11, 0x70, v11
	v_and_or_b32 v5, v5, s43, v11
	v_cmp_gt_u32_e32 vcc, 16, v4
	ds_permute_b32 v4, v6, v7
	s_nop 0
	v_cndmask_b32_e32 v11, 4, v5, vcc
	ds_permute_b32 v1, v11, v1
	s_waitcnt lgkmcnt(2)
	v_add_f32_e32 v5, v8, v10
	v_div_scale_f32 v8, s[2:3], v5, v5, v9
	v_rcp_f32_e32 v10, v8
	s_waitcnt lgkmcnt(0)
	v_readlane_b32 s2, v1, 0
	v_div_scale_f32 v7, vcc, v9, v5, v9
	s_nop 0
	v_subrev_f32_e32 v1, s2, v1
	v_mul_f32_e32 v1, 0x3fb8aa3b, v1
	v_exp_f32_e32 v1, v1
	v_fma_f32 v6, -v8, v10, 1.0
	v_fmac_f32_e32 v10, v6, v10
	v_mul_f32_e32 v12, v7, v10
	v_cndmask_b32_e64 v1, 0, v1, s[12:13]
	ds_bpermute_b32 v6, v240, v1
	v_fma_f32 v13, -v8, v12, v7
	v_fmac_f32_e32 v12, v13, v10
	v_fma_f32 v7, -v8, v12, v7
	v_div_fmas_f32 v7, v7, v10, v12
	s_waitcnt lgkmcnt(0)
	v_add_f32_e32 v6, v1, v6
	ds_bpermute_b32 v14, v241, v6
	v_div_fixup_f32 v5, v7, v5, v9
	ds_write2st64_b64 v239, v[2:3], v[4:5] offset0:2 offset1:3
	v_not_b32_e32 v7, v0
	v_cmp_gt_i32_e32 vcc, 0, v0
	s_waitcnt lgkmcnt(1)
	v_add_f32_e32 v6, v6, v14
	ds_bpermute_b32 v8, v242, v6
	v_lshlrev_b32_e32 v2, 7, v22
	v_and_b32_e32 v3, 0x7f, v30
	v_and_or_b32 v2, v2, s44, v3
	v_lshlrev_b32_e32 v3, 7, v24
	s_waitcnt lgkmcnt(0)
	v_add_f32_e32 v4, v6, v8
	v_or_b32_e32 v6, 0x80000000, v0
	v_cndmask_b32_e32 v6, v6, v7, vcc
	v_and_b32_e32 v6, 0xffffffc0, v6
	v_bitop3_b32 v6, v6, 63, v81 bitop3:0x36
	v_cndmask_b32_e64 v6, 0, v6, s[10:11]
	ds_bpermute_b32 v5, v243, v4
	v_readlane_b32 s2, v6, 0
	s_waitcnt lgkmcnt(0)
	v_readlane_b32 s50, v6, 1
	v_add_f32_e32 v4, v4, v5
	v_mov_b32_e32 v7, 0
	v_cmp_gt_u32_e32 vcc, s2, v6
	v_readlane_b32 s2, v6, 2
	v_cmp_gt_u32_e64 s[48:49], s50, v6
	v_readlane_b32 s50, v6, 3
	v_addc_co_u32_e32 v7, vcc, 0, v7, vcc
	v_cmp_gt_u32_e32 vcc, s2, v6
	v_readlane_b32 s2, v6, 4
	v_addc_co_u32_e64 v7, s[48:49], 0, v7, s[48:49]
	v_cmp_gt_u32_e64 s[48:49], s50, v6
	v_readlane_b32 s50, v6, 5
	v_addc_co_u32_e32 v7, vcc, 0, v7, vcc
	v_cmp_gt_u32_e32 vcc, s2, v6
	v_readlane_b32 s2, v6, 6
	v_addc_co_u32_e64 v7, s[48:49], 0, v7, s[48:49]
	v_cmp_gt_u32_e64 s[48:49], s50, v6
	v_readlane_b32 s50, v6, 7
	v_addc_co_u32_e32 v7, vcc, 0, v7, vcc
	v_cmp_gt_u32_e32 vcc, s2, v6
	v_readlane_b32 s2, v6, 8
	v_addc_co_u32_e64 v7, s[48:49], 0, v7, s[48:49]
	v_cmp_gt_u32_e64 s[48:49], s50, v6
	v_readlane_b32 s50, v6, 9
	v_addc_co_u32_e32 v7, vcc, 0, v7, vcc
	v_cmp_gt_u32_e32 vcc, s2, v6
	v_readlane_b32 s2, v6, 10
	v_addc_co_u32_e64 v7, s[48:49], 0, v7, s[48:49]
	v_cmp_gt_u32_e64 s[48:49], s50, v6
	v_readlane_b32 s50, v6, 11
	v_addc_co_u32_e32 v7, vcc, 0, v7, vcc
	v_cmp_gt_u32_e32 vcc, s2, v6
	v_readlane_b32 s2, v6, 12
	v_addc_co_u32_e64 v7, s[48:49], 0, v7, s[48:49]
	v_cmp_gt_u32_e64 s[48:49], s50, v6
	v_readlane_b32 s50, v6, 13
	v_addc_co_u32_e32 v7, vcc, 0, v7, vcc
	v_cmp_gt_u32_e32 vcc, s2, v6
	v_readlane_b32 s2, v6, 14
	v_addc_co_u32_e64 v7, s[48:49], 0, v7, s[48:49]
	v_cmp_gt_u32_e64 s[48:49], s50, v6
	v_readlane_b32 s50, v6, 15
	v_addc_co_u32_e32 v7, vcc, 0, v7, vcc
	v_cmp_gt_u32_e32 vcc, s2, v6
	v_readlane_b32 s2, v6, 16
	v_addc_co_u32_e64 v7, s[48:49], 0, v7, s[48:49]
	v_cmp_gt_u32_e64 s[48:49], s50, v6
	v_readlane_b32 s50, v6, 17
	v_addc_co_u32_e32 v7, vcc, 0, v7, vcc
	v_cmp_gt_u32_e32 vcc, s2, v6
	v_readlane_b32 s2, v6, 18
	v_addc_co_u32_e64 v7, s[48:49], 0, v7, s[48:49]
	v_cmp_gt_u32_e64 s[48:49], s50, v6
	v_readlane_b32 s50, v6, 19
	v_addc_co_u32_e32 v7, vcc, 0, v7, vcc
	v_cmp_gt_u32_e32 vcc, s2, v6
	v_readlane_b32 s2, v6, 20
	v_addc_co_u32_e64 v7, s[48:49], 0, v7, s[48:49]
	v_cmp_gt_u32_e64 s[48:49], s50, v6
	v_readlane_b32 s50, v6, 21
	v_addc_co_u32_e32 v7, vcc, 0, v7, vcc
	v_cmp_gt_u32_e32 vcc, s2, v6
	v_readlane_b32 s2, v6, 22
	v_addc_co_u32_e64 v7, s[48:49], 0, v7, s[48:49]
	v_cmp_gt_u32_e64 s[48:49], s50, v6
	v_readlane_b32 s50, v6, 23
	v_addc_co_u32_e32 v7, vcc, 0, v7, vcc
	v_cmp_gt_u32_e32 vcc, s2, v6
	v_readlane_b32 s2, v6, 24
	v_addc_co_u32_e64 v7, s[48:49], 0, v7, s[48:49]
	v_cmp_gt_u32_e64 s[48:49], s50, v6
	v_readlane_b32 s50, v6, 25
	v_addc_co_u32_e32 v7, vcc, 0, v7, vcc
	v_cmp_gt_u32_e32 vcc, s2, v6
	v_readlane_b32 s2, v6, 26
	v_addc_co_u32_e64 v7, s[48:49], 0, v7, s[48:49]
	v_cmp_gt_u32_e64 s[48:49], s50, v6
	v_readlane_b32 s50, v6, 27
	v_addc_co_u32_e32 v7, vcc, 0, v7, vcc
	v_cmp_gt_u32_e32 vcc, s2, v6
	v_readlane_b32 s2, v6, 28
	v_addc_co_u32_e64 v7, s[48:49], 0, v7, s[48:49]
	v_cmp_gt_u32_e64 s[48:49], s50, v6
	v_readlane_b32 s50, v6, 29
	v_addc_co_u32_e32 v7, vcc, 0, v7, vcc
	v_cmp_gt_u32_e32 vcc, s2, v6
	v_readlane_b32 s2, v6, 30
	v_addc_co_u32_e64 v7, s[48:49], 0, v7, s[48:49]
	v_cmp_gt_u32_e64 s[48:49], s50, v6
	v_readlane_b32 s50, v6, 31
	v_addc_co_u32_e32 v7, vcc, 0, v7, vcc
	v_cmp_gt_u32_e32 vcc, s2, v6
	v_readlane_b32 s2, v6, 32
	v_addc_co_u32_e64 v7, s[48:49], 0, v7, s[48:49]
	v_cmp_gt_u32_e64 s[48:49], s50, v6
	v_readlane_b32 s50, v6, 33
	v_addc_co_u32_e32 v7, vcc, 0, v7, vcc
	v_cmp_gt_u32_e32 vcc, s2, v6
	v_readlane_b32 s2, v6, 34
	v_addc_co_u32_e64 v7, s[48:49], 0, v7, s[48:49]
	v_cmp_gt_u32_e64 s[48:49], s50, v6
	v_readlane_b32 s50, v6, 35
	v_addc_co_u32_e32 v7, vcc, 0, v7, vcc
	v_cmp_gt_u32_e32 vcc, s2, v6
	v_readlane_b32 s2, v6, 36
	v_addc_co_u32_e64 v7, s[48:49], 0, v7, s[48:49]
	v_cmp_gt_u32_e64 s[48:49], s50, v6
	v_readlane_b32 s50, v6, 37
	v_addc_co_u32_e32 v7, vcc, 0, v7, vcc
	v_cmp_gt_u32_e32 vcc, s2, v6
	v_readlane_b32 s2, v6, 38
	v_addc_co_u32_e64 v7, s[48:49], 0, v7, s[48:49]
	v_cmp_gt_u32_e64 s[48:49], s50, v6
	v_readlane_b32 s50, v6, 39
	v_addc_co_u32_e32 v7, vcc, 0, v7, vcc
	v_cmp_gt_u32_e32 vcc, s2, v6
	v_readlane_b32 s2, v6, 40
	v_addc_co_u32_e64 v7, s[48:49], 0, v7, s[48:49]
	v_cmp_gt_u32_e64 s[48:49], s50, v6
	v_readlane_b32 s50, v6, 41
	v_addc_co_u32_e32 v7, vcc, 0, v7, vcc
	v_cmp_gt_u32_e32 vcc, s2, v6
	v_readlane_b32 s2, v6, 42
	v_addc_co_u32_e64 v7, s[48:49], 0, v7, s[48:49]
	v_cmp_gt_u32_e64 s[48:49], s50, v6
	v_readlane_b32 s50, v6, 43
	v_addc_co_u32_e32 v7, vcc, 0, v7, vcc
	v_cmp_gt_u32_e32 vcc, s2, v6
	v_readlane_b32 s2, v6, 44
	v_addc_co_u32_e64 v7, s[48:49], 0, v7, s[48:49]
	v_cmp_gt_u32_e64 s[48:49], s50, v6
	v_readlane_b32 s50, v6, 45
	v_addc_co_u32_e32 v7, vcc, 0, v7, vcc
	v_cmp_gt_u32_e32 vcc, s2, v6
	v_readlane_b32 s2, v6, 46
	v_addc_co_u32_e64 v7, s[48:49], 0, v7, s[48:49]
	v_cmp_gt_u32_e64 s[48:49], s50, v6
	v_readlane_b32 s50, v6, 47
	v_addc_co_u32_e32 v7, vcc, 0, v7, vcc
	v_cmp_gt_u32_e32 vcc, s2, v6
	v_readlane_b32 s2, v6, 48
	v_addc_co_u32_e64 v7, s[48:49], 0, v7, s[48:49]
	v_cmp_gt_u32_e64 s[48:49], s50, v6
	v_readlane_b32 s50, v6, 49
	v_addc_co_u32_e32 v7, vcc, 0, v7, vcc
	v_cmp_gt_u32_e32 vcc, s2, v6
	v_addc_co_u32_e64 v7, s[48:49], 0, v7, s[48:49]
	v_cmp_gt_u32_e64 s[48:49], s50, v6
	v_addc_co_u32_e32 v7, vcc, 0, v7, vcc
	s_nop 0
	v_addc_co_u32_e64 v6, s[48:49], 0, v7, s[48:49]
	v_lshlrev_b32_e32 v8, 3, v6
	v_lshlrev_b32_e32 v7, 7, v6
	v_and_b32_e32 v8, 0x70, v8
	v_and_or_b32 v7, v7, s43, v8
	v_cmp_gt_u32_e32 vcc, 16, v6
	s_nop 1
	v_cndmask_b32_e32 v6, 4, v7, vcc
	ds_permute_b32 v0, v6, v0
	v_and_b32_e32 v7, 0x7f, v29
	v_and_or_b32 v7, v3, s44, v7
	s_waitcnt lgkmcnt(0)
	v_readlane_b32 s2, v0, 0
	s_nop 1
	v_subrev_f32_e32 v0, s2, v0
	v_mul_f32_e32 v0, 0x3fb8aa3b, v0
	v_exp_f32_e32 v5, v0
	ds_permute_b32 v0, v11, v2
	v_div_scale_f32 v8, s[2:3], v4, v4, v1
	v_cndmask_b32_e64 v10, 0, v5, s[12:13]
	ds_bpermute_b32 v2, v240, v10
	v_rcp_f32_e32 v9, v8
	s_waitcnt lgkmcnt(0)
	v_add_f32_e32 v2, v10, v2
	ds_bpermute_b32 v11, v241, v2
	v_fma_f32 v5, -v8, v9, 1.0
	v_fmac_f32_e32 v9, v5, v9
	v_div_scale_f32 v5, vcc, v1, v4, v1
	v_mul_f32_e32 v12, v5, v9
	v_fma_f32 v13, -v8, v12, v5
	v_fmac_f32_e32 v12, v13, v9
	s_waitcnt lgkmcnt(0)
	v_add_f32_e32 v2, v2, v11
	v_fma_f32 v5, -v8, v12, v5
	ds_bpermute_b32 v8, v242, v2
	v_div_fmas_f32 v5, v5, v9, v12
	s_waitcnt vmcnt(25)
	v_cmp_lt_i32_e32 vcc, -1, v19
	v_div_fixup_f32 v1, v5, v4, v1
	v_and_b32_e32 v4, 0xffffff80, v20
	v_cndmask_b32_e64 v3, v232, -1, vcc
	v_cmp_lt_i32_e32 vcc, -1, v20
	s_waitcnt lgkmcnt(0)
	v_add_f32_e32 v8, v2, v8
	v_and_b32_e32 v2, 0xffffff80, v19
	v_cndmask_b32_e64 v5, v232, -1, vcc
	s_waitcnt vmcnt(24)
	v_cmp_lt_i32_e32 vcc, -1, v16
	v_xor_b32_e32 v3, v3, v2
	v_xor_b32_e32 v5, v5, v4
	v_cndmask_b32_e64 v11, v232, -1, vcc
	v_cmp_lt_i32_e32 vcc, -1, v18
	v_and_b32_e32 v2, 0xffffff80, v16
	v_and_b32_e32 v4, 0xffffff80, v18
	v_cndmask_b32_e64 v12, v232, -1, vcc
	v_xor_b32_e32 v2, v11, v2
	v_xor_b32_e32 v4, v12, v4
	v_pk_add_f32 v[2:3], v[4:5], v[2:3]
	ds_bpermute_b32 v9, v243, v8
	v_or_b32_e32 v4, 0x80000000, v3
	v_not_b32_e32 v5, v3
	v_cmp_gt_i32_e32 vcc, 0, v3
	s_nop 1
	v_cndmask_b32_e32 v4, v4, v5, vcc
	v_and_b32_e32 v4, 0xffffffc0, v4
	v_bitop3_b32 v4, v4, 63, v81 bitop3:0x36
	v_cndmask_b32_e64 v4, 0, v4, s[10:11]
	s_nop 0
	v_readlane_b32 s2, v4, 0
	v_readlane_b32 s50, v4, 1
	v_mov_b32_e32 v5, 0
	v_cmp_gt_u32_e32 vcc, s2, v4
	v_readlane_b32 s2, v4, 2
	v_cmp_gt_u32_e64 s[48:49], s50, v4
	v_readlane_b32 s50, v4, 3
	v_addc_co_u32_e32 v5, vcc, 0, v5, vcc
	v_cmp_gt_u32_e32 vcc, s2, v4
	v_readlane_b32 s2, v4, 4
	v_addc_co_u32_e64 v5, s[48:49], 0, v5, s[48:49]
	v_cmp_gt_u32_e64 s[48:49], s50, v4
	v_readlane_b32 s50, v4, 5
	v_addc_co_u32_e32 v5, vcc, 0, v5, vcc
	v_cmp_gt_u32_e32 vcc, s2, v4
	v_readlane_b32 s2, v4, 6
	v_addc_co_u32_e64 v5, s[48:49], 0, v5, s[48:49]
	v_cmp_gt_u32_e64 s[48:49], s50, v4
	v_readlane_b32 s50, v4, 7
	v_addc_co_u32_e32 v5, vcc, 0, v5, vcc
	v_cmp_gt_u32_e32 vcc, s2, v4
	v_readlane_b32 s2, v4, 8
	v_addc_co_u32_e64 v5, s[48:49], 0, v5, s[48:49]
	v_cmp_gt_u32_e64 s[48:49], s50, v4
	v_readlane_b32 s50, v4, 9
	v_addc_co_u32_e32 v5, vcc, 0, v5, vcc
	v_cmp_gt_u32_e32 vcc, s2, v4
	v_readlane_b32 s2, v4, 10
	v_addc_co_u32_e64 v5, s[48:49], 0, v5, s[48:49]
	v_cmp_gt_u32_e64 s[48:49], s50, v4
	v_readlane_b32 s50, v4, 11
	v_addc_co_u32_e32 v5, vcc, 0, v5, vcc
	v_cmp_gt_u32_e32 vcc, s2, v4
	v_readlane_b32 s2, v4, 12
	v_addc_co_u32_e64 v5, s[48:49], 0, v5, s[48:49]
	v_cmp_gt_u32_e64 s[48:49], s50, v4
	v_readlane_b32 s50, v4, 13
	v_addc_co_u32_e32 v5, vcc, 0, v5, vcc
	v_cmp_gt_u32_e32 vcc, s2, v4
	v_readlane_b32 s2, v4, 14
	v_addc_co_u32_e64 v5, s[48:49], 0, v5, s[48:49]
	v_cmp_gt_u32_e64 s[48:49], s50, v4
	v_readlane_b32 s50, v4, 15
	v_addc_co_u32_e32 v5, vcc, 0, v5, vcc
	v_cmp_gt_u32_e32 vcc, s2, v4
	v_readlane_b32 s2, v4, 16
	v_addc_co_u32_e64 v5, s[48:49], 0, v5, s[48:49]
	v_cmp_gt_u32_e64 s[48:49], s50, v4
	v_readlane_b32 s50, v4, 17
	v_addc_co_u32_e32 v5, vcc, 0, v5, vcc
	v_cmp_gt_u32_e32 vcc, s2, v4
	v_readlane_b32 s2, v4, 18
	v_addc_co_u32_e64 v5, s[48:49], 0, v5, s[48:49]
	v_cmp_gt_u32_e64 s[48:49], s50, v4
	v_readlane_b32 s50, v4, 19
	v_addc_co_u32_e32 v5, vcc, 0, v5, vcc
	v_cmp_gt_u32_e32 vcc, s2, v4
	v_readlane_b32 s2, v4, 20
	v_addc_co_u32_e64 v5, s[48:49], 0, v5, s[48:49]
	v_cmp_gt_u32_e64 s[48:49], s50, v4
	v_readlane_b32 s50, v4, 21
	v_addc_co_u32_e32 v5, vcc, 0, v5, vcc
	v_cmp_gt_u32_e32 vcc, s2, v4
	v_readlane_b32 s2, v4, 22
	v_addc_co_u32_e64 v5, s[48:49], 0, v5, s[48:49]
	v_cmp_gt_u32_e64 s[48:49], s50, v4
	v_readlane_b32 s50, v4, 23
	v_addc_co_u32_e32 v5, vcc, 0, v5, vcc
	v_cmp_gt_u32_e32 vcc, s2, v4
	v_readlane_b32 s2, v4, 24
	v_addc_co_u32_e64 v5, s[48:49], 0, v5, s[48:49]
	v_cmp_gt_u32_e64 s[48:49], s50, v4
	v_readlane_b32 s50, v4, 25
	v_addc_co_u32_e32 v5, vcc, 0, v5, vcc
	v_cmp_gt_u32_e32 vcc, s2, v4
	v_readlane_b32 s2, v4, 26
	v_addc_co_u32_e64 v5, s[48:49], 0, v5, s[48:49]
	v_cmp_gt_u32_e64 s[48:49], s50, v4
	v_readlane_b32 s50, v4, 27
	v_addc_co_u32_e32 v5, vcc, 0, v5, vcc
	v_cmp_gt_u32_e32 vcc, s2, v4
	v_readlane_b32 s2, v4, 28
	v_addc_co_u32_e64 v5, s[48:49], 0, v5, s[48:49]
	v_cmp_gt_u32_e64 s[48:49], s50, v4
	v_readlane_b32 s50, v4, 29
	v_addc_co_u32_e32 v5, vcc, 0, v5, vcc
	v_cmp_gt_u32_e32 vcc, s2, v4
	v_readlane_b32 s2, v4, 30
	v_addc_co_u32_e64 v5, s[48:49], 0, v5, s[48:49]
	v_cmp_gt_u32_e64 s[48:49], s50, v4
	v_readlane_b32 s50, v4, 31
	v_addc_co_u32_e32 v5, vcc, 0, v5, vcc
	v_cmp_gt_u32_e32 vcc, s2, v4
	v_readlane_b32 s2, v4, 32
	v_addc_co_u32_e64 v5, s[48:49], 0, v5, s[48:49]
	v_cmp_gt_u32_e64 s[48:49], s50, v4
	v_readlane_b32 s50, v4, 33
	v_addc_co_u32_e32 v5, vcc, 0, v5, vcc
	v_cmp_gt_u32_e32 vcc, s2, v4
	v_readlane_b32 s2, v4, 34
	v_addc_co_u32_e64 v5, s[48:49], 0, v5, s[48:49]
	v_cmp_gt_u32_e64 s[48:49], s50, v4
	v_readlane_b32 s50, v4, 35
	v_addc_co_u32_e32 v5, vcc, 0, v5, vcc
	v_cmp_gt_u32_e32 vcc, s2, v4
	v_readlane_b32 s2, v4, 36
	v_addc_co_u32_e64 v5, s[48:49], 0, v5, s[48:49]
	v_cmp_gt_u32_e64 s[48:49], s50, v4
	v_readlane_b32 s50, v4, 37
	v_addc_co_u32_e32 v5, vcc, 0, v5, vcc
	v_cmp_gt_u32_e32 vcc, s2, v4
	v_readlane_b32 s2, v4, 38
	v_addc_co_u32_e64 v5, s[48:49], 0, v5, s[48:49]
	v_cmp_gt_u32_e64 s[48:49], s50, v4
	v_readlane_b32 s50, v4, 39
	v_addc_co_u32_e32 v5, vcc, 0, v5, vcc
	v_cmp_gt_u32_e32 vcc, s2, v4
	v_readlane_b32 s2, v4, 40
	v_addc_co_u32_e64 v5, s[48:49], 0, v5, s[48:49]
	v_cmp_gt_u32_e64 s[48:49], s50, v4
	v_readlane_b32 s50, v4, 41
	v_addc_co_u32_e32 v5, vcc, 0, v5, vcc
	v_cmp_gt_u32_e32 vcc, s2, v4
	v_readlane_b32 s2, v4, 42
	v_addc_co_u32_e64 v5, s[48:49], 0, v5, s[48:49]
	v_cmp_gt_u32_e64 s[48:49], s50, v4
	v_readlane_b32 s50, v4, 43
	v_addc_co_u32_e32 v5, vcc, 0, v5, vcc
	v_cmp_gt_u32_e32 vcc, s2, v4
	v_readlane_b32 s2, v4, 44
	v_addc_co_u32_e64 v5, s[48:49], 0, v5, s[48:49]
	v_cmp_gt_u32_e64 s[48:49], s50, v4
	v_readlane_b32 s50, v4, 45
	v_addc_co_u32_e32 v5, vcc, 0, v5, vcc
	v_cmp_gt_u32_e32 vcc, s2, v4
	v_readlane_b32 s2, v4, 46
	v_addc_co_u32_e64 v5, s[48:49], 0, v5, s[48:49]
	v_cmp_gt_u32_e64 s[48:49], s50, v4
	v_readlane_b32 s50, v4, 47
	v_addc_co_u32_e32 v5, vcc, 0, v5, vcc
	v_cmp_gt_u32_e32 vcc, s2, v4
	v_readlane_b32 s2, v4, 48
	v_addc_co_u32_e64 v5, s[48:49], 0, v5, s[48:49]
	v_cmp_gt_u32_e64 s[48:49], s50, v4
	v_readlane_b32 s50, v4, 49
	v_addc_co_u32_e32 v5, vcc, 0, v5, vcc
	v_cmp_gt_u32_e32 vcc, s2, v4
	v_addc_co_u32_e64 v5, s[48:49], 0, v5, s[48:49]
	v_cmp_gt_u32_e64 s[48:49], s50, v4
	v_addc_co_u32_e32 v5, vcc, 0, v5, vcc
	s_nop 0
	v_addc_co_u32_e64 v4, s[48:49], 0, v5, s[48:49]
	v_lshlrev_b32_e32 v11, 3, v4
	v_lshlrev_b32_e32 v5, 7, v4
	v_and_b32_e32 v11, 0x70, v11
	v_and_or_b32 v5, v5, s43, v11
	v_cmp_gt_u32_e32 vcc, 16, v4
	ds_permute_b32 v4, v6, v7
	s_nop 0
	v_cndmask_b32_e32 v11, 4, v5, vcc
	s_waitcnt lgkmcnt(1)
	v_add_f32_e32 v5, v8, v9
	v_div_scale_f32 v8, s[2:3], v5, v5, v10
	v_rcp_f32_e32 v9, v8
	v_div_scale_f32 v7, vcc, v10, v5, v10
	ds_permute_b32 v3, v11, v3
	v_fma_f32 v6, -v8, v9, 1.0
	v_fmac_f32_e32 v9, v6, v9
	v_mul_f32_e32 v12, v7, v9
	v_fma_f32 v13, -v8, v12, v7
	v_fmac_f32_e32 v12, v13, v9
	v_fma_f32 v7, -v8, v12, v7
	v_div_fmas_f32 v7, v7, v9, v12
	v_or_b32_e32 v8, 0x80000000, v2
	v_not_b32_e32 v9, v2
	v_cmp_gt_i32_e32 vcc, 0, v2
	s_waitcnt lgkmcnt(0)
	v_readlane_b32 s2, v3, 0
	v_div_fixup_f32 v5, v7, v5, v10
	v_cndmask_b32_e32 v8, v8, v9, vcc
	v_and_b32_e32 v8, 0xffffffc0, v8
	v_bitop3_b32 v8, v8, 63, v81 bitop3:0x36
	v_cndmask_b32_e64 v8, 0, v8, s[10:11]
	v_subrev_f32_e32 v3, s2, v3
	v_readlane_b32 s2, v8, 0
	v_mul_f32_e32 v3, 0x3fb8aa3b, v3
	v_exp_f32_e32 v3, v3
	v_readlane_b32 s50, v8, 1
	v_mov_b32_e32 v9, 0
	v_cmp_gt_u32_e32 vcc, s2, v8
	ds_write2st64_b64 v239, v[0:1], v[4:5] offset0:4 offset1:5
	v_readlane_b32 s2, v8, 2
	v_cmp_gt_u32_e64 s[48:49], s50, v8
	v_readlane_b32 s50, v8, 3
	v_cndmask_b32_e64 v3, 0, v3, s[12:13]
	v_addc_co_u32_e32 v9, vcc, 0, v9, vcc
	v_cmp_gt_u32_e32 vcc, s2, v8
	v_readlane_b32 s2, v8, 4
	ds_bpermute_b32 v6, v240, v3
	v_addc_co_u32_e64 v9, s[48:49], 0, v9, s[48:49]
	v_cmp_gt_u32_e64 s[48:49], s50, v8
	v_readlane_b32 s50, v8, 5
	v_lshlrev_b32_e32 v0, 7, v20
	v_addc_co_u32_e32 v9, vcc, 0, v9, vcc
	v_cmp_gt_u32_e32 vcc, s2, v8
	v_readlane_b32 s2, v8, 6
	s_waitcnt lgkmcnt(0)
	v_add_f32_e32 v6, v3, v6
	v_addc_co_u32_e64 v9, s[48:49], 0, v9, s[48:49]
	v_cmp_gt_u32_e64 s[48:49], s50, v8
	v_readlane_b32 s50, v8, 7
	ds_bpermute_b32 v13, v241, v6
	v_addc_co_u32_e32 v9, vcc, 0, v9, vcc
	v_cmp_gt_u32_e32 vcc, s2, v8
	v_readlane_b32 s2, v8, 8
	s_waitcnt lgkmcnt(0)
	v_addc_co_u32_e64 v9, s[48:49], 0, v9, s[48:49]
	v_add_f32_e32 v6, v6, v13
	v_cmp_gt_u32_e64 s[48:49], s50, v8
	v_readlane_b32 s50, v8, 9
	v_addc_co_u32_e32 v9, vcc, 0, v9, vcc
	ds_bpermute_b32 v7, v242, v6
	v_cmp_gt_u32_e32 vcc, s2, v8
	v_readlane_b32 s2, v8, 10
	v_addc_co_u32_e64 v9, s[48:49], 0, v9, s[48:49]
	v_and_b32_e32 v1, 0x7f, v19
	v_cmp_gt_u32_e64 s[48:49], s50, v8
	v_readlane_b32 s50, v8, 11
	v_addc_co_u32_e32 v9, vcc, 0, v9, vcc
	s_waitcnt lgkmcnt(0)
	v_cmp_gt_u32_e32 vcc, s2, v8
	v_add_f32_e32 v4, v6, v7
	v_readlane_b32 s2, v8, 12
	v_addc_co_u32_e64 v9, s[48:49], 0, v9, s[48:49]
	v_cmp_gt_u32_e64 s[48:49], s50, v8
	v_and_or_b32 v0, v0, s44, v1
	v_readlane_b32 s50, v8, 13
	v_addc_co_u32_e32 v9, vcc, 0, v9, vcc
	v_cmp_gt_u32_e32 vcc, s2, v8
	ds_bpermute_b32 v5, v243, v4
	v_readlane_b32 s2, v8, 14
	v_addc_co_u32_e64 v9, s[48:49], 0, v9, s[48:49]
	v_cmp_gt_u32_e64 s[48:49], s50, v8
	ds_permute_b32 v0, v11, v0
	v_readlane_b32 s50, v8, 15
	v_addc_co_u32_e32 v9, vcc, 0, v9, vcc
	v_lshlrev_b32_e32 v6, 7, v18
	v_cmp_gt_u32_e32 vcc, s2, v8
	v_readlane_b32 s2, v8, 16
	v_addc_co_u32_e64 v9, s[48:49], 0, v9, s[48:49]
	v_cmp_gt_u32_e64 s[48:49], s50, v8
	v_readlane_b32 s50, v8, 17
	v_addc_co_u32_e32 v9, vcc, 0, v9, vcc
	v_cmp_gt_u32_e32 vcc, s2, v8
	v_readlane_b32 s2, v8, 18
	v_addc_co_u32_e64 v9, s[48:49], 0, v9, s[48:49]
	v_cmp_gt_u32_e64 s[48:49], s50, v8
	v_readlane_b32 s50, v8, 19
	v_addc_co_u32_e32 v9, vcc, 0, v9, vcc
	v_cmp_gt_u32_e32 vcc, s2, v8
	v_readlane_b32 s2, v8, 20
	v_addc_co_u32_e64 v9, s[48:49], 0, v9, s[48:49]
	v_cmp_gt_u32_e64 s[48:49], s50, v8
	v_readlane_b32 s50, v8, 21
	v_addc_co_u32_e32 v9, vcc, 0, v9, vcc
	v_cmp_gt_u32_e32 vcc, s2, v8
	v_readlane_b32 s2, v8, 22
	v_addc_co_u32_e64 v9, s[48:49], 0, v9, s[48:49]
	v_cmp_gt_u32_e64 s[48:49], s50, v8
	v_readlane_b32 s50, v8, 23
	v_addc_co_u32_e32 v9, vcc, 0, v9, vcc
	v_cmp_gt_u32_e32 vcc, s2, v8
	v_readlane_b32 s2, v8, 24
	v_addc_co_u32_e64 v9, s[48:49], 0, v9, s[48:49]
	v_cmp_gt_u32_e64 s[48:49], s50, v8
	v_readlane_b32 s50, v8, 25
	v_addc_co_u32_e32 v9, vcc, 0, v9, vcc
	v_cmp_gt_u32_e32 vcc, s2, v8
	v_readlane_b32 s2, v8, 26
	v_addc_co_u32_e64 v9, s[48:49], 0, v9, s[48:49]
	v_cmp_gt_u32_e64 s[48:49], s50, v8
	v_readlane_b32 s50, v8, 27
	v_addc_co_u32_e32 v9, vcc, 0, v9, vcc
	v_cmp_gt_u32_e32 vcc, s2, v8
	v_readlane_b32 s2, v8, 28
	v_addc_co_u32_e64 v9, s[48:49], 0, v9, s[48:49]
	v_cmp_gt_u32_e64 s[48:49], s50, v8
	v_readlane_b32 s50, v8, 29
	v_addc_co_u32_e32 v9, vcc, 0, v9, vcc
	v_cmp_gt_u32_e32 vcc, s2, v8
	v_readlane_b32 s2, v8, 30
	v_addc_co_u32_e64 v9, s[48:49], 0, v9, s[48:49]
	v_cmp_gt_u32_e64 s[48:49], s50, v8
	v_readlane_b32 s50, v8, 31
	v_addc_co_u32_e32 v9, vcc, 0, v9, vcc
	v_cmp_gt_u32_e32 vcc, s2, v8
	v_readlane_b32 s2, v8, 32
	v_addc_co_u32_e64 v9, s[48:49], 0, v9, s[48:49]
	v_cmp_gt_u32_e64 s[48:49], s50, v8
	v_readlane_b32 s50, v8, 33
	v_addc_co_u32_e32 v9, vcc, 0, v9, vcc
	v_cmp_gt_u32_e32 vcc, s2, v8
	v_readlane_b32 s2, v8, 34
	v_addc_co_u32_e64 v9, s[48:49], 0, v9, s[48:49]
	v_cmp_gt_u32_e64 s[48:49], s50, v8
	v_readlane_b32 s50, v8, 35
	v_addc_co_u32_e32 v9, vcc, 0, v9, vcc
	v_cmp_gt_u32_e32 vcc, s2, v8
	v_readlane_b32 s2, v8, 36
	v_addc_co_u32_e64 v9, s[48:49], 0, v9, s[48:49]
	v_cmp_gt_u32_e64 s[48:49], s50, v8
	v_readlane_b32 s50, v8, 37
	v_addc_co_u32_e32 v9, vcc, 0, v9, vcc
	v_cmp_gt_u32_e32 vcc, s2, v8
	v_readlane_b32 s2, v8, 38
	v_addc_co_u32_e64 v9, s[48:49], 0, v9, s[48:49]
	v_cmp_gt_u32_e64 s[48:49], s50, v8
	v_readlane_b32 s50, v8, 39
	v_addc_co_u32_e32 v9, vcc, 0, v9, vcc
	v_cmp_gt_u32_e32 vcc, s2, v8
	v_readlane_b32 s2, v8, 40
	v_addc_co_u32_e64 v9, s[48:49], 0, v9, s[48:49]
	v_cmp_gt_u32_e64 s[48:49], s50, v8
	v_readlane_b32 s50, v8, 41
	v_addc_co_u32_e32 v9, vcc, 0, v9, vcc
	v_cmp_gt_u32_e32 vcc, s2, v8
	v_readlane_b32 s2, v8, 42
	v_addc_co_u32_e64 v9, s[48:49], 0, v9, s[48:49]
	v_cmp_gt_u32_e64 s[48:49], s50, v8
	v_readlane_b32 s50, v8, 43
	v_addc_co_u32_e32 v9, vcc, 0, v9, vcc
	v_cmp_gt_u32_e32 vcc, s2, v8
	v_readlane_b32 s2, v8, 44
	v_addc_co_u32_e64 v9, s[48:49], 0, v9, s[48:49]
	v_cmp_gt_u32_e64 s[48:49], s50, v8
	v_readlane_b32 s50, v8, 45
	v_addc_co_u32_e32 v9, vcc, 0, v9, vcc
	v_cmp_gt_u32_e32 vcc, s2, v8
	v_readlane_b32 s2, v8, 46
	v_addc_co_u32_e64 v9, s[48:49], 0, v9, s[48:49]
	v_cmp_gt_u32_e64 s[48:49], s50, v8
	v_readlane_b32 s50, v8, 47
	v_addc_co_u32_e32 v9, vcc, 0, v9, vcc
	v_cmp_gt_u32_e32 vcc, s2, v8
	v_readlane_b32 s2, v8, 48
	v_addc_co_u32_e64 v9, s[48:49], 0, v9, s[48:49]
	v_cmp_gt_u32_e64 s[48:49], s50, v8
	v_readlane_b32 s50, v8, 49
	v_addc_co_u32_e32 v9, vcc, 0, v9, vcc
	v_cmp_gt_u32_e32 vcc, s2, v8
	v_addc_co_u32_e64 v9, s[48:49], 0, v9, s[48:49]
	v_cmp_gt_u32_e64 s[48:49], s50, v8
	v_addc_co_u32_e32 v9, vcc, 0, v9, vcc
	s_nop 0
	v_addc_co_u32_e64 v8, s[48:49], 0, v9, s[48:49]
	v_lshlrev_b32_e32 v10, 3, v8
	v_lshlrev_b32_e32 v9, 7, v8
	v_and_b32_e32 v10, 0x70, v10
	v_and_or_b32 v9, v9, s43, v10
	v_cmp_gt_u32_e32 vcc, 16, v8
	v_and_b32_e32 v10, 0x7f, v16
	s_nop 0
	v_cndmask_b32_e32 v8, 4, v9, vcc
	ds_permute_b32 v2, v8, v2
	s_waitcnt lgkmcnt(0)
	v_readlane_b32 s2, v2, 0
	s_nop 1
	v_subrev_f32_e32 v2, s2, v2
	v_mul_f32_e32 v2, 0x3fb8aa3b, v2
	v_exp_f32_e32 v2, v2
	s_nop 0
	v_cndmask_b32_e64 v7, 0, v2, s[12:13]
	ds_bpermute_b32 v1, v240, v7
	v_add_f32_e32 v2, v4, v5
	v_div_scale_f32 v4, s[2:3], v2, v2, v3
	v_rcp_f32_e32 v5, v4
	s_waitcnt lgkmcnt(0)
	v_add_f32_e32 v1, v7, v1
	ds_bpermute_b32 v9, v241, v1
	v_fma_f32 v11, -v4, v5, 1.0
	v_fmac_f32_e32 v5, v11, v5
	v_div_scale_f32 v11, vcc, v3, v2, v3
	s_waitcnt lgkmcnt(0)
	v_add_f32_e32 v1, v1, v9
	ds_bpermute_b32 v9, v242, v1
	v_mul_f32_e32 v12, v11, v5
	v_fma_f32 v13, -v4, v12, v11
	v_fmac_f32_e32 v12, v13, v5
	v_fma_f32 v4, -v4, v12, v11
	s_waitcnt lgkmcnt(0)
	v_add_f32_e32 v1, v1, v9
	ds_bpermute_b32 v9, v243, v1
	v_div_fmas_f32 v4, v4, v5, v12
	s_waitcnt lgkmcnt(0)
	v_add_f32_e32 v5, v1, v9
	v_div_scale_f32 v9, s[2:3], v5, v5, v7
	v_rcp_f32_e32 v11, v9
	v_div_fixup_f32 v1, v4, v2, v3
	v_and_or_b32 v2, v6, s44, v10
	ds_permute_b32 v2, v8, v2
	v_fma_f32 v3, -v9, v11, 1.0
	v_fmac_f32_e32 v11, v3, v11
	v_div_scale_f32 v3, vcc, v7, v5, v7
	v_mul_f32_e32 v4, v3, v11
	v_fma_f32 v6, -v9, v4, v3
	v_fmac_f32_e32 v4, v6, v11
	v_fma_f32 v3, -v9, v4, v3
	v_div_fmas_f32 v3, v3, v11, v4
	v_div_fixup_f32 v3, v3, v5, v7
	s_waitcnt lgkmcnt(0)
	ds_write2st64_b64 v239, v[0:1], v[2:3] offset0:6 offset1:7
	s_branch .LBB0_330

	.amdhsa_kernel _Z4mega6Paramsiii
		.amdhsa_group_segment_fixed_size 73744
		.amdhsa_private_segment_fixed_size 0
		.amdhsa_kernarg_size 672
		.amdhsa_user_sgpr_count 2
		.amdhsa_user_sgpr_dispatch_ptr 0
		.amdhsa_user_sgpr_queue_ptr 0
		.amdhsa_user_sgpr_kernarg_segment_ptr 1
		.amdhsa_user_sgpr_dispatch_id 0
		.amdhsa_user_sgpr_kernarg_preload_length 0
		.amdhsa_user_sgpr_kernarg_preload_offset 0
		.amdhsa_user_sgpr_private_segment_size 0
		.amdhsa_uses_dynamic_stack 0
		.amdhsa_enable_private_segment 0
		.amdhsa_system_sgpr_workgroup_id_x 1
		.amdhsa_system_sgpr_workgroup_id_y 0
		.amdhsa_system_sgpr_workgroup_id_z 0
		.amdhsa_system_sgpr_workgroup_info 0
		.amdhsa_system_vgpr_workitem_id 2
		.amdhsa_next_free_vgpr 256
		.amdhsa_next_free_sgpr 100
		.amdhsa_accum_offset 256
		.amdhsa_reserve_vcc 1
		.amdhsa_float_round_mode_32 0
		.amdhsa_float_round_mode_16_64 0
		.amdhsa_float_denorm_mode_32 3
		.amdhsa_float_denorm_mode_16_64 3
		.amdhsa_dx10_clamp 1
		.amdhsa_ieee_mode 1
		.amdhsa_fp16_overflow 0
		.amdhsa_tg_split 0
		.amdhsa_exception_fp_ieee_invalid_op 0
		.amdhsa_exception_fp_denorm_src 0
		.amdhsa_exception_fp_ieee_div_zero 0
		.amdhsa_exception_fp_ieee_overflow 0
		.amdhsa_exception_fp_ieee_underflow 0
		.amdhsa_exception_fp_ieee_inexact 0
		.amdhsa_exception_int_div_zero 0
	.end_amdhsa_kernel

amdhsa.kernels:
  - .agpr_count:     0
    .args:
      - .offset:         0
        .size:           400
        .value_kind:     by_value
      - .offset:         400
        .size:           4
        .value_kind:     by_value
      - .offset:         404
        .size:           4
        .value_kind:     by_value
      - .offset:         408
        .size:           4
        .value_kind:     by_value
      - .offset:         416
        .size:           4
        .value_kind:     hidden_block_count_x
      - .offset:         420
        .size:           4
        .value_kind:     hidden_block_count_y
      - .offset:         424
        .size:           4
        .value_kind:     hidden_block_count_z
      - .offset:         428
        .size:           2
        .value_kind:     hidden_group_size_x
      - .offset:         430
        .size:           2
        .value_kind:     hidden_group_size_y
      - .offset:         432
        .size:           2
        .value_kind:     hidden_group_size_z
      - .offset:         434
        .size:           2
        .value_kind:     hidden_remainder_x
      - .offset:         436
        .size:           2
        .value_kind:     hidden_remainder_y
      - .offset:         438
        .size:           2
        .value_kind:     hidden_remainder_z
      - .offset:         456
        .size:           8
        .value_kind:     hidden_global_offset_x
      - .offset:         464
        .size:           8
        .value_kind:     hidden_global_offset_y
      - .offset:         472
        .size:           8
        .value_kind:     hidden_global_offset_z
      - .offset:         480
        .size:           2
        .value_kind:     hidden_grid_dims
      - .offset:         504
        .size:           8
        .value_kind:     hidden_multigrid_sync_arg
    .group_segment_fixed_size: 73744
    .kernarg_segment_align: 8
    .kernarg_segment_size: 672
    .language:       OpenCL C
    .language_version:
      - 2
      - 0
    .max_flat_workgroup_size: 256
    .name:           _Z4mega6Paramsiii
    .private_segment_fixed_size: 0
    .sgpr_count:     106
    .sgpr_spill_count: 220
    .symbol:         _Z4mega6Paramsiii.kd
    .uniform_work_group_size: 1
    .uses_dynamic_stack: false
    .vgpr_count:     256
    .vgpr_spill_count: 0
    .wavefront_size: 64
